# speedup vs baseline: 1.0340x; 1.0043x over previous
; DEV f32x4 mfma16(bf16x8 a, bf16x8 b, f32x4 c) { return __builtin_amdgcn_mfma_f32_16x16x32_bf16(a, b, c, 0, 0, 0); }
; DEV void gemm_tile(const u16* __restrict__ A, size_t lda, const u16* __restrict__ Bt, size_t ldb, int K,
;                    u16* sA, u16* sB, f32x4 (&acc)[8][4]) {
;     ...
;   for (int kt = 0; kt < nk; ++kt) {
;     const int st = kt & 1;
;     if (kt + 1 < nk) S_STORE(st ^ 1)
;     if (kt + 2 < nk) G_LOAD((kt + 2) << 5)
;     {
;       const u16* pa = sAr + st * 12288;
;       const u16* pb = sBr + st * 12288;
;       bf16x8 b[4];
; #pragma unroll
;       for (int ni = 0; ni < 4; ++ni) b[ni] = *(const bf16x8*)(pb + ni * 16 * 32);
; #pragma unroll
;       for (int mh = 0; mh < 2; ++mh) {
;         bf16x8 a[4];
; #pragma unroll
;         for (int mi = 0; mi < 4; ++mi) a[mi] = *(const bf16x8*)(pa + (mh * 64 + mi * 16) * 32);
; #pragma unroll
;         for (int mi = 0; mi < 4; ++mi)
; #pragma unroll
;           for (int ni = 0; ni < 4; ++ni) acc[mh * 4 + mi][ni] = mfma16(a[mi], b[ni], acc[mh * 4 + mi][ni]);
;       }
;     }
;     __syncthreads();
;   }
.LBB0_122:
	v_add_u32_e32 v229, s8, v158
	v_add_u32_e32 v228, s8, v156
	ds_read_b128 v[92:95], v229 offset:16384
	ds_read_b128 v[160:163], v228
	ds_read_b128 v[100:103], v229 offset:17408
	ds_read_b128 v[116:119], v229 offset:18432
	ds_read_b128 v[104:107], v229 offset:19456
	ds_read_b128 v[164:167], v228 offset:1024
	ds_read_b128 v[168:171], v228 offset:2048
	ds_read_b128 v[232:235], v228 offset:3072
	s_waitcnt lgkmcnt(6)
	v_mfma_f32_16x16x32_bf16 v[148:151], v[160:163], v[92:95], v[148:151]
	s_add_i32 m0, s9, 0x0
	s_waitcnt lgkmcnt(5)
	v_mfma_f32_16x16x32_bf16 v[144:147], v[160:163], v[100:103], v[144:147]
	global_load_lds_dwordx4 v[112:113], off
	v_lshl_add_u64 v[112:113], v[112:113], 0, 64
	global_load_dwordx4 v[252:255], v[112:113], off
	v_lshl_add_u64 v[112:113], v[112:113], 0, 64
	s_waitcnt lgkmcnt(4)
	v_mfma_f32_16x16x32_bf16 v[140:143], v[160:163], v[116:119], v[140:143]
	s_add_i32 m0, s9, 0x1000
	s_waitcnt lgkmcnt(3)
	v_mfma_f32_16x16x32_bf16 v[136:139], v[160:163], v[104:107], v[136:139]
	ds_read_b128 v[236:239], v228 offset:4096
	ds_read_b128 v[240:243], v228 offset:5120
	s_waitcnt lgkmcnt(4)
	v_mfma_f32_16x16x32_bf16 v[132:135], v[164:167], v[92:95], v[132:135]
	global_load_lds_dwordx4 v[114:115], off
	v_lshl_add_u64 v[114:115], v[114:115], 0, 64
	global_load_dwordx4 v[208:211], v[114:115], off
	v_lshl_add_u64 v[114:115], v[114:115], 0, 64
	v_mfma_f32_16x16x32_bf16 v[128:131], v[164:167], v[100:103], v[128:131]
	s_add_i32 m0, s9, 0x2000
	v_mfma_f32_16x16x32_bf16 v[124:127], v[164:167], v[116:119], v[124:127]
	global_load_lds_dwordx4 v[172:173], off
	v_lshl_add_u64 v[172:173], v[172:173], 0, 64
	global_load_dwordx4 v[212:215], v[172:173], off
	v_lshl_add_u64 v[172:173], v[172:173], 0, 64
	v_mfma_f32_16x16x32_bf16 v[120:123], v[164:167], v[104:107], v[120:123]
	s_add_i32 m0, s9, 0x3000
	s_waitcnt lgkmcnt(3)
	v_mfma_f32_16x16x32_bf16 v[96:99], v[168:171], v[92:95], v[96:99]
	global_load_lds_dwordx4 v[108:109], off
	v_lshl_add_u64 v[108:109], v[108:109], 0, 64
	global_load_dwordx4 v[216:219], v[108:109], off
	v_lshl_add_u64 v[108:109], v[108:109], 0, 64
	v_mfma_f32_16x16x32_bf16 v[88:91], v[168:171], v[100:103], v[88:91]
	s_add_i32 m0, s9, 0x4000
	v_mfma_f32_16x16x32_bf16 v[84:87], v[168:171], v[116:119], v[84:87]
	global_load_lds_dwordx4 v[110:111], off
	v_lshl_add_u64 v[110:111], v[110:111], 0, 64
	global_load_dwordx4 v[220:223], v[110:111], off
	v_lshl_add_u64 v[110:111], v[110:111], 0, 64
	v_mfma_f32_16x16x32_bf16 v[80:83], v[168:171], v[104:107], v[80:83]
	ds_read_b128 v[244:247], v228 offset:6144
	ds_read_b128 v[160:163], v228 offset:7168
	s_waitcnt lgkmcnt(4)
	v_mfma_f32_16x16x32_bf16 v[76:79], v[232:235], v[92:95], v[76:79]
	s_add_i32 m0, s9, 0x5000
	v_mfma_f32_16x16x32_bf16 v[72:75], v[232:235], v[100:103], v[72:75]
	global_load_lds_dwordx4 v[174:175], off
	v_lshl_add_u64 v[174:175], v[174:175], 0, 64
	global_load_dwordx4 v[224:227], v[174:175], off
	v_lshl_add_u64 v[174:175], v[174:175], 0, 64
	v_mfma_f32_16x16x32_bf16 v[68:71], v[232:235], v[116:119], v[68:71]
	s_add_i32 s9, s8, s5
	s_add_i32 s8, s8, 0x6000
	v_mfma_f32_16x16x32_bf16 v[64:67], v[232:235], v[104:107], v[64:67]
	s_cmp_eq_u32 s8, 0x12000
	s_cselect_b32 s8, 0, s8
	s_waitcnt lgkmcnt(3)
	v_mfma_f32_16x16x32_bf16 v[60:63], v[236:239], v[92:95], v[60:63]
	s_add_u32 s6, s6, 64
	s_addc_u32 s7, s7, 0
	s_cmpk_lg_i32 s6, 0xf80
	v_mfma_f32_16x16x32_bf16 v[56:59], v[236:239], v[100:103], v[56:59]
	v_mfma_f32_16x16x32_bf16 v[52:55], v[236:239], v[116:119], v[52:55]
	v_mfma_f32_16x16x32_bf16 v[48:51], v[236:239], v[104:107], v[48:51]
	s_waitcnt lgkmcnt(2)
	v_mfma_f32_16x16x32_bf16 v[44:47], v[240:243], v[92:95], v[44:47]
	v_mfma_f32_16x16x32_bf16 v[40:43], v[240:243], v[100:103], v[40:43]
	v_mfma_f32_16x16x32_bf16 v[36:39], v[240:243], v[116:119], v[36:39]
	v_mfma_f32_16x16x32_bf16 v[32:35], v[240:243], v[104:107], v[32:35]
	s_waitcnt lgkmcnt(1)
	v_mfma_f32_16x16x32_bf16 v[28:31], v[244:247], v[92:95], v[28:31]
	v_mfma_f32_16x16x32_bf16 v[24:27], v[244:247], v[100:103], v[24:27]
	v_mfma_f32_16x16x32_bf16 v[20:23], v[244:247], v[116:119], v[20:23]
	v_mfma_f32_16x16x32_bf16 v[16:19], v[244:247], v[104:107], v[16:19]
	s_waitcnt lgkmcnt(0)
	s_waitcnt vmcnt(12)
	s_barrier
	v_mfma_f32_16x16x32_bf16 v[12:15], v[160:163], v[92:95], v[12:15]
	v_mfma_f32_16x16x32_bf16 v[8:11], v[160:163], v[100:103], v[8:11]
	v_mfma_f32_16x16x32_bf16 v[4:7], v[160:163], v[116:119], v[4:7]
	v_mfma_f32_16x16x32_bf16 v[0:3], v[160:163], v[104:107], v[0:3]
	v_add_u32_e32 v229, s8, v158
	v_add_u32_e32 v228, s8, v156
	ds_read_b128 v[92:95], v229 offset:16384
	ds_read_b128 v[160:163], v228
	ds_read_b128 v[100:103], v229 offset:17408
	ds_read_b128 v[116:119], v229 offset:18432
	ds_read_b128 v[104:107], v229 offset:19456
	ds_read_b128 v[164:167], v228 offset:1024
	ds_read_b128 v[168:171], v228 offset:2048
	ds_read_b128 v[232:235], v228 offset:3072
	s_waitcnt lgkmcnt(6)
	v_mfma_f32_16x16x32_bf16 v[148:151], v[160:163], v[92:95], v[148:151]
	s_waitcnt lgkmcnt(5)
	v_mfma_f32_16x16x32_bf16 v[144:147], v[160:163], v[100:103], v[144:147]
	s_waitcnt lgkmcnt(4)
	v_mfma_f32_16x16x32_bf16 v[140:143], v[160:163], v[116:119], v[140:143]
	s_waitcnt lgkmcnt(3)
	v_mfma_f32_16x16x32_bf16 v[136:139], v[160:163], v[104:107], v[136:139]
	ds_read_b128 v[236:239], v228 offset:4096
	ds_read_b128 v[240:243], v228 offset:5120
	s_waitcnt lgkmcnt(4)
	v_mfma_f32_16x16x32_bf16 v[132:135], v[164:167], v[92:95], v[132:135]
	v_mfma_f32_16x16x32_bf16 v[128:131], v[164:167], v[100:103], v[128:131]
	v_mfma_f32_16x16x32_bf16 v[124:127], v[164:167], v[116:119], v[124:127]
	v_mfma_f32_16x16x32_bf16 v[120:123], v[164:167], v[104:107], v[120:123]
	s_waitcnt lgkmcnt(3)
; DEV f32x4 mfma16(bf16x8 a, bf16x8 b, f32x4 c) { return __builtin_amdgcn_mfma_f32_16x16x32_bf16(a, b, c, 0, 0, 0); }
; DEV void gemm_tile(const u16* __restrict__ A, size_t lda, const u16* __restrict__ Bt, size_t ldb, int K,
;                    u16* sA, u16* sB, f32x4 (&acc)[8][4]) {
;     ...
;   for (int kt = 0; kt < nk; ++kt) {
;     const int st = kt & 1;
;     if (kt + 1 < nk) S_STORE(st ^ 1)
;     if (kt + 2 < nk) G_LOAD((kt + 2) << 5)
;     {
;       const u16* pa = sAr + st * 12288;
;       const u16* pb = sBr + st * 12288;
;       bf16x8 b[4];
; #pragma unroll
;       for (int ni = 0; ni < 4; ++ni) b[ni] = *(const bf16x8*)(pb + ni * 16 * 32);
; #pragma unroll
;       for (int mh = 0; mh < 2; ++mh) {
;         bf16x8 a[4];
; #pragma unroll
;         for (int mi = 0; mi < 4; ++mi) a[mi] = *(const bf16x8*)(pa + (mh * 64 + mi * 16) * 32);
; #pragma unroll
;         for (int mi = 0; mi < 4; ++mi)
; #pragma unroll
;           for (int ni = 0; ni < 4; ++ni) acc[mh * 4 + mi][ni] = mfma16(a[mi], b[ni], acc[mh * 4 + mi][ni]);
;       }
;     }
;     __syncthreads();
;   }
	v_mfma_f32_16x16x32_bf16 v[96:99], v[168:171], v[92:95], v[96:99]
	v_mfma_f32_16x16x32_bf16 v[88:91], v[168:171], v[100:103], v[88:91]
	v_mfma_f32_16x16x32_bf16 v[84:87], v[168:171], v[116:119], v[84:87]
	v_mfma_f32_16x16x32_bf16 v[80:83], v[168:171], v[104:107], v[80:83]
	ds_read_b128 v[244:247], v228 offset:6144
	ds_read_b128 v[160:163], v228 offset:7168
	s_waitcnt lgkmcnt(4)
	v_mfma_f32_16x16x32_bf16 v[76:79], v[232:235], v[92:95], v[76:79]
	s_waitcnt vmcnt(0)
	v_add_u32_e32 v231, s9, v230
	v_mfma_f32_16x16x32_bf16 v[72:75], v[232:235], v[100:103], v[72:75]
	ds_write_b128 v231, v[252:255]
	v_mfma_f32_16x16x32_bf16 v[68:71], v[232:235], v[116:119], v[68:71]
	ds_write_b128 v231, v[208:211] offset:4096
	v_mfma_f32_16x16x32_bf16 v[64:67], v[232:235], v[104:107], v[64:67]
	ds_write_b128 v231, v[212:215] offset:8192
	s_waitcnt lgkmcnt(6)
	v_mfma_f32_16x16x32_bf16 v[60:63], v[236:239], v[92:95], v[60:63]
	ds_write_b128 v231, v[216:219] offset:12288
	v_mfma_f32_16x16x32_bf16 v[56:59], v[236:239], v[100:103], v[56:59]
	ds_write_b128 v231, v[220:223] offset:16384
	v_mfma_f32_16x16x32_bf16 v[52:55], v[236:239], v[116:119], v[52:55]
	ds_write_b128 v231, v[224:227] offset:20480
	v_mfma_f32_16x16x32_bf16 v[48:51], v[236:239], v[104:107], v[48:51]
	s_add_i32 s9, s8, s5
	s_add_i32 s8, s8, 0x6000
	s_waitcnt lgkmcnt(8)
	v_mfma_f32_16x16x32_bf16 v[44:47], v[240:243], v[92:95], v[44:47]
	s_cmp_eq_u32 s8, 0x12000
	s_cselect_b32 s8, 0, s8
	v_mfma_f32_16x16x32_bf16 v[40:43], v[240:243], v[100:103], v[40:43]
	s_add_u32 s6, s6, 64
	s_addc_u32 s7, s7, 0
	s_cmpk_lg_i32 s6, 0xf80
	v_mfma_f32_16x16x32_bf16 v[36:39], v[240:243], v[116:119], v[36:39]
	v_mfma_f32_16x16x32_bf16 v[32:35], v[240:243], v[104:107], v[32:35]
	s_waitcnt lgkmcnt(7)
	v_mfma_f32_16x16x32_bf16 v[28:31], v[244:247], v[92:95], v[28:31]
	v_mfma_f32_16x16x32_bf16 v[24:27], v[244:247], v[100:103], v[24:27]
	v_mfma_f32_16x16x32_bf16 v[20:23], v[244:247], v[116:119], v[20:23]
	v_mfma_f32_16x16x32_bf16 v[16:19], v[244:247], v[104:107], v[16:19]
	s_waitcnt lgkmcnt(6)
	s_waitcnt lgkmcnt(0)
	s_barrier
	v_mfma_f32_16x16x32_bf16 v[12:15], v[160:163], v[92:95], v[12:15]
	v_mfma_f32_16x16x32_bf16 v[8:11], v[160:163], v[100:103], v[8:11]
	v_mfma_f32_16x16x32_bf16 v[4:7], v[160:163], v[116:119], v[4:7]
	v_mfma_f32_16x16x32_bf16 v[0:3], v[160:163], v[104:107], v[0:3]
	s_cbranch_scc1 .LBB0_122
	ds_read_b128 v[92:95], v158 offset:16384
	ds_read_b128 v[100:103], v158 offset:17408
	ds_read_b128 v[104:107], v158 offset:18432
	ds_read_b128 v[108:111], v158 offset:19456
	ds_read_b128 v[112:115], v156
	ds_read_b128 v[116:119], v156 offset:1024
	ds_read_b128 v[152:155], v156 offset:2048
	ds_read_b128 v[160:163], v156 offset:3072
	s_movk_i32 s5, 0xb49
	s_waitcnt lgkmcnt(3)
	v_mfma_f32_16x16x32_bf16 v[148:151], v[112:115], v[92:95], v[148:151]
	v_mfma_f32_16x16x32_bf16 v[144:147], v[112:115], v[100:103], v[144:147]
	v_mfma_f32_16x16x32_bf16 v[140:143], v[112:115], v[104:107], v[140:143]
	v_mfma_f32_16x16x32_bf16 v[112:115], v[112:115], v[108:111], v[136:139]
	s_waitcnt lgkmcnt(2)
	v_mfma_f32_16x16x32_bf16 v[132:135], v[116:119], v[92:95], v[132:135]
	v_mfma_f32_16x16x32_bf16 v[128:131], v[116:119], v[100:103], v[128:131]
	v_mfma_f32_16x16x32_bf16 v[136:139], v[116:119], v[104:107], v[124:127]
	v_mfma_f32_16x16x32_bf16 v[164:167], v[116:119], v[108:111], v[120:123]
	s_waitcnt lgkmcnt(1)
	v_mfma_f32_16x16x32_bf16 v[168:171], v[152:155], v[92:95], v[96:99]
	s_nop 2
	ds_read_b128 v[96:99], v156 offset:4096
	ds_read_b128 v[116:119], v156 offset:5120
	ds_read_b128 v[120:123], v156 offset:6144
	ds_read_b128 v[124:127], v156 offset:7168
	s_waitcnt lgkmcnt(0)
	s_waitcnt vmcnt(0)
	s_barrier
	v_mfma_f32_16x16x32_bf16 v[88:91], v[152:155], v[100:103], v[88:91]
	v_mfma_f32_16x16x32_bf16 v[84:87], v[152:155], v[104:107], v[84:87]
	v_mfma_f32_16x16x32_bf16 v[80:83], v[152:155], v[108:111], v[80:83]
	v_mfma_f32_16x16x32_bf16 v[76:79], v[160:163], v[92:95], v[76:79]
	v_mfma_f32_16x16x32_bf16 v[72:75], v[160:163], v[100:103], v[72:75]
	v_mfma_f32_16x16x32_bf16 v[68:71], v[160:163], v[104:107], v[68:71]
	v_mfma_f32_16x16x32_bf16 v[64:67], v[160:163], v[108:111], v[64:67]
	v_mfma_f32_16x16x32_bf16 v[60:63], v[96:99], v[92:95], v[60:63]
	v_mfma_f32_16x16x32_bf16 v[56:59], v[96:99], v[100:103], v[56:59]
	v_mfma_f32_16x16x32_bf16 v[52:55], v[96:99], v[104:107], v[52:55]
	v_mfma_f32_16x16x32_bf16 v[48:51], v[96:99], v[108:111], v[48:51]
	v_mfma_f32_16x16x32_bf16 v[44:47], v[116:119], v[92:95], v[44:47]
	v_mfma_f32_16x16x32_bf16 v[28:31], v[120:123], v[92:95], v[28:31]
	v_mfma_f32_16x16x32_bf16 v[12:15], v[124:127], v[92:95], v[12:15]
	ds_read_b128 v[152:155], v158 offset:40960
	ds_read_b128 v[160:163], v158 offset:41984
	ds_read_b128 v[172:175], v158 offset:43008
	ds_read_b128 v[192:195], v158 offset:44032
	ds_read_b128 v[92:95], v156 offset:24576
	ds_read_b128 v[96:99], v156 offset:25600
	ds_read_b128 v[196:199], v156 offset:26624
	ds_read_b128 v[200:203], v156 offset:27648
	v_mfma_f32_16x16x32_bf16 v[40:43], v[116:119], v[100:103], v[40:43]
	v_mfma_f32_16x16x32_bf16 v[36:39], v[116:119], v[104:107], v[36:39]
	v_mfma_f32_16x16x32_bf16 v[32:35], v[116:119], v[108:111], v[32:35]
	v_mfma_f32_16x16x32_bf16 v[24:27], v[120:123], v[100:103], v[24:27]
	v_mfma_f32_16x16x32_bf16 v[20:23], v[120:123], v[104:107], v[20:23]
	v_mfma_f32_16x16x32_bf16 v[16:19], v[120:123], v[108:111], v[16:19]
	v_mfma_f32_16x16x32_bf16 v[8:11], v[124:127], v[100:103], v[8:11]
	v_mfma_f32_16x16x32_bf16 v[4:7], v[124:127], v[104:107], v[4:7]
	v_mfma_f32_16x16x32_bf16 v[0:3], v[124:127], v[108:111], v[0:3]
	s_waitcnt lgkmcnt(3)
	v_mfma_f32_16x16x32_bf16 v[116:119], v[92:95], v[172:175], v[140:143]
	s_waitcnt lgkmcnt(2)
	v_mfma_f32_16x16x32_bf16 v[108:111], v[96:99], v[152:155], v[132:135]
	v_mfma_f32_16x16x32_bf16 v[104:107], v[96:99], v[160:163], v[128:131]
	v_mfma_f32_16x16x32_bf16 v[100:103], v[96:99], v[172:175], v[136:139]
	s_nop 1
	ds_read_b128 v[128:131], v156 offset:28672
	ds_read_b128 v[132:135], v156 offset:29696
	ds_read_b128 v[136:139], v156 offset:30720
	ds_read_b128 v[140:143], v156 offset:31744
	s_waitcnt lgkmcnt(0)
	s_barrier
; DEV f32x4 mfma16(bf16x8 a, bf16x8 b, f32x4 c) { return __builtin_amdgcn_mfma_f32_16x16x32_bf16(a, b, c, 0, 0, 0); }
; DEV void gemm_tile(const u16* __restrict__ A, size_t lda, const u16* __restrict__ Bt, size_t ldb, int K,
;                    u16* sA, u16* sB, f32x4 (&acc)[8][4]) {
;     ...
;   for (int kt = 0; kt < nk; ++kt) {
;     const int st = kt & 1;
;     if (kt + 1 < nk) S_STORE(st ^ 1)
;     if (kt + 2 < nk) G_LOAD((kt + 2) << 5)
;     {
;       const u16* pa = sAr + st * 12288;
;       const u16* pb = sBr + st * 12288;
;       bf16x8 b[4];
; #pragma unroll
;       for (int ni = 0; ni < 4; ++ni) b[ni] = *(const bf16x8*)(pb + ni * 16 * 32);
; #pragma unroll
;       for (int mh = 0; mh < 2; ++mh) {
;         bf16x8 a[4];
; #pragma unroll
;         for (int mi = 0; mi < 4; ++mi) a[mi] = *(const bf16x8*)(pa + (mh * 64 + mi * 16) * 32);
; #pragma unroll
;         for (int mi = 0; mi < 4; ++mi)
; #pragma unroll
;           for (int ni = 0; ni < 4; ++ni) acc[mh * 4 + mi][ni] = mfma16(a[mi], b[ni], acc[mh * 4 + mi][ni]);
;       }
;     }
;     __syncthreads();
;   }
; DEV void store_tile_bf16(const f32x4 (&acc)[8][4], u16* __restrict__ OUT, size_t ld, int m0, int n0, int ncols,
;                          unsigned char* smem) {
;     ...
; #pragma unroll
;   for (int mh = 0; mh < 2; ++mh) {
; #pragma unroll
;     for (int mi = 0; mi < 4; ++mi)
; #pragma unroll
;       for (int ni = 0; ni < 4; ++ni)
; #pragma unroll
;         for (int j = 0; j < 4; ++j) st[(mi * 16 + fq * 4 + j) * 72 + ni * 16 + fr] = f2bf(acc[mh * 4 + mi][ni][j]);
	v_mfma_f32_16x16x32_bf16 v[60:63], v[128:131], v[152:155], v[60:63]
	v_mfma_f32_16x16x32_bf16 v[56:59], v[128:131], v[160:163], v[56:59]
	v_mfma_f32_16x16x32_bf16 v[52:55], v[128:131], v[172:175], v[52:55]
	v_mfma_f32_16x16x32_bf16 v[48:51], v[128:131], v[192:195], v[48:51]
	v_mov_b32_e32 v129, v178
	v_mfma_f32_16x16x32_bf16 v[124:127], v[92:95], v[152:155], v[148:151]
	v_lshrrev_b32_e32 v128, 6, v129
	v_mul_lo_u32 v131, v128, s75
	v_lshrrev_b32_e32 v128, 2, v129
	v_mfma_f32_16x16x32_bf16 v[44:47], v[132:135], v[152:155], v[44:47]
	v_and_b32_e32 v130, 15, v129
	v_lshl_or_b32 v130, v130, 1, v131
	v_mfma_f32_16x16x32_bf16 v[40:43], v[132:135], v[160:163], v[40:43]
	v_mfma_f32_16x16x32_bf16 v[36:39], v[132:135], v[172:175], v[36:39]
	v_mfma_f32_16x16x32_bf16 v[32:35], v[132:135], v[192:195], v[32:35]
	v_lshlrev_b32_e32 v133, 3, v129
	v_and_b32_e32 v132, 12, v128
	v_and_b32_e32 v128, 64, v129
	v_and_b32_e32 v133, 56, v133
	v_or3_b32 v128, v128, s14, v133
	v_lshl_or_b32 v131, v133, 1, v131
	v_bfe_u32 v133, v129, 3, 3
	v_and_b32_e32 v129, 0xffffff80, v129
	v_add_u32_e32 v134, s4, v129
	v_bfe_u32 v135, v124, 16, 1
	s_movk_i32 s4, 0x90
	v_add3_u32 v135, v124, v135, s71
	v_mad_u32_u24 v124, v132, s4, v130
	v_bfe_u32 v130, v125, 16, 1
	v_add3_u32 v125, v125, v130, s71
	v_mfma_f32_16x16x32_bf16 v[120:123], v[92:95], v[160:163], v[144:147]
	ds_write_b16_d16_hi v124, v125 offset:144
	v_bfe_u32 v125, v126, 16, 1
	v_add3_u32 v125, v126, v125, s71
	ds_write_b16_d16_hi v124, v125 offset:288
	v_bfe_u32 v125, v127, 16, 1
	v_add3_u32 v125, v127, v125, s71
	ds_write_b16_d16_hi v124, v125 offset:432
	s_nop 0
	v_bfe_u32 v125, v120, 16, 1
	v_add3_u32 v120, v120, v125, s71
	ds_write_b16_d16_hi v124, v120 offset:32
	v_bfe_u32 v120, v121, 16, 1
	v_add3_u32 v120, v121, v120, s71
	ds_write_b16_d16_hi v124, v120 offset:176
	v_bfe_u32 v120, v122, 16, 1
	v_add3_u32 v120, v122, v120, s71
	ds_write_b16_d16_hi v124, v120 offset:320
	v_bfe_u32 v120, v123, 16, 1
	v_add3_u32 v120, v123, v120, s71
	ds_write_b16_d16_hi v124, v120 offset:464
	v_bfe_u32 v120, v116, 16, 1
	v_add3_u32 v116, v116, v120, s71
	ds_write_b16_d16_hi v124, v116 offset:64
	v_bfe_u32 v116, v117, 16, 1
	v_add3_u32 v116, v117, v116, s71
	v_mfma_f32_16x16x32_bf16 v[112:115], v[92:95], v[192:195], v[112:115]
	ds_write_b16_d16_hi v124, v116 offset:208
	v_bfe_u32 v116, v118, 16, 1
	v_add3_u32 v116, v118, v116, s71
	ds_write_b16_d16_hi v124, v116 offset:352
	v_bfe_u32 v116, v119, 16, 1
	v_add3_u32 v116, v119, v116, s71
	ds_write_b16_d16_hi v124, v116 offset:496
	s_nop 0
	v_bfe_u32 v116, v112, 16, 1
	v_add3_u32 v112, v112, v116, s71
	ds_write_b16_d16_hi v124, v112 offset:96
	v_bfe_u32 v112, v113, 16, 1
	v_add3_u32 v112, v113, v112, s71
	ds_write_b16_d16_hi v124, v112 offset:240
	v_bfe_u32 v112, v114, 16, 1
	v_add3_u32 v112, v114, v112, s71
	ds_write_b16_d16_hi v124, v112 offset:384
	v_bfe_u32 v112, v115, 16, 1
	v_add3_u32 v112, v115, v112, s71
	ds_write_b16_d16_hi v124, v112 offset:528
	v_bfe_u32 v112, v108, 16, 1
	v_add3_u32 v108, v108, v112, s71
	ds_write_b16_d16_hi v124, v108 offset:2304
	v_bfe_u32 v108, v109, 16, 1
	v_add3_u32 v108, v109, v108, s71
	ds_write_b16_d16_hi v124, v108 offset:2448
	v_bfe_u32 v108, v110, 16, 1
	v_add3_u32 v108, v110, v108, s71
	ds_write_b16_d16_hi v124, v108 offset:2592
	v_bfe_u32 v108, v111, 16, 1
	v_add3_u32 v108, v111, v108, s71
	ds_write_b16_d16_hi v124, v108 offset:2736
	v_bfe_u32 v108, v104, 16, 1
	v_add3_u32 v104, v104, v108, s71
	ds_write_b16_d16_hi v124, v104 offset:2336
	v_bfe_u32 v104, v105, 16, 1
	v_add3_u32 v104, v105, v104, s71
	ds_write_b16_d16_hi v124, v104 offset:2480
	v_bfe_u32 v104, v106, 16, 1
	v_add3_u32 v104, v106, v104, s71
	ds_write_b16_d16_hi v124, v104 offset:2624
	v_bfe_u32 v104, v107, 16, 1
	v_add3_u32 v104, v107, v104, s71
	ds_write_b16_d16_hi v124, v104 offset:2768
	v_bfe_u32 v104, v100, 16, 1
	v_add3_u32 v100, v100, v104, s71
	ds_write_b16_d16_hi v124, v100 offset:2368
	v_bfe_u32 v100, v101, 16, 1
	v_add3_u32 v100, v101, v100, s71
	v_mfma_f32_16x16x32_bf16 v[96:99], v[96:99], v[192:195], v[164:167]
	ds_write_b16_d16_hi v124, v100 offset:2512
	v_bfe_u32 v100, v102, 16, 1
	v_add3_u32 v100, v102, v100, s71
	ds_write_b16_d16_hi v124, v100 offset:2656
	v_bfe_u32 v100, v103, 16, 1
	v_add3_u32 v100, v103, v100, s71
	ds_write_b16_d16_hi v124, v100 offset:2800
	s_nop 0
	v_bfe_u32 v100, v96, 16, 1
	v_add3_u32 v96, v96, v100, s71
	ds_write_b16_d16_hi v124, v96 offset:2400
	v_bfe_u32 v96, v97, 16, 1
	v_add3_u32 v96, v97, v96, s71
	v_mfma_f32_16x16x32_bf16 v[92:95], v[196:199], v[152:155], v[168:171]
	ds_write_b16_d16_hi v124, v96 offset:2544
	v_bfe_u32 v96, v98, 16, 1
	v_add3_u32 v96, v98, v96, s71
	ds_write_b16_d16_hi v124, v96 offset:2688
	v_bfe_u32 v96, v99, 16, 1
	v_add3_u32 v96, v99, v96, s71
	ds_write_b16_d16_hi v124, v96 offset:2832
	s_nop 0
	v_bfe_u32 v96, v92, 16, 1
	v_add3_u32 v92, v92, v96, s71
	ds_write_b16_d16_hi v124, v92 offset:4608
	v_bfe_u32 v92, v93, 16, 1
	v_add3_u32 v92, v93, v92, s71
	v_mfma_f32_16x16x32_bf16 v[88:91], v[196:199], v[160:163], v[88:91]
	ds_write_b16_d16_hi v124, v92 offset:4752
	v_bfe_u32 v92, v94, 16, 1
	v_add3_u32 v92, v94, v92, s71
	ds_write_b16_d16_hi v124, v92 offset:4896
	v_bfe_u32 v92, v95, 16, 1
	v_add3_u32 v92, v95, v92, s71
	ds_write_b16_d16_hi v124, v92 offset:5040
	s_nop 0
	v_bfe_u32 v92, v88, 16, 1
	v_add3_u32 v88, v88, v92, s71
	ds_write_b16_d16_hi v124, v88 offset:4640
	v_bfe_u32 v88, v89, 16, 1
	v_add3_u32 v88, v89, v88, s71
; DEV void store_tile_bf16(const f32x4 (&acc)[8][4], u16* __restrict__ OUT, size_t ld, int m0, int n0, int ncols,
;                          unsigned char* smem) {
;     ...
; #pragma unroll
;   for (int mh = 0; mh < 2; ++mh) {
; #pragma unroll
;     for (int mi = 0; mi < 4; ++mi)
; #pragma unroll
;       for (int ni = 0; ni < 4; ++ni)
; #pragma unroll
;         for (int j = 0; j < 4; ++j) st[(mi * 16 + fq * 4 + j) * 72 + ni * 16 + fr] = f2bf(acc[mh * 4 + mi][ni][j]);
;     const int chunk = lane & 7;
;     const int c0 = n0 + wc * 64 + chunk * 8;
; #pragma unroll
;     for (int itr = 0; itr < 8; ++itr) {
;       const int rl = (lane >> 3) + 8 * itr;
;       const u32x4 v = *(const u32x4*)(st + rl * 72 + chunk * 8);
;       if (c0 + 8 <= ncols) *(u32x4*)(OUT + (size_t)(m0 + wr * 128 + mh * 64 + rl) * ld + c0) = v;
;     }
	v_mfma_f32_16x16x32_bf16 v[84:87], v[196:199], v[172:175], v[84:87]
	ds_write_b16_d16_hi v124, v88 offset:4784
	v_bfe_u32 v88, v90, 16, 1
	v_add3_u32 v88, v90, v88, s71
	ds_write_b16_d16_hi v124, v88 offset:4928
	v_bfe_u32 v88, v91, 16, 1
	v_add3_u32 v88, v91, v88, s71
	ds_write_b16_d16_hi v124, v88 offset:5072
	s_nop 0
	v_bfe_u32 v88, v84, 16, 1
	v_add3_u32 v84, v84, v88, s71
	ds_write_b16_d16_hi v124, v84 offset:4672
	v_bfe_u32 v84, v85, 16, 1
	v_add3_u32 v84, v85, v84, s71
	v_mfma_f32_16x16x32_bf16 v[80:83], v[196:199], v[192:195], v[80:83]
	ds_write_b16_d16_hi v124, v84 offset:4816
	v_bfe_u32 v84, v86, 16, 1
	v_add3_u32 v84, v86, v84, s71
	ds_write_b16_d16_hi v124, v84 offset:4960
	v_bfe_u32 v84, v87, 16, 1
	v_add3_u32 v84, v87, v84, s71
	ds_write_b16_d16_hi v124, v84 offset:5104
	s_nop 0
	v_bfe_u32 v84, v80, 16, 1
	v_add3_u32 v80, v80, v84, s71
	ds_write_b16_d16_hi v124, v80 offset:4704
	v_bfe_u32 v80, v81, 16, 1
	v_add3_u32 v80, v81, v80, s71
	v_mfma_f32_16x16x32_bf16 v[76:79], v[200:203], v[152:155], v[76:79]
	ds_write_b16_d16_hi v124, v80 offset:4848
	v_bfe_u32 v80, v82, 16, 1
	v_add3_u32 v80, v82, v80, s71
	ds_write_b16_d16_hi v124, v80 offset:4992
	v_bfe_u32 v80, v83, 16, 1
	v_add3_u32 v80, v83, v80, s71
	ds_write_b16_d16_hi v124, v80 offset:5136
	s_nop 0
	v_bfe_u32 v80, v76, 16, 1
	v_add3_u32 v76, v76, v80, s71
	ds_write_b16_d16_hi v124, v76 offset:6912
	v_bfe_u32 v76, v77, 16, 1
	v_add3_u32 v76, v77, v76, s71
	v_mfma_f32_16x16x32_bf16 v[72:75], v[200:203], v[160:163], v[72:75]
	ds_write_b16_d16_hi v124, v76 offset:7056
	v_bfe_u32 v76, v78, 16, 1
	v_add3_u32 v76, v78, v76, s71
	ds_write_b16_d16_hi v124, v76 offset:7200
	v_bfe_u32 v76, v79, 16, 1
	v_add3_u32 v76, v79, v76, s71
	ds_write_b16_d16_hi v124, v76 offset:7344
	s_nop 0
	v_bfe_u32 v76, v72, 16, 1
	v_add3_u32 v72, v72, v76, s71
	ds_write_b16_d16_hi v124, v72 offset:6944
	v_bfe_u32 v72, v73, 16, 1
	v_add3_u32 v72, v73, v72, s71
	v_mfma_f32_16x16x32_bf16 v[68:71], v[200:203], v[172:175], v[68:71]
	ds_write_b16_d16_hi v124, v72 offset:7088
	v_bfe_u32 v72, v74, 16, 1
	v_add3_u32 v72, v74, v72, s71
	ds_write_b16_d16_hi v124, v72 offset:7232
	v_bfe_u32 v72, v75, 16, 1
	v_add3_u32 v72, v75, v72, s71
	ds_write_b16_d16_hi v124, v72 offset:7376
	s_nop 0
	v_bfe_u32 v72, v68, 16, 1
	v_add3_u32 v68, v68, v72, s71
	ds_write_b16_d16_hi v124, v68 offset:6976
	v_bfe_u32 v68, v69, 16, 1
	v_add3_u32 v68, v69, v68, s71
	v_mfma_f32_16x16x32_bf16 v[64:67], v[200:203], v[192:195], v[64:67]
	ds_write_b16_d16_hi v124, v68 offset:7120
	v_bfe_u32 v68, v70, 16, 1
	v_add3_u32 v68, v70, v68, s71
	ds_write_b16_d16_hi v124, v68 offset:7264
	v_bfe_u32 v68, v71, 16, 1
	v_add3_u32 v68, v71, v68, s71
	ds_write_b16_d16_hi v124, v68 offset:7408
	s_nop 0
	v_bfe_u32 v68, v64, 16, 1
	v_add3_u32 v64, v64, v68, s71
	ds_write_b16_d16_hi v124, v64 offset:7008
	v_bfe_u32 v64, v65, 16, 1
	v_add3_u32 v64, v65, v64, s71
	ds_write_b16_d16_hi v124, v64 offset:7152
	v_bfe_u32 v64, v66, 16, 1
	v_mfma_f32_16x16x32_bf16 v[28:31], v[136:139], v[152:155], v[28:31]
	v_add3_u32 v64, v66, v64, s71
	ds_write_b16_d16_hi v124, v64 offset:7296
	v_bfe_u32 v64, v67, 16, 1
	v_mfma_f32_16x16x32_bf16 v[24:27], v[136:139], v[160:163], v[24:27]
	v_ashrrev_i32_e32 v129, 31, v128
	v_add3_u32 v64, v67, v64, s71
	v_cmp_gt_i32_e32 vcc, s5, v128
	v_mfma_f32_16x16x32_bf16 v[20:23], v[136:139], v[172:175], v[20:23]
	v_lshl_add_u64 v[128:129], v[128:129], 1, s[68:69]
	ds_write_b16_d16_hi v124, v64 offset:7440
	v_mad_u32_u24 v65, v133, s4, v131
	v_mfma_f32_16x16x32_bf16 v[16:19], v[136:139], v[192:195], v[16:19]
	v_or_b32_e32 v64, v134, v133
	ds_write_b16_d16_hi v124, v135
	v_mfma_f32_16x16x32_bf16 v[12:15], v[140:143], v[152:155], v[12:15]
	v_mfma_f32_16x16x32_bf16 v[8:11], v[140:143], v[160:163], v[8:11]
	v_mfma_f32_16x16x32_bf16 v[4:7], v[140:143], v[172:175], v[4:7]
	v_mfma_f32_16x16x32_bf16 v[0:3], v[140:143], v[192:195], v[0:3]
	s_and_saveexec_b64 s[4:5], vcc
	s_cbranch_execz .LBB0_125
	ds_read_b128 v[66:69], v65
	v_mad_i64_i32 v[70:71], s[6:7], v64, s80, v[128:129]
	s_waitcnt lgkmcnt(0)
	global_store_dwordx4 v[70:71], v[66:69], off
	ds_read_b128 v[66:69], v65 offset:1152
	v_or_b32_e32 v70, 8, v64
	v_mad_i64_i32 v[70:71], s[6:7], v70, s80, v[128:129]
	s_waitcnt lgkmcnt(0)
	global_store_dwordx4 v[70:71], v[66:69], off
	ds_read_b128 v[66:69], v65 offset:2304
	v_or_b32_e32 v70, 16, v64
	v_mad_i64_i32 v[70:71], s[6:7], v70, s80, v[128:129]
	s_waitcnt lgkmcnt(0)
	global_store_dwordx4 v[70:71], v[66:69], off
	ds_read_b128 v[66:69], v65 offset:3456
	v_or_b32_e32 v70, 24, v64
	v_mad_i64_i32 v[70:71], s[6:7], v70, s80, v[128:129]
	s_waitcnt lgkmcnt(0)
	global_store_dwordx4 v[70:71], v[66:69], off
	ds_read_b128 v[66:69], v65 offset:4608
	v_or_b32_e32 v70, 32, v64
	v_mad_i64_i32 v[70:71], s[6:7], v70, s80, v[128:129]
	s_waitcnt lgkmcnt(0)
	global_store_dwordx4 v[70:71], v[66:69], off
	ds_read_b128 v[66:69], v65 offset:5760
	v_or_b32_e32 v70, 40, v64
	v_mad_i64_i32 v[70:71], s[6:7], v70, s80, v[128:129]
	s_waitcnt lgkmcnt(0)
	global_store_dwordx4 v[70:71], v[66:69], off
	ds_read_b128 v[66:69], v65 offset:6912
	v_or_b32_e32 v70, 48, v64
	v_mad_i64_i32 v[70:71], s[6:7], v70, s80, v[128:129]
	s_waitcnt lgkmcnt(0)
	global_store_dwordx4 v[70:71], v[66:69], off
	ds_read_b128 v[66:69], v65 offset:8064
	v_or_b32_e32 v70, 56, v64
	v_mad_i64_i32 v[70:71], s[6:7], v70, s80, v[128:129]
	s_waitcnt lgkmcnt(0)
	global_store_dwordx4 v[70:71], v[66:69], off

; DEV f32x4 mfma16(bf16x8 a, bf16x8 b, f32x4 c) { return __builtin_amdgcn_mfma_f32_16x16x32_bf16(a, b, c, 0, 0, 0); }
; DEV void gemm_tile(const u16* __restrict__ A, size_t lda, const u16* __restrict__ Bt, size_t ldb, int K,
;                    u16* sA, u16* sB, f32x4 (&acc)[8][4]) {
;     ...
;   for (int kt = 0; kt < nk; ++kt) {
;     const int st = kt & 1;
;     if (kt + 1 < nk) S_STORE(st ^ 1)
;     if (kt + 2 < nk) G_LOAD((kt + 2) << 5)
;     {
;       const u16* pa = sAr + st * 12288;
;       const u16* pb = sBr + st * 12288;
;       bf16x8 b[4];
; #pragma unroll
;       for (int ni = 0; ni < 4; ++ni) b[ni] = *(const bf16x8*)(pb + ni * 16 * 32);
; #pragma unroll
;       for (int mh = 0; mh < 2; ++mh) {
;         bf16x8 a[4];
; #pragma unroll
;         for (int mi = 0; mi < 4; ++mi) a[mi] = *(const bf16x8*)(pa + (mh * 64 + mi * 16) * 32);
; #pragma unroll
;         for (int mi = 0; mi < 4; ++mi)
; #pragma unroll
;           for (int ni = 0; ni < 4; ++ni) acc[mh * 4 + mi][ni] = mfma16(a[mi], b[ni], acc[mh * 4 + mi][ni]);
;       }
;     }
;     __syncthreads();
;   }
.LBB0_162:
	v_add_u32_e32 v229, s7, v158
	v_add_u32_e32 v228, s7, v156
	ds_read_b128 v[92:95], v229 offset:16384
	ds_read_b128 v[160:163], v228
	ds_read_b128 v[100:103], v229 offset:17408
	ds_read_b128 v[116:119], v229 offset:18432
	ds_read_b128 v[104:107], v229 offset:19456
	ds_read_b128 v[164:167], v228 offset:1024
	ds_read_b128 v[168:171], v228 offset:2048
	ds_read_b128 v[232:235], v228 offset:3072
	s_waitcnt lgkmcnt(6)
	v_mfma_f32_16x16x32_bf16 v[148:151], v[160:163], v[92:95], v[148:151]
	s_add_i32 m0, s10, 0x0
	s_waitcnt lgkmcnt(5)
	v_mfma_f32_16x16x32_bf16 v[144:147], v[160:163], v[100:103], v[144:147]
	global_load_lds_dwordx4 v[112:113], off
	v_lshl_add_u64 v[112:113], v[112:113], 0, 64
	global_load_dwordx4 v[252:255], v[112:113], off
	v_lshl_add_u64 v[112:113], v[112:113], 0, 64
	s_waitcnt lgkmcnt(4)
	v_mfma_f32_16x16x32_bf16 v[140:143], v[160:163], v[116:119], v[140:143]
	s_add_i32 m0, s10, 0x1000
	s_waitcnt lgkmcnt(3)
	v_mfma_f32_16x16x32_bf16 v[136:139], v[160:163], v[104:107], v[136:139]
	ds_read_b128 v[236:239], v228 offset:4096
	ds_read_b128 v[240:243], v228 offset:5120
	s_waitcnt lgkmcnt(4)
	v_mfma_f32_16x16x32_bf16 v[132:135], v[164:167], v[92:95], v[132:135]
	global_load_lds_dwordx4 v[114:115], off
	v_lshl_add_u64 v[114:115], v[114:115], 0, 64
	global_load_dwordx4 v[208:211], v[114:115], off
	v_lshl_add_u64 v[114:115], v[114:115], 0, 64
	v_mfma_f32_16x16x32_bf16 v[128:131], v[164:167], v[100:103], v[128:131]
	s_add_i32 m0, s10, 0x2000
	v_mfma_f32_16x16x32_bf16 v[124:127], v[164:167], v[116:119], v[124:127]
	global_load_lds_dwordx4 v[172:173], off
	v_lshl_add_u64 v[172:173], v[172:173], 0, 64
	global_load_dwordx4 v[212:215], v[172:173], off
	v_lshl_add_u64 v[172:173], v[172:173], 0, 64
	v_mfma_f32_16x16x32_bf16 v[120:123], v[164:167], v[104:107], v[120:123]
	s_add_i32 m0, s10, 0x3000
	s_waitcnt lgkmcnt(3)
	v_mfma_f32_16x16x32_bf16 v[96:99], v[168:171], v[92:95], v[96:99]
	global_load_lds_dwordx4 v[108:109], off
	v_lshl_add_u64 v[108:109], v[108:109], 0, 64
	global_load_dwordx4 v[216:219], v[108:109], off
	v_lshl_add_u64 v[108:109], v[108:109], 0, 64
	v_mfma_f32_16x16x32_bf16 v[88:91], v[168:171], v[100:103], v[88:91]
	s_add_i32 m0, s10, 0x4000
	v_mfma_f32_16x16x32_bf16 v[84:87], v[168:171], v[116:119], v[84:87]
	global_load_lds_dwordx4 v[110:111], off
	v_lshl_add_u64 v[110:111], v[110:111], 0, 64
	global_load_dwordx4 v[220:223], v[110:111], off
	v_lshl_add_u64 v[110:111], v[110:111], 0, 64
	v_mfma_f32_16x16x32_bf16 v[80:83], v[168:171], v[104:107], v[80:83]
	ds_read_b128 v[244:247], v228 offset:6144
	ds_read_b128 v[160:163], v228 offset:7168
	s_waitcnt lgkmcnt(4)
	v_mfma_f32_16x16x32_bf16 v[76:79], v[232:235], v[92:95], v[76:79]
	s_add_i32 m0, s10, 0x5000
	v_mfma_f32_16x16x32_bf16 v[72:75], v[232:235], v[100:103], v[72:75]
	global_load_lds_dwordx4 v[174:175], off
	v_lshl_add_u64 v[174:175], v[174:175], 0, 64
	global_load_dwordx4 v[224:227], v[174:175], off
	v_lshl_add_u64 v[174:175], v[174:175], 0, 64
	v_mfma_f32_16x16x32_bf16 v[68:71], v[232:235], v[116:119], v[68:71]
	s_add_i32 s10, s7, s5
	s_add_i32 s7, s7, 0x6000
	v_mfma_f32_16x16x32_bf16 v[64:67], v[232:235], v[104:107], v[64:67]
	s_cmp_eq_u32 s7, 0x12000
	s_cselect_b32 s7, 0, s7
	s_waitcnt lgkmcnt(3)
	v_mfma_f32_16x16x32_bf16 v[60:63], v[236:239], v[92:95], v[60:63]
	s_add_u32 s8, s8, 64
	s_addc_u32 s9, s9, 0
	s_cmpk_lg_i32 s8, 0xf80
	v_mfma_f32_16x16x32_bf16 v[56:59], v[236:239], v[100:103], v[56:59]
	v_mfma_f32_16x16x32_bf16 v[52:55], v[236:239], v[116:119], v[52:55]
	v_mfma_f32_16x16x32_bf16 v[48:51], v[236:239], v[104:107], v[48:51]
	s_waitcnt lgkmcnt(2)
	v_mfma_f32_16x16x32_bf16 v[44:47], v[240:243], v[92:95], v[44:47]
	v_mfma_f32_16x16x32_bf16 v[40:43], v[240:243], v[100:103], v[40:43]
	v_mfma_f32_16x16x32_bf16 v[36:39], v[240:243], v[116:119], v[36:39]
	v_mfma_f32_16x16x32_bf16 v[32:35], v[240:243], v[104:107], v[32:35]
	s_waitcnt lgkmcnt(1)
	v_mfma_f32_16x16x32_bf16 v[28:31], v[244:247], v[92:95], v[28:31]
	v_mfma_f32_16x16x32_bf16 v[24:27], v[244:247], v[100:103], v[24:27]
	v_mfma_f32_16x16x32_bf16 v[20:23], v[244:247], v[116:119], v[20:23]
	v_mfma_f32_16x16x32_bf16 v[16:19], v[244:247], v[104:107], v[16:19]
	s_waitcnt lgkmcnt(0)
	s_waitcnt vmcnt(12)
	s_barrier
	v_mfma_f32_16x16x32_bf16 v[12:15], v[160:163], v[92:95], v[12:15]
	v_mfma_f32_16x16x32_bf16 v[8:11], v[160:163], v[100:103], v[8:11]
	v_mfma_f32_16x16x32_bf16 v[4:7], v[160:163], v[116:119], v[4:7]
	v_mfma_f32_16x16x32_bf16 v[0:3], v[160:163], v[104:107], v[0:3]
	v_add_u32_e32 v229, s7, v158
	v_add_u32_e32 v228, s7, v156
	ds_read_b128 v[92:95], v229 offset:16384
	ds_read_b128 v[160:163], v228
	ds_read_b128 v[100:103], v229 offset:17408
	ds_read_b128 v[116:119], v229 offset:18432
	ds_read_b128 v[104:107], v229 offset:19456
	ds_read_b128 v[164:167], v228 offset:1024
	ds_read_b128 v[168:171], v228 offset:2048
	ds_read_b128 v[232:235], v228 offset:3072
	s_waitcnt lgkmcnt(6)
	v_mfma_f32_16x16x32_bf16 v[148:151], v[160:163], v[92:95], v[148:151]
	s_waitcnt lgkmcnt(5)
	v_mfma_f32_16x16x32_bf16 v[144:147], v[160:163], v[100:103], v[144:147]
	s_waitcnt lgkmcnt(4)
	v_mfma_f32_16x16x32_bf16 v[140:143], v[160:163], v[116:119], v[140:143]
	s_waitcnt lgkmcnt(3)
	v_mfma_f32_16x16x32_bf16 v[136:139], v[160:163], v[104:107], v[136:139]
	ds_read_b128 v[236:239], v228 offset:4096
	ds_read_b128 v[240:243], v228 offset:5120
	s_waitcnt lgkmcnt(4)
	v_mfma_f32_16x16x32_bf16 v[132:135], v[164:167], v[92:95], v[132:135]
	v_mfma_f32_16x16x32_bf16 v[128:131], v[164:167], v[100:103], v[128:131]
	v_mfma_f32_16x16x32_bf16 v[124:127], v[164:167], v[116:119], v[124:127]
	v_mfma_f32_16x16x32_bf16 v[120:123], v[164:167], v[104:107], v[120:123]
	s_waitcnt lgkmcnt(3)
; DEV f32x4 mfma16(bf16x8 a, bf16x8 b, f32x4 c) { return __builtin_amdgcn_mfma_f32_16x16x32_bf16(a, b, c, 0, 0, 0); }
; DEV void gemm_tile(const u16* __restrict__ A, size_t lda, const u16* __restrict__ Bt, size_t ldb, int K,
;                    u16* sA, u16* sB, f32x4 (&acc)[8][4]) {
;     ...
;   for (int kt = 0; kt < nk; ++kt) {
;     const int st = kt & 1;
;     if (kt + 1 < nk) S_STORE(st ^ 1)
;     if (kt + 2 < nk) G_LOAD((kt + 2) << 5)
;     {
;       const u16* pa = sAr + st * 12288;
;       const u16* pb = sBr + st * 12288;
;       bf16x8 b[4];
; #pragma unroll
;       for (int ni = 0; ni < 4; ++ni) b[ni] = *(const bf16x8*)(pb + ni * 16 * 32);
; #pragma unroll
;       for (int mh = 0; mh < 2; ++mh) {
;         bf16x8 a[4];
; #pragma unroll
;         for (int mi = 0; mi < 4; ++mi) a[mi] = *(const bf16x8*)(pa + (mh * 64 + mi * 16) * 32);
; #pragma unroll
;         for (int mi = 0; mi < 4; ++mi)
; #pragma unroll
;           for (int ni = 0; ni < 4; ++ni) acc[mh * 4 + mi][ni] = mfma16(a[mi], b[ni], acc[mh * 4 + mi][ni]);
;       }
;     }
;     __syncthreads();
;   }
	v_mfma_f32_16x16x32_bf16 v[96:99], v[168:171], v[92:95], v[96:99]
	v_mfma_f32_16x16x32_bf16 v[88:91], v[168:171], v[100:103], v[88:91]
	v_mfma_f32_16x16x32_bf16 v[84:87], v[168:171], v[116:119], v[84:87]
	v_mfma_f32_16x16x32_bf16 v[80:83], v[168:171], v[104:107], v[80:83]
	ds_read_b128 v[244:247], v228 offset:6144
	ds_read_b128 v[160:163], v228 offset:7168
	s_waitcnt lgkmcnt(4)
	v_mfma_f32_16x16x32_bf16 v[76:79], v[232:235], v[92:95], v[76:79]
	s_waitcnt vmcnt(0)
	v_add_u32_e32 v231, s10, v230
	v_mfma_f32_16x16x32_bf16 v[72:75], v[232:235], v[100:103], v[72:75]
	ds_write_b128 v231, v[252:255]
	v_mfma_f32_16x16x32_bf16 v[68:71], v[232:235], v[116:119], v[68:71]
	ds_write_b128 v231, v[208:211] offset:4096
	v_mfma_f32_16x16x32_bf16 v[64:67], v[232:235], v[104:107], v[64:67]
	ds_write_b128 v231, v[212:215] offset:8192
	s_waitcnt lgkmcnt(6)
	v_mfma_f32_16x16x32_bf16 v[60:63], v[236:239], v[92:95], v[60:63]
	ds_write_b128 v231, v[216:219] offset:12288
	v_mfma_f32_16x16x32_bf16 v[56:59], v[236:239], v[100:103], v[56:59]
	ds_write_b128 v231, v[220:223] offset:16384
	v_mfma_f32_16x16x32_bf16 v[52:55], v[236:239], v[116:119], v[52:55]
	ds_write_b128 v231, v[224:227] offset:20480
	v_mfma_f32_16x16x32_bf16 v[48:51], v[236:239], v[104:107], v[48:51]
	s_add_i32 s10, s7, s5
	s_add_i32 s7, s7, 0x6000
	s_waitcnt lgkmcnt(8)
	v_mfma_f32_16x16x32_bf16 v[44:47], v[240:243], v[92:95], v[44:47]
	s_cmp_eq_u32 s7, 0x12000
	s_cselect_b32 s7, 0, s7
	v_mfma_f32_16x16x32_bf16 v[40:43], v[240:243], v[100:103], v[40:43]
	s_add_u32 s8, s8, 64
	s_addc_u32 s9, s9, 0
	s_cmpk_lg_i32 s8, 0xf80
	v_mfma_f32_16x16x32_bf16 v[36:39], v[240:243], v[116:119], v[36:39]
	v_mfma_f32_16x16x32_bf16 v[32:35], v[240:243], v[104:107], v[32:35]
	s_waitcnt lgkmcnt(7)
	v_mfma_f32_16x16x32_bf16 v[28:31], v[244:247], v[92:95], v[28:31]
	v_mfma_f32_16x16x32_bf16 v[24:27], v[244:247], v[100:103], v[24:27]
	v_mfma_f32_16x16x32_bf16 v[20:23], v[244:247], v[116:119], v[20:23]
	v_mfma_f32_16x16x32_bf16 v[16:19], v[244:247], v[104:107], v[16:19]
	s_waitcnt lgkmcnt(6)
	s_waitcnt lgkmcnt(0)
	s_barrier
	v_mfma_f32_16x16x32_bf16 v[12:15], v[160:163], v[92:95], v[12:15]
	v_mfma_f32_16x16x32_bf16 v[8:11], v[160:163], v[100:103], v[8:11]
	v_mfma_f32_16x16x32_bf16 v[4:7], v[160:163], v[116:119], v[4:7]
	v_mfma_f32_16x16x32_bf16 v[0:3], v[160:163], v[104:107], v[0:3]
	s_cbranch_scc1 .LBB0_162
	ds_read_b128 v[92:95], v158 offset:16384
	ds_read_b128 v[100:103], v158 offset:17408
	ds_read_b128 v[104:107], v158 offset:18432
	ds_read_b128 v[108:111], v158 offset:19456
	ds_read_b128 v[112:115], v156
	ds_read_b128 v[116:119], v156 offset:1024
	ds_read_b128 v[152:155], v156 offset:2048
	ds_read_b128 v[160:163], v156 offset:3072
	s_movk_i32 s5, 0x11f9
	s_waitcnt lgkmcnt(3)
	v_mfma_f32_16x16x32_bf16 v[148:151], v[112:115], v[92:95], v[148:151]
	v_mfma_f32_16x16x32_bf16 v[144:147], v[112:115], v[100:103], v[144:147]
	v_mfma_f32_16x16x32_bf16 v[140:143], v[112:115], v[104:107], v[140:143]
	v_mfma_f32_16x16x32_bf16 v[112:115], v[112:115], v[108:111], v[136:139]
	s_waitcnt lgkmcnt(2)
	v_mfma_f32_16x16x32_bf16 v[132:135], v[116:119], v[92:95], v[132:135]
	v_mfma_f32_16x16x32_bf16 v[128:131], v[116:119], v[100:103], v[128:131]
	v_mfma_f32_16x16x32_bf16 v[136:139], v[116:119], v[104:107], v[124:127]
	v_mfma_f32_16x16x32_bf16 v[164:167], v[116:119], v[108:111], v[120:123]
	s_waitcnt lgkmcnt(1)
	v_mfma_f32_16x16x32_bf16 v[168:171], v[152:155], v[92:95], v[96:99]
	s_nop 2
	ds_read_b128 v[96:99], v156 offset:4096
	ds_read_b128 v[116:119], v156 offset:5120
	ds_read_b128 v[120:123], v156 offset:6144
	ds_read_b128 v[124:127], v156 offset:7168
	s_waitcnt lgkmcnt(0)
	s_waitcnt vmcnt(0)
	s_barrier
	v_mfma_f32_16x16x32_bf16 v[88:91], v[152:155], v[100:103], v[88:91]
	v_mfma_f32_16x16x32_bf16 v[84:87], v[152:155], v[104:107], v[84:87]
	v_mfma_f32_16x16x32_bf16 v[80:83], v[152:155], v[108:111], v[80:83]
	v_mfma_f32_16x16x32_bf16 v[76:79], v[160:163], v[92:95], v[76:79]
	v_mfma_f32_16x16x32_bf16 v[72:75], v[160:163], v[100:103], v[72:75]
	v_mfma_f32_16x16x32_bf16 v[68:71], v[160:163], v[104:107], v[68:71]
	v_mfma_f32_16x16x32_bf16 v[64:67], v[160:163], v[108:111], v[64:67]
	v_mfma_f32_16x16x32_bf16 v[60:63], v[96:99], v[92:95], v[60:63]
	v_mfma_f32_16x16x32_bf16 v[56:59], v[96:99], v[100:103], v[56:59]
	v_mfma_f32_16x16x32_bf16 v[52:55], v[96:99], v[104:107], v[52:55]
	v_mfma_f32_16x16x32_bf16 v[48:51], v[96:99], v[108:111], v[48:51]
	v_mfma_f32_16x16x32_bf16 v[44:47], v[116:119], v[92:95], v[44:47]
	v_mfma_f32_16x16x32_bf16 v[28:31], v[120:123], v[92:95], v[28:31]
	v_mfma_f32_16x16x32_bf16 v[12:15], v[124:127], v[92:95], v[12:15]
	ds_read_b128 v[152:155], v158 offset:40960
	ds_read_b128 v[160:163], v158 offset:41984
	ds_read_b128 v[172:175], v158 offset:43008
	ds_read_b128 v[192:195], v158 offset:44032
	ds_read_b128 v[92:95], v156 offset:24576
	ds_read_b128 v[96:99], v156 offset:25600
	ds_read_b128 v[196:199], v156 offset:26624
	ds_read_b128 v[200:203], v156 offset:27648
	v_mfma_f32_16x16x32_bf16 v[40:43], v[116:119], v[100:103], v[40:43]
	v_mfma_f32_16x16x32_bf16 v[36:39], v[116:119], v[104:107], v[36:39]
	v_mfma_f32_16x16x32_bf16 v[32:35], v[116:119], v[108:111], v[32:35]
	v_mfma_f32_16x16x32_bf16 v[24:27], v[120:123], v[100:103], v[24:27]
	v_mfma_f32_16x16x32_bf16 v[20:23], v[120:123], v[104:107], v[20:23]
	v_mfma_f32_16x16x32_bf16 v[16:19], v[120:123], v[108:111], v[16:19]
	v_mfma_f32_16x16x32_bf16 v[8:11], v[124:127], v[100:103], v[8:11]
	v_mfma_f32_16x16x32_bf16 v[4:7], v[124:127], v[104:107], v[4:7]
	v_mfma_f32_16x16x32_bf16 v[0:3], v[124:127], v[108:111], v[0:3]
	s_waitcnt lgkmcnt(3)
	v_mfma_f32_16x16x32_bf16 v[116:119], v[92:95], v[172:175], v[140:143]
	s_waitcnt lgkmcnt(2)
	v_mfma_f32_16x16x32_bf16 v[108:111], v[96:99], v[152:155], v[132:135]
	v_mfma_f32_16x16x32_bf16 v[104:107], v[96:99], v[160:163], v[128:131]
	v_mfma_f32_16x16x32_bf16 v[100:103], v[96:99], v[172:175], v[136:139]
	s_nop 1
	ds_read_b128 v[128:131], v156 offset:28672
	ds_read_b128 v[132:135], v156 offset:29696
	ds_read_b128 v[136:139], v156 offset:30720
	ds_read_b128 v[140:143], v156 offset:31744
	s_waitcnt lgkmcnt(0)
	s_barrier
; DEV int TID() { int t = threadIdx.x; asm volatile("" : "+v"(t)); return t; }
; DEV f32x4 mfma16(bf16x8 a, bf16x8 b, f32x4 c) { return __builtin_amdgcn_mfma_f32_16x16x32_bf16(a, b, c, 0, 0, 0); }
; DEV void gemm_tile(const u16* __restrict__ A, size_t lda, const u16* __restrict__ Bt, size_t ldb, int K,
;                    u16* sA, u16* sB, f32x4 (&acc)[8][4]) {
;     ...
;       for (int ni = 0; ni < 4; ++ni) b[ni] = *(const bf16x8*)(pb + ni * 16 * 32);
; #pragma unroll
;       for (int mh = 0; mh < 2; ++mh) {
;         bf16x8 a[4];
; #pragma unroll
;         for (int mi = 0; mi < 4; ++mi) a[mi] = *(const bf16x8*)(pa + (mh * 64 + mi * 16) * 32);
; #pragma unroll
;         for (int mi = 0; mi < 4; ++mi)
; #pragma unroll
;           for (int ni = 0; ni < 4; ++ni) acc[mh * 4 + mi][ni] = mfma16(a[mi], b[ni], acc[mh * 4 + mi][ni]);
; DEV void store_tile_bf16(const f32x4 (&acc)[8][4], u16* __restrict__ OUT, size_t ld, int m0, int n0, int ncols,
;                          unsigned char* smem) {
;   const int tid = TID(), lane = tid & 63, wid = tid >> 6;
;   const int wr = wid >> 1, wc = wid & 1, fr = lane & 15, fq = lane >> 4;
;   u16* st = (u16*)(smem + wid * 9216);
; #pragma unroll
;   for (int mh = 0; mh < 2; ++mh) {
; #pragma unroll
;     for (int mi = 0; mi < 4; ++mi)
; #pragma unroll
;       for (int ni = 0; ni < 4; ++ni)
; #pragma unroll
;         for (int j = 0; j < 4; ++j) st[(mi * 16 + fq * 4 + j) * 72 + ni * 16 + fr] = f2bf(acc[mh * 4 + mi][ni][j]);
;     const int chunk = lane & 7;
;     const int c0 = n0 + wc * 64 + chunk * 8;
; #pragma unroll
;     for (int itr = 0; itr < 8; ++itr) {
;       const int rl = (lane >> 3) + 8 * itr;
;       const u32x4 v = *(const u32x4*)(st + rl * 72 + chunk * 8);
;       if (c0 + 8 <= ncols) *(u32x4*)(OUT + (size_t)(m0 + wr * 128 + mh * 64 + rl) * ld + c0) = v;
;     }
;   }
; }
	v_mfma_f32_16x16x32_bf16 v[60:63], v[128:131], v[152:155], v[60:63]
	v_mfma_f32_16x16x32_bf16 v[56:59], v[128:131], v[160:163], v[56:59]
	v_mfma_f32_16x16x32_bf16 v[52:55], v[128:131], v[172:175], v[52:55]
	v_mfma_f32_16x16x32_bf16 v[48:51], v[128:131], v[192:195], v[48:51]
	v_mov_b32_e32 v129, v178
	v_mfma_f32_16x16x32_bf16 v[124:127], v[92:95], v[152:155], v[148:151]
	v_lshrrev_b32_e32 v128, 6, v129
	v_mul_lo_u32 v131, v128, s75
	v_lshrrev_b32_e32 v128, 2, v129
	v_mfma_f32_16x16x32_bf16 v[44:47], v[132:135], v[152:155], v[44:47]
	v_and_b32_e32 v130, 15, v129
	v_lshl_or_b32 v130, v130, 1, v131
	v_mfma_f32_16x16x32_bf16 v[40:43], v[132:135], v[160:163], v[40:43]
	v_mfma_f32_16x16x32_bf16 v[36:39], v[132:135], v[172:175], v[36:39]
	v_mfma_f32_16x16x32_bf16 v[32:35], v[132:135], v[192:195], v[32:35]
	v_lshlrev_b32_e32 v133, 3, v129
	v_and_b32_e32 v132, 12, v128
	v_and_b32_e32 v128, 64, v129
	v_and_b32_e32 v133, 56, v133
	v_or3_b32 v128, v128, s6, v133
	v_lshl_or_b32 v131, v133, 1, v131
	v_bfe_u32 v133, v129, 3, 3
	v_and_b32_e32 v129, 0xffffff80, v129
	v_add_u32_e32 v134, s4, v129
	v_bfe_u32 v135, v124, 16, 1
	s_movk_i32 s4, 0x90
	v_add3_u32 v135, v124, v135, s71
	v_mad_u32_u24 v124, v132, s4, v130
	v_bfe_u32 v130, v125, 16, 1
	v_add3_u32 v125, v125, v130, s71
	v_mfma_f32_16x16x32_bf16 v[120:123], v[92:95], v[160:163], v[144:147]
	ds_write_b16_d16_hi v124, v125 offset:144
	v_bfe_u32 v125, v126, 16, 1
	v_add3_u32 v125, v126, v125, s71
	ds_write_b16_d16_hi v124, v125 offset:288
	v_bfe_u32 v125, v127, 16, 1
	v_add3_u32 v125, v127, v125, s71
	ds_write_b16_d16_hi v124, v125 offset:432
	s_nop 0
	v_bfe_u32 v125, v120, 16, 1
	v_add3_u32 v120, v120, v125, s71
	ds_write_b16_d16_hi v124, v120 offset:32
	v_bfe_u32 v120, v121, 16, 1
	v_add3_u32 v120, v121, v120, s71
	ds_write_b16_d16_hi v124, v120 offset:176
	v_bfe_u32 v120, v122, 16, 1
	v_add3_u32 v120, v122, v120, s71
	ds_write_b16_d16_hi v124, v120 offset:320
	v_bfe_u32 v120, v123, 16, 1
	v_add3_u32 v120, v123, v120, s71
	ds_write_b16_d16_hi v124, v120 offset:464
	v_bfe_u32 v120, v116, 16, 1
	v_add3_u32 v116, v116, v120, s71
	ds_write_b16_d16_hi v124, v116 offset:64
	v_bfe_u32 v116, v117, 16, 1
	v_add3_u32 v116, v117, v116, s71
	v_mfma_f32_16x16x32_bf16 v[112:115], v[92:95], v[192:195], v[112:115]
	ds_write_b16_d16_hi v124, v116 offset:208
	v_bfe_u32 v116, v118, 16, 1
	v_add3_u32 v116, v118, v116, s71
	ds_write_b16_d16_hi v124, v116 offset:352
	v_bfe_u32 v116, v119, 16, 1
	v_add3_u32 v116, v119, v116, s71
	ds_write_b16_d16_hi v124, v116 offset:496
	s_nop 0
	v_bfe_u32 v116, v112, 16, 1
	v_add3_u32 v112, v112, v116, s71
	ds_write_b16_d16_hi v124, v112 offset:96
	v_bfe_u32 v112, v113, 16, 1
	v_add3_u32 v112, v113, v112, s71
	ds_write_b16_d16_hi v124, v112 offset:240
	v_bfe_u32 v112, v114, 16, 1
	v_add3_u32 v112, v114, v112, s71
	ds_write_b16_d16_hi v124, v112 offset:384
	v_bfe_u32 v112, v115, 16, 1
	v_add3_u32 v112, v115, v112, s71
	ds_write_b16_d16_hi v124, v112 offset:528
	v_bfe_u32 v112, v108, 16, 1
	v_add3_u32 v108, v108, v112, s71
	ds_write_b16_d16_hi v124, v108 offset:2304
	v_bfe_u32 v108, v109, 16, 1
	v_add3_u32 v108, v109, v108, s71
	ds_write_b16_d16_hi v124, v108 offset:2448
	v_bfe_u32 v108, v110, 16, 1
	v_add3_u32 v108, v110, v108, s71
	ds_write_b16_d16_hi v124, v108 offset:2592
	v_bfe_u32 v108, v111, 16, 1
	v_add3_u32 v108, v111, v108, s71
	ds_write_b16_d16_hi v124, v108 offset:2736
	v_bfe_u32 v108, v104, 16, 1
	v_add3_u32 v104, v104, v108, s71
	ds_write_b16_d16_hi v124, v104 offset:2336
	v_bfe_u32 v104, v105, 16, 1
	v_add3_u32 v104, v105, v104, s71
	ds_write_b16_d16_hi v124, v104 offset:2480
	v_bfe_u32 v104, v106, 16, 1
	v_add3_u32 v104, v106, v104, s71
	ds_write_b16_d16_hi v124, v104 offset:2624
	v_bfe_u32 v104, v107, 16, 1
	v_add3_u32 v104, v107, v104, s71
	ds_write_b16_d16_hi v124, v104 offset:2768
	v_bfe_u32 v104, v100, 16, 1
	v_add3_u32 v100, v100, v104, s71
	ds_write_b16_d16_hi v124, v100 offset:2368
	v_bfe_u32 v100, v101, 16, 1
	v_add3_u32 v100, v101, v100, s71
	v_mfma_f32_16x16x32_bf16 v[96:99], v[96:99], v[192:195], v[164:167]
	ds_write_b16_d16_hi v124, v100 offset:2512
	v_bfe_u32 v100, v102, 16, 1
	v_add3_u32 v100, v102, v100, s71
	ds_write_b16_d16_hi v124, v100 offset:2656
	v_bfe_u32 v100, v103, 16, 1
	v_add3_u32 v100, v103, v100, s71
	ds_write_b16_d16_hi v124, v100 offset:2800
	s_nop 0
	v_bfe_u32 v100, v96, 16, 1
	v_add3_u32 v96, v96, v100, s71
	ds_write_b16_d16_hi v124, v96 offset:2400
	v_bfe_u32 v96, v97, 16, 1
	v_add3_u32 v96, v97, v96, s71
	v_mfma_f32_16x16x32_bf16 v[92:95], v[196:199], v[152:155], v[168:171]
	ds_write_b16_d16_hi v124, v96 offset:2544
	v_bfe_u32 v96, v98, 16, 1
	v_add3_u32 v96, v98, v96, s71
	ds_write_b16_d16_hi v124, v96 offset:2688
	v_bfe_u32 v96, v99, 16, 1
	v_add3_u32 v96, v99, v96, s71
	ds_write_b16_d16_hi v124, v96 offset:2832
	s_nop 0
	v_bfe_u32 v96, v92, 16, 1
	v_add3_u32 v92, v92, v96, s71
	ds_write_b16_d16_hi v124, v92 offset:4608
	v_bfe_u32 v92, v93, 16, 1
	v_add3_u32 v92, v93, v92, s71
	v_mfma_f32_16x16x32_bf16 v[88:91], v[196:199], v[160:163], v[88:91]
	ds_write_b16_d16_hi v124, v92 offset:4752
	v_bfe_u32 v92, v94, 16, 1
	v_add3_u32 v92, v94, v92, s71
	ds_write_b16_d16_hi v124, v92 offset:4896
	v_bfe_u32 v92, v95, 16, 1
	v_add3_u32 v92, v95, v92, s71
	ds_write_b16_d16_hi v124, v92 offset:5040
	s_nop 0
	v_bfe_u32 v92, v88, 16, 1
	v_add3_u32 v88, v88, v92, s71
	ds_write_b16_d16_hi v124, v88 offset:4640
	v_bfe_u32 v88, v89, 16, 1
	v_add3_u32 v88, v89, v88, s71
; DEV int TID() { int t = threadIdx.x; asm volatile("" : "+v"(t)); return t; }
; DEV f32x4 mfma16(bf16x8 a, bf16x8 b, f32x4 c) { return __builtin_amdgcn_mfma_f32_16x16x32_bf16(a, b, c, 0, 0, 0); }
; DEV void gemm_tile(const u16* __restrict__ A, size_t lda, const u16* __restrict__ Bt, size_t ldb, int K,
;                    u16* sA, u16* sB, f32x4 (&acc)[8][4]) {
;     ...
;       for (int ni = 0; ni < 4; ++ni) b[ni] = *(const bf16x8*)(pb + ni * 16 * 32);
; #pragma unroll
;       for (int mh = 0; mh < 2; ++mh) {
;         bf16x8 a[4];
; #pragma unroll
;         for (int mi = 0; mi < 4; ++mi) a[mi] = *(const bf16x8*)(pa + (mh * 64 + mi * 16) * 32);
; #pragma unroll
;         for (int mi = 0; mi < 4; ++mi)
; #pragma unroll
;           for (int ni = 0; ni < 4; ++ni) acc[mh * 4 + mi][ni] = mfma16(a[mi], b[ni], acc[mh * 4 + mi][ni]);
; DEV void store_tile_bf16(const f32x4 (&acc)[8][4], u16* __restrict__ OUT, size_t ld, int m0, int n0, int ncols,
;                          unsigned char* smem) {
;   const int tid = TID(), lane = tid & 63, wid = tid >> 6;
;   const int wr = wid >> 1, wc = wid & 1, fr = lane & 15, fq = lane >> 4;
;   u16* st = (u16*)(smem + wid * 9216);
; #pragma unroll
;   for (int mh = 0; mh < 2; ++mh) {
; #pragma unroll
;     for (int mi = 0; mi < 4; ++mi)
; #pragma unroll
;       for (int ni = 0; ni < 4; ++ni)
; #pragma unroll
;         for (int j = 0; j < 4; ++j) st[(mi * 16 + fq * 4 + j) * 72 + ni * 16 + fr] = f2bf(acc[mh * 4 + mi][ni][j]);
;     const int chunk = lane & 7;
;     const int c0 = n0 + wc * 64 + chunk * 8;
; #pragma unroll
;     for (int itr = 0; itr < 8; ++itr) {
;       const int rl = (lane >> 3) + 8 * itr;
;       const u32x4 v = *(const u32x4*)(st + rl * 72 + chunk * 8);
;       if (c0 + 8 <= ncols) *(u32x4*)(OUT + (size_t)(m0 + wr * 128 + mh * 64 + rl) * ld + c0) = v;
;     }
;   }
; }
	v_mfma_f32_16x16x32_bf16 v[84:87], v[196:199], v[172:175], v[84:87]
	ds_write_b16_d16_hi v124, v88 offset:4784
	v_bfe_u32 v88, v90, 16, 1
	v_add3_u32 v88, v90, v88, s71
	ds_write_b16_d16_hi v124, v88 offset:4928
	v_bfe_u32 v88, v91, 16, 1
	v_add3_u32 v88, v91, v88, s71
	ds_write_b16_d16_hi v124, v88 offset:5072
	s_nop 0
	v_bfe_u32 v88, v84, 16, 1
	v_add3_u32 v84, v84, v88, s71
	ds_write_b16_d16_hi v124, v84 offset:4672
	v_bfe_u32 v84, v85, 16, 1
	v_add3_u32 v84, v85, v84, s71
	v_mfma_f32_16x16x32_bf16 v[80:83], v[196:199], v[192:195], v[80:83]
	ds_write_b16_d16_hi v124, v84 offset:4816
	v_bfe_u32 v84, v86, 16, 1
	v_add3_u32 v84, v86, v84, s71
	ds_write_b16_d16_hi v124, v84 offset:4960
	v_bfe_u32 v84, v87, 16, 1
	v_add3_u32 v84, v87, v84, s71
	ds_write_b16_d16_hi v124, v84 offset:5104
	s_nop 0
	v_bfe_u32 v84, v80, 16, 1
	v_add3_u32 v80, v80, v84, s71
	ds_write_b16_d16_hi v124, v80 offset:4704
	v_bfe_u32 v80, v81, 16, 1
	v_add3_u32 v80, v81, v80, s71
	v_mfma_f32_16x16x32_bf16 v[76:79], v[200:203], v[152:155], v[76:79]
	ds_write_b16_d16_hi v124, v80 offset:4848
	v_bfe_u32 v80, v82, 16, 1
	v_add3_u32 v80, v82, v80, s71
	ds_write_b16_d16_hi v124, v80 offset:4992
	v_bfe_u32 v80, v83, 16, 1
	v_add3_u32 v80, v83, v80, s71
	ds_write_b16_d16_hi v124, v80 offset:5136
	s_nop 0
	v_bfe_u32 v80, v76, 16, 1
	v_add3_u32 v76, v76, v80, s71
	ds_write_b16_d16_hi v124, v76 offset:6912
	v_bfe_u32 v76, v77, 16, 1
	v_add3_u32 v76, v77, v76, s71
	v_mfma_f32_16x16x32_bf16 v[72:75], v[200:203], v[160:163], v[72:75]
	ds_write_b16_d16_hi v124, v76 offset:7056
	v_bfe_u32 v76, v78, 16, 1
	v_add3_u32 v76, v78, v76, s71
	ds_write_b16_d16_hi v124, v76 offset:7200
	v_bfe_u32 v76, v79, 16, 1
	v_add3_u32 v76, v79, v76, s71
	ds_write_b16_d16_hi v124, v76 offset:7344
	s_nop 0
	v_bfe_u32 v76, v72, 16, 1
	v_add3_u32 v72, v72, v76, s71
	ds_write_b16_d16_hi v124, v72 offset:6944
	v_bfe_u32 v72, v73, 16, 1
	v_add3_u32 v72, v73, v72, s71
	v_mfma_f32_16x16x32_bf16 v[68:71], v[200:203], v[172:175], v[68:71]
	ds_write_b16_d16_hi v124, v72 offset:7088
	v_bfe_u32 v72, v74, 16, 1
	v_add3_u32 v72, v74, v72, s71
	ds_write_b16_d16_hi v124, v72 offset:7232
	v_bfe_u32 v72, v75, 16, 1
	v_add3_u32 v72, v75, v72, s71
	ds_write_b16_d16_hi v124, v72 offset:7376
	s_nop 0
	v_bfe_u32 v72, v68, 16, 1
	v_add3_u32 v68, v68, v72, s71
	ds_write_b16_d16_hi v124, v68 offset:6976
	v_bfe_u32 v68, v69, 16, 1
	v_add3_u32 v68, v69, v68, s71
	v_mfma_f32_16x16x32_bf16 v[64:67], v[200:203], v[192:195], v[64:67]
	ds_write_b16_d16_hi v124, v68 offset:7120
	v_bfe_u32 v68, v70, 16, 1
	v_add3_u32 v68, v70, v68, s71
	ds_write_b16_d16_hi v124, v68 offset:7264
	v_bfe_u32 v68, v71, 16, 1
	v_add3_u32 v68, v71, v68, s71
	ds_write_b16_d16_hi v124, v68 offset:7408
	s_nop 0
	v_bfe_u32 v68, v64, 16, 1
	v_add3_u32 v64, v64, v68, s71
	ds_write_b16_d16_hi v124, v64 offset:7008
	v_bfe_u32 v64, v65, 16, 1
	v_add3_u32 v64, v65, v64, s71
	ds_write_b16_d16_hi v124, v64 offset:7152
	v_bfe_u32 v64, v66, 16, 1
	v_mfma_f32_16x16x32_bf16 v[28:31], v[136:139], v[152:155], v[28:31]
	v_add3_u32 v64, v66, v64, s71
	ds_write_b16_d16_hi v124, v64 offset:7296
	v_bfe_u32 v64, v67, 16, 1
	v_mfma_f32_16x16x32_bf16 v[24:27], v[136:139], v[160:163], v[24:27]
	v_ashrrev_i32_e32 v129, 31, v128
	v_add3_u32 v64, v67, v64, s71
	v_cmp_gt_i32_e32 vcc, s5, v128
	v_mfma_f32_16x16x32_bf16 v[20:23], v[136:139], v[172:175], v[20:23]
	v_lshl_add_u64 v[128:129], v[128:129], 1, s[68:69]
	ds_write_b16_d16_hi v124, v64 offset:7440
	v_mad_u32_u24 v65, v133, s4, v131
	v_mfma_f32_16x16x32_bf16 v[16:19], v[136:139], v[192:195], v[16:19]
	v_or_b32_e32 v64, v134, v133
	ds_write_b16_d16_hi v124, v135
	v_mfma_f32_16x16x32_bf16 v[12:15], v[140:143], v[152:155], v[12:15]
	v_mfma_f32_16x16x32_bf16 v[8:11], v[140:143], v[160:163], v[8:11]
	v_mfma_f32_16x16x32_bf16 v[4:7], v[140:143], v[172:175], v[4:7]
	v_mfma_f32_16x16x32_bf16 v[0:3], v[140:143], v[192:195], v[0:3]
	s_and_saveexec_b64 s[4:5], vcc
	s_cbranch_execz .LBB0_165
	ds_read_b128 v[66:69], v65
	v_mad_i64_i32 v[70:71], s[6:7], v64, s75, v[128:129]
	s_waitcnt lgkmcnt(0)
	global_store_dwordx4 v[70:71], v[66:69], off
	ds_read_b128 v[66:69], v65 offset:1152
	v_or_b32_e32 v70, 8, v64
	v_mad_i64_i32 v[70:71], s[6:7], v70, s75, v[128:129]
	s_waitcnt lgkmcnt(0)
	global_store_dwordx4 v[70:71], v[66:69], off
	ds_read_b128 v[66:69], v65 offset:2304
	v_or_b32_e32 v70, 16, v64
	v_mad_i64_i32 v[70:71], s[6:7], v70, s75, v[128:129]
	s_waitcnt lgkmcnt(0)
	global_store_dwordx4 v[70:71], v[66:69], off
	ds_read_b128 v[66:69], v65 offset:3456
	v_or_b32_e32 v70, 24, v64
	v_mad_i64_i32 v[70:71], s[6:7], v70, s75, v[128:129]
	s_waitcnt lgkmcnt(0)
	global_store_dwordx4 v[70:71], v[66:69], off
	ds_read_b128 v[66:69], v65 offset:4608
	v_or_b32_e32 v70, 32, v64
	v_mad_i64_i32 v[70:71], s[6:7], v70, s75, v[128:129]
	s_waitcnt lgkmcnt(0)
	global_store_dwordx4 v[70:71], v[66:69], off
	ds_read_b128 v[66:69], v65 offset:5760
	v_or_b32_e32 v70, 40, v64
	v_mad_i64_i32 v[70:71], s[6:7], v70, s75, v[128:129]
	s_waitcnt lgkmcnt(0)
	global_store_dwordx4 v[70:71], v[66:69], off
	ds_read_b128 v[66:69], v65 offset:6912
	v_or_b32_e32 v70, 48, v64
	v_mad_i64_i32 v[70:71], s[6:7], v70, s75, v[128:129]
	s_waitcnt lgkmcnt(0)
	global_store_dwordx4 v[70:71], v[66:69], off
	ds_read_b128 v[66:69], v65 offset:8064
	v_or_b32_e32 v70, 56, v64
	v_mad_i64_i32 v[70:71], s[6:7], v70, s75, v[128:129]
	s_waitcnt lgkmcnt(0)
	global_store_dwordx4 v[70:71], v[66:69], off

; DEV f32x4 mfma16(bf16x8 a, bf16x8 b, f32x4 c) { return __builtin_amdgcn_mfma_f32_16x16x32_bf16(a, b, c, 0, 0, 0); }
; DEV void gemm_tile(const u16* __restrict__ A, size_t lda, const u16* __restrict__ Bt, size_t ldb, int K,
;                    u16* sA, u16* sB, f32x4 (&acc)[8][4]) {
;     ...
;   for (int kt = 0; kt < nk; ++kt) {
;     const int st = kt & 1;
;     if (kt + 1 < nk) S_STORE(st ^ 1)
;     if (kt + 2 < nk) G_LOAD((kt + 2) << 5)
;     {
;       const u16* pa = sAr + st * 12288;
;       const u16* pb = sBr + st * 12288;
;       bf16x8 b[4];
; #pragma unroll
;       for (int ni = 0; ni < 4; ++ni) b[ni] = *(const bf16x8*)(pb + ni * 16 * 32);
; #pragma unroll
;       for (int mh = 0; mh < 2; ++mh) {
;         bf16x8 a[4];
; #pragma unroll
;         for (int mi = 0; mi < 4; ++mi) a[mi] = *(const bf16x8*)(pa + (mh * 64 + mi * 16) * 32);
; #pragma unroll
;         for (int mi = 0; mi < 4; ++mi)
; #pragma unroll
;           for (int ni = 0; ni < 4; ++ni) acc[mh * 4 + mi][ni] = mfma16(a[mi], b[ni], acc[mh * 4 + mi][ni]);
;       }
;     }
;     __syncthreads();
;   }
.LBB0_198:
	v_add_u32_e32 v229, s8, v166
	v_add_u32_e32 v228, s8, v156
	ds_read_b128 v[116:119], v229 offset:16384
	ds_read_b128 v[168:171], v228
	ds_read_b128 v[128:131], v229 offset:17408
	ds_read_b128 v[140:143], v229 offset:18432
	ds_read_b128 v[120:123], v229 offset:19456
	ds_read_b128 v[152:155], v228 offset:1024
	ds_read_b128 v[172:175], v228 offset:2048
	ds_read_b128 v[132:135], v228 offset:3072
	s_waitcnt lgkmcnt(6)
	v_mfma_f32_16x16x32_bf16 v[148:151], v[168:171], v[116:119], v[148:151]
	s_add_i32 m0, s9, 0x0
	s_waitcnt lgkmcnt(5)
	v_mfma_f32_16x16x32_bf16 v[144:147], v[168:171], v[128:131], v[144:147]
	global_load_lds_dwordx4 v[136:137], off
	v_lshl_add_u64 v[136:137], v[136:137], 0, 64
	global_load_dwordx4 v[244:247], v[136:137], off
	v_lshl_add_u64 v[136:137], v[136:137], 0, 64
	s_waitcnt lgkmcnt(4)
	v_mfma_f32_16x16x32_bf16 v[124:127], v[168:171], v[140:143], v[124:127]
	s_add_i32 m0, s9, 0x1000
	s_waitcnt lgkmcnt(3)
	v_mfma_f32_16x16x32_bf16 v[112:115], v[168:171], v[120:123], v[112:115]
	ds_read_b128 v[232:235], v228 offset:4096
	ds_read_b128 v[236:239], v228 offset:5120
	s_waitcnt lgkmcnt(4)
	v_mfma_f32_16x16x32_bf16 v[108:111], v[152:155], v[116:119], v[108:111]
	global_load_lds_dwordx4 v[138:139], off
	v_lshl_add_u64 v[138:139], v[138:139], 0, 64
	global_load_dwordx4 v[252:255], v[138:139], off
	v_lshl_add_u64 v[138:139], v[138:139], 0, 64
	v_mfma_f32_16x16x32_bf16 v[104:107], v[152:155], v[128:131], v[104:107]
	s_add_i32 m0, s9, 0x2000
	v_mfma_f32_16x16x32_bf16 v[100:103], v[152:155], v[140:143], v[100:103]
	global_load_lds_dwordx4 v[176:177], off
	v_lshl_add_u64 v[176:177], v[176:177], 0, 64
	global_load_dwordx4 v[208:211], v[176:177], off
	v_lshl_add_u64 v[176:177], v[176:177], 0, 64
	v_mfma_f32_16x16x32_bf16 v[96:99], v[152:155], v[120:123], v[96:99]
	s_add_i32 m0, s9, 0x3000
	s_waitcnt lgkmcnt(3)
	v_mfma_f32_16x16x32_bf16 v[92:95], v[172:175], v[116:119], v[92:95]
	global_load_lds_dwordx4 v[186:187], off
	v_lshl_add_u64 v[186:187], v[186:187], 0, 64
	global_load_dwordx4 v[212:215], v[186:187], off
	v_lshl_add_u64 v[186:187], v[186:187], 0, 64
	v_mfma_f32_16x16x32_bf16 v[88:91], v[172:175], v[128:131], v[88:91]
	s_add_i32 m0, s9, 0x4000
	v_mfma_f32_16x16x32_bf16 v[84:87], v[172:175], v[140:143], v[84:87]
	global_load_lds_dwordx4 v[188:189], off
	v_lshl_add_u64 v[188:189], v[188:189], 0, 64
	global_load_dwordx4 v[216:219], v[188:189], off
	v_lshl_add_u64 v[188:189], v[188:189], 0, 64
	v_mfma_f32_16x16x32_bf16 v[80:83], v[172:175], v[120:123], v[80:83]
	ds_read_b128 v[240:243], v228 offset:6144
	ds_read_b128 v[168:171], v228 offset:7168
	s_waitcnt lgkmcnt(4)
	v_mfma_f32_16x16x32_bf16 v[76:79], v[132:135], v[116:119], v[76:79]
	s_add_i32 m0, s9, 0x5000
	v_mfma_f32_16x16x32_bf16 v[72:75], v[132:135], v[128:131], v[72:75]
	global_load_lds_dwordx4 v[192:193], off
	v_lshl_add_u64 v[192:193], v[192:193], 0, 64
	global_load_dwordx4 v[220:223], v[192:193], off
	v_lshl_add_u64 v[192:193], v[192:193], 0, 64
	v_mfma_f32_16x16x32_bf16 v[68:71], v[132:135], v[140:143], v[68:71]
	s_add_i32 s9, s8, s5
	s_add_i32 s8, s8, 0x6000
	v_mfma_f32_16x16x32_bf16 v[64:67], v[132:135], v[120:123], v[64:67]
	s_cmp_eq_u32 s8, 0x12000
	s_cselect_b32 s8, 0, s8
	s_waitcnt lgkmcnt(3)
	v_mfma_f32_16x16x32_bf16 v[60:63], v[232:235], v[116:119], v[60:63]
	s_add_u32 s6, s6, 64
	s_addc_u32 s7, s7, 0
	s_cmpk_lg_i32 s6, 0xf80
	v_mfma_f32_16x16x32_bf16 v[56:59], v[232:235], v[128:131], v[56:59]
	v_mfma_f32_16x16x32_bf16 v[52:55], v[232:235], v[140:143], v[52:55]
	v_mfma_f32_16x16x32_bf16 v[48:51], v[232:235], v[120:123], v[48:51]
	s_waitcnt lgkmcnt(2)
	v_mfma_f32_16x16x32_bf16 v[44:47], v[236:239], v[116:119], v[44:47]
	v_mfma_f32_16x16x32_bf16 v[40:43], v[236:239], v[128:131], v[40:43]
	v_mfma_f32_16x16x32_bf16 v[36:39], v[236:239], v[140:143], v[36:39]
	v_mfma_f32_16x16x32_bf16 v[32:35], v[236:239], v[120:123], v[32:35]
	s_waitcnt lgkmcnt(1)
	v_mfma_f32_16x16x32_bf16 v[28:31], v[240:243], v[116:119], v[28:31]
	v_mfma_f32_16x16x32_bf16 v[24:27], v[240:243], v[128:131], v[24:27]
	v_mfma_f32_16x16x32_bf16 v[20:23], v[240:243], v[140:143], v[20:23]
	v_mfma_f32_16x16x32_bf16 v[16:19], v[240:243], v[120:123], v[16:19]
	s_waitcnt lgkmcnt(0)
	s_waitcnt vmcnt(12)
	s_barrier
	v_mfma_f32_16x16x32_bf16 v[12:15], v[168:171], v[116:119], v[12:15]
	v_mfma_f32_16x16x32_bf16 v[8:11], v[168:171], v[128:131], v[8:11]
	v_mfma_f32_16x16x32_bf16 v[4:7], v[168:171], v[140:143], v[4:7]
	v_mfma_f32_16x16x32_bf16 v[0:3], v[168:171], v[120:123], v[0:3]
	v_add_u32_e32 v229, s8, v166
	v_add_u32_e32 v228, s8, v156
	ds_read_b128 v[116:119], v229 offset:16384
	ds_read_b128 v[168:171], v228
	ds_read_b128 v[128:131], v229 offset:17408
	ds_read_b128 v[140:143], v229 offset:18432
	ds_read_b128 v[120:123], v229 offset:19456
	ds_read_b128 v[152:155], v228 offset:1024
	ds_read_b128 v[172:175], v228 offset:2048
	ds_read_b128 v[132:135], v228 offset:3072
	s_waitcnt lgkmcnt(6)
	v_mfma_f32_16x16x32_bf16 v[148:151], v[168:171], v[116:119], v[148:151]
	s_waitcnt lgkmcnt(5)
	v_mfma_f32_16x16x32_bf16 v[144:147], v[168:171], v[128:131], v[144:147]
	s_waitcnt lgkmcnt(4)
	v_mfma_f32_16x16x32_bf16 v[124:127], v[168:171], v[140:143], v[124:127]
	s_waitcnt lgkmcnt(3)
	v_mfma_f32_16x16x32_bf16 v[112:115], v[168:171], v[120:123], v[112:115]
	ds_read_b128 v[232:235], v228 offset:4096
	ds_read_b128 v[236:239], v228 offset:5120
	s_waitcnt lgkmcnt(4)
	v_mfma_f32_16x16x32_bf16 v[108:111], v[152:155], v[116:119], v[108:111]
	v_mfma_f32_16x16x32_bf16 v[104:107], v[152:155], v[128:131], v[104:107]
	v_mfma_f32_16x16x32_bf16 v[100:103], v[152:155], v[140:143], v[100:103]
	v_mfma_f32_16x16x32_bf16 v[96:99], v[152:155], v[120:123], v[96:99]
	s_waitcnt lgkmcnt(3)
; DEV f32x4 mfma16(bf16x8 a, bf16x8 b, f32x4 c) { return __builtin_amdgcn_mfma_f32_16x16x32_bf16(a, b, c, 0, 0, 0); }
; DEV void gemm_tile(const u16* __restrict__ A, size_t lda, const u16* __restrict__ Bt, size_t ldb, int K,
;                    u16* sA, u16* sB, f32x4 (&acc)[8][4]) {
;     ...
;   for (int kt = 0; kt < nk; ++kt) {
;     const int st = kt & 1;
;     if (kt + 1 < nk) S_STORE(st ^ 1)
;     if (kt + 2 < nk) G_LOAD((kt + 2) << 5)
;     {
;       const u16* pa = sAr + st * 12288;
;       const u16* pb = sBr + st * 12288;
;       bf16x8 b[4];
; #pragma unroll
;       for (int ni = 0; ni < 4; ++ni) b[ni] = *(const bf16x8*)(pb + ni * 16 * 32);
; #pragma unroll
;       for (int mh = 0; mh < 2; ++mh) {
;         bf16x8 a[4];
; #pragma unroll
;         for (int mi = 0; mi < 4; ++mi) a[mi] = *(const bf16x8*)(pa + (mh * 64 + mi * 16) * 32);
; #pragma unroll
;         for (int mi = 0; mi < 4; ++mi)
; #pragma unroll
;           for (int ni = 0; ni < 4; ++ni) acc[mh * 4 + mi][ni] = mfma16(a[mi], b[ni], acc[mh * 4 + mi][ni]);
;       }
;     }
;     __syncthreads();
;   }
	v_mfma_f32_16x16x32_bf16 v[92:95], v[172:175], v[116:119], v[92:95]
	v_mfma_f32_16x16x32_bf16 v[88:91], v[172:175], v[128:131], v[88:91]
	v_mfma_f32_16x16x32_bf16 v[84:87], v[172:175], v[140:143], v[84:87]
	v_mfma_f32_16x16x32_bf16 v[80:83], v[172:175], v[120:123], v[80:83]
	ds_read_b128 v[240:243], v228 offset:6144
	ds_read_b128 v[168:171], v228 offset:7168
	s_waitcnt lgkmcnt(4)
	v_mfma_f32_16x16x32_bf16 v[76:79], v[132:135], v[116:119], v[76:79]
	s_waitcnt vmcnt(0)
	v_add_u32_e32 v231, s9, v230
	v_mfma_f32_16x16x32_bf16 v[72:75], v[132:135], v[128:131], v[72:75]
	ds_write_b128 v231, v[244:247]
	v_mfma_f32_16x16x32_bf16 v[68:71], v[132:135], v[140:143], v[68:71]
	ds_write_b128 v231, v[252:255] offset:4096
	v_mfma_f32_16x16x32_bf16 v[64:67], v[132:135], v[120:123], v[64:67]
	ds_write_b128 v231, v[208:211] offset:8192
	s_waitcnt lgkmcnt(6)
	v_mfma_f32_16x16x32_bf16 v[60:63], v[232:235], v[116:119], v[60:63]
	ds_write_b128 v231, v[212:215] offset:12288
	v_mfma_f32_16x16x32_bf16 v[56:59], v[232:235], v[128:131], v[56:59]
	ds_write_b128 v231, v[216:219] offset:16384
	v_mfma_f32_16x16x32_bf16 v[52:55], v[232:235], v[140:143], v[52:55]
	ds_write_b128 v231, v[220:223] offset:20480
	v_mfma_f32_16x16x32_bf16 v[48:51], v[232:235], v[120:123], v[48:51]
	s_add_i32 s9, s8, s5
	s_add_i32 s8, s8, 0x6000
	s_waitcnt lgkmcnt(8)
	v_mfma_f32_16x16x32_bf16 v[44:47], v[236:239], v[116:119], v[44:47]
	s_cmp_eq_u32 s8, 0x12000
	s_cselect_b32 s8, 0, s8
	v_mfma_f32_16x16x32_bf16 v[40:43], v[236:239], v[128:131], v[40:43]
	s_add_u32 s6, s6, 64
	s_addc_u32 s7, s7, 0
	s_cmpk_lg_i32 s6, 0xf80
	v_mfma_f32_16x16x32_bf16 v[36:39], v[236:239], v[140:143], v[36:39]
	v_mfma_f32_16x16x32_bf16 v[32:35], v[236:239], v[120:123], v[32:35]
	s_waitcnt lgkmcnt(7)
	v_mfma_f32_16x16x32_bf16 v[28:31], v[240:243], v[116:119], v[28:31]
	v_mfma_f32_16x16x32_bf16 v[24:27], v[240:243], v[128:131], v[24:27]
	v_mfma_f32_16x16x32_bf16 v[20:23], v[240:243], v[140:143], v[20:23]
	v_mfma_f32_16x16x32_bf16 v[16:19], v[240:243], v[120:123], v[16:19]
	s_waitcnt lgkmcnt(6)
	s_waitcnt lgkmcnt(0)
	s_barrier
	v_mfma_f32_16x16x32_bf16 v[12:15], v[168:171], v[116:119], v[12:15]
	v_mfma_f32_16x16x32_bf16 v[8:11], v[168:171], v[128:131], v[8:11]
	v_mfma_f32_16x16x32_bf16 v[4:7], v[168:171], v[140:143], v[4:7]
	v_mfma_f32_16x16x32_bf16 v[0:3], v[168:171], v[120:123], v[0:3]
	s_cbranch_scc1 .LBB0_198
	ds_read_b128 v[116:119], v166 offset:16384
	ds_read_b128 v[120:123], v166 offset:17408
	ds_read_b128 v[128:131], v166 offset:18432
	ds_read_b128 v[132:135], v166 offset:19456
	ds_read_b128 v[136:139], v156
	ds_read_b128 v[140:143], v156 offset:1024
	ds_read_b128 v[152:155], v156 offset:2048
	ds_read_b128 v[162:165], v156 offset:3072
	s_movk_i32 s5, 0x2200
	s_waitcnt lgkmcnt(3)
	v_mfma_f32_16x16x32_bf16 v[148:151], v[136:139], v[116:119], v[148:151]
	s_movk_i32 s8, 0x110
	v_mfma_f32_16x16x32_bf16 v[144:147], v[136:139], v[120:123], v[144:147]
	v_mfma_f32_16x16x32_bf16 v[124:127], v[136:139], v[128:131], v[124:127]
	v_mfma_f32_16x16x32_bf16 v[112:115], v[136:139], v[132:135], v[112:115]
	s_waitcnt lgkmcnt(2)
	v_mfma_f32_16x16x32_bf16 v[108:111], v[140:143], v[116:119], v[108:111]
	v_mfma_f32_16x16x32_bf16 v[104:107], v[140:143], v[120:123], v[104:107]
	v_mfma_f32_16x16x32_bf16 v[100:103], v[140:143], v[128:131], v[100:103]
	v_mfma_f32_16x16x32_bf16 v[96:99], v[140:143], v[132:135], v[96:99]
	s_waitcnt lgkmcnt(1)
	v_mfma_f32_16x16x32_bf16 v[92:95], v[152:155], v[116:119], v[92:95]
	v_mfma_f32_16x16x32_bf16 v[88:91], v[152:155], v[120:123], v[88:91]
	v_mfma_f32_16x16x32_bf16 v[84:87], v[152:155], v[128:131], v[84:87]
	v_mfma_f32_16x16x32_bf16 v[80:83], v[152:155], v[132:135], v[80:83]
	s_waitcnt lgkmcnt(0)
	v_mfma_f32_16x16x32_bf16 v[76:79], v[162:165], v[116:119], v[76:79]
	v_mfma_f32_16x16x32_bf16 v[72:75], v[162:165], v[120:123], v[72:75]
	v_mfma_f32_16x16x32_bf16 v[68:71], v[162:165], v[128:131], v[68:71]
	v_mfma_f32_16x16x32_bf16 v[64:67], v[162:165], v[132:135], v[64:67]
	ds_read_b128 v[136:139], v156 offset:4096
	ds_read_b128 v[140:143], v156 offset:5120
	ds_read_b128 v[152:155], v156 offset:6144
	ds_read_b128 v[162:165], v156 offset:7168
	s_waitcnt lgkmcnt(0)
	s_waitcnt vmcnt(0)
	s_barrier
	v_mfma_f32_16x16x32_bf16 v[60:63], v[136:139], v[116:119], v[60:63]
	v_mfma_f32_16x16x32_bf16 v[56:59], v[136:139], v[120:123], v[56:59]
	v_mfma_f32_16x16x32_bf16 v[52:55], v[136:139], v[128:131], v[52:55]
	v_mfma_f32_16x16x32_bf16 v[48:51], v[136:139], v[132:135], v[48:51]
	v_mfma_f32_16x16x32_bf16 v[44:47], v[140:143], v[116:119], v[44:47]
	v_mfma_f32_16x16x32_bf16 v[40:43], v[140:143], v[120:123], v[40:43]
	v_mfma_f32_16x16x32_bf16 v[36:39], v[140:143], v[128:131], v[36:39]
	v_mfma_f32_16x16x32_bf16 v[32:35], v[140:143], v[132:135], v[32:35]
	v_mfma_f32_16x16x32_bf16 v[28:31], v[152:155], v[116:119], v[28:31]
	v_mfma_f32_16x16x32_bf16 v[24:27], v[152:155], v[120:123], v[24:27]
	v_mfma_f32_16x16x32_bf16 v[20:23], v[152:155], v[128:131], v[20:23]
	v_mfma_f32_16x16x32_bf16 v[16:19], v[152:155], v[132:135], v[16:19]
	v_mfma_f32_16x16x32_bf16 v[12:15], v[162:165], v[116:119], v[12:15]
	v_mfma_f32_16x16x32_bf16 v[8:11], v[162:165], v[120:123], v[8:11]
	v_mfma_f32_16x16x32_bf16 v[4:7], v[162:165], v[128:131], v[4:7]
	v_mfma_f32_16x16x32_bf16 v[0:3], v[162:165], v[132:135], v[0:3]
	ds_read_b128 v[116:119], v166 offset:40960
	ds_read_b128 v[120:123], v166 offset:41984
	ds_read_b128 v[128:131], v166 offset:43008
	ds_read_b128 v[132:135], v166 offset:44032
	ds_read_b128 v[136:139], v156 offset:24576
	ds_read_b128 v[140:143], v156 offset:25600
	ds_read_b128 v[152:155], v156 offset:26624
	ds_read_b128 v[162:165], v156 offset:27648
	s_waitcnt lgkmcnt(3)
; DEV int TID() { int t = threadIdx.x; asm volatile("" : "+v"(t)); return t; }
; DEV void store_tile_f32_add(const f32x4 (&acc)[8][4], const float* xres, float* out, int m0, int n0, unsigned char* smem) {
;   const int tid = TID(), lane = tid & 63, wid = tid >> 6;
;   const int wr = wid >> 1, wc = wid & 1, fr = lane & 15, fq = lane >> 4;
;   float* st = (float*)(smem + wid * 8704);
;   const int chunk = lane & 15;
; #pragma unroll
;   for (int mq = 0; mq < 4; ++mq) {
; #pragma unroll
;     for (int mh = 0; mh < 2; ++mh)
; #pragma unroll
;       for (int ni = 0; ni < 4; ++ni)
; #pragma unroll
;         for (int j = 0; j < 4; ++j) st[(mh * 16 + fq * 4 + j) * 68 + ni * 16 + fr] = acc[mq * 2 + mh][ni][j];
; #pragma unroll
;     for (int itr = 0; itr < 8; ++itr) {
;       const int rl = (lane >> 4) + 4 * itr;
;       const f32x4 v = *(const f32x4*)(st + rl * 68 + chunk * 4);
;       const size_t idx = (size_t)(m0 + wr * 128 + mq * 32 + rl) * 2048 + n0 + wc * 64 + chunk * 4;
;       const f32x4 x = *(const f32x4*)(xres + idx);
;       *(f32x4*)(out + idx) = x + v;
;     }
;   }
; }
	v_mfma_f32_16x16x32_bf16 v[148:151], v[136:139], v[116:119], v[148:151]
	v_mfma_f32_16x16x32_bf16 v[144:147], v[136:139], v[120:123], v[144:147]
	v_mfma_f32_16x16x32_bf16 v[124:127], v[136:139], v[128:131], v[124:127]
	v_mfma_f32_16x16x32_bf16 v[112:115], v[136:139], v[132:135], v[112:115]
	s_waitcnt lgkmcnt(2)
	v_mfma_f32_16x16x32_bf16 v[108:111], v[140:143], v[116:119], v[108:111]
	v_mfma_f32_16x16x32_bf16 v[104:107], v[140:143], v[120:123], v[104:107]
	v_mfma_f32_16x16x32_bf16 v[136:139], v[140:143], v[128:131], v[100:103]
	v_mfma_f32_16x16x32_bf16 v[96:99], v[140:143], v[132:135], v[96:99]
	s_waitcnt lgkmcnt(1)
	v_mfma_f32_16x16x32_bf16 v[92:95], v[152:155], v[116:119], v[92:95]
	v_mfma_f32_16x16x32_bf16 v[88:91], v[152:155], v[120:123], v[88:91]
	v_mfma_f32_16x16x32_bf16 v[84:87], v[152:155], v[128:131], v[84:87]
	v_mfma_f32_16x16x32_bf16 v[80:83], v[152:155], v[132:135], v[80:83]
	s_waitcnt lgkmcnt(0)
	v_mfma_f32_16x16x32_bf16 v[76:79], v[162:165], v[116:119], v[76:79]
	v_mfma_f32_16x16x32_bf16 v[72:75], v[162:165], v[120:123], v[72:75]
	v_mfma_f32_16x16x32_bf16 v[68:71], v[162:165], v[128:131], v[68:71]
	v_mfma_f32_16x16x32_bf16 v[64:67], v[162:165], v[132:135], v[64:67]
	ds_read_b128 v[100:103], v156 offset:28672
	ds_read_b128 v[140:143], v156 offset:29696
	ds_read_b128 v[152:155], v156 offset:30720
	ds_read_b128 v[162:165], v156 offset:31744
	s_waitcnt lgkmcnt(0)
	s_barrier
	v_mfma_f32_16x16x32_bf16 v[60:63], v[100:103], v[116:119], v[60:63]
	v_mfma_f32_16x16x32_bf16 v[56:59], v[100:103], v[120:123], v[56:59]
	v_mfma_f32_16x16x32_bf16 v[52:55], v[100:103], v[128:131], v[52:55]
	v_mfma_f32_16x16x32_bf16 v[48:51], v[100:103], v[132:135], v[48:51]
	v_mov_b32_e32 v102, v178
	s_nop 0
	v_lshrrev_b32_e32 v101, 6, v102
	v_and_b32_e32 v103, 15, v102
	v_mfma_f32_16x16x32_bf16 v[44:47], v[140:143], v[116:119], v[44:47]
	v_mul_lo_u32 v101, v101, s5
	v_bfe_u32 v100, v102, 4, 2
	v_mfma_f32_16x16x32_bf16 v[28:31], v[152:155], v[116:119], v[28:31]
	v_mfma_f32_16x16x32_bf16 v[12:15], v[162:165], v[116:119], v[12:15]
	v_lshlrev_b32_e32 v116, 2, v103
	v_or_b32_e32 v117, v101, v116
	v_and_b32_e32 v101, 0xffffff80, v102
	v_add_u32_e32 v101, s4, v101
	s_movk_i32 s4, 0x440
	v_mad_u32_u24 v118, v103, 12, v117
	v_and_or_b32 v116, v102, 64, v116
	v_mad_u32_u24 v103, v100, s4, v117
	v_readlane_b32 s4, v251, 7
	ds_write_b32 v103, v148
	ds_write_b32 v103, v149 offset:272
	ds_write_b32 v103, v150 offset:544
	ds_write_b32 v103, v151 offset:816
	ds_write_b32 v103, v144 offset:64
	ds_write_b32 v103, v145 offset:336
	ds_write_b32 v103, v146 offset:608
	ds_write_b32 v103, v147 offset:880
	ds_write_b32 v103, v124 offset:128
	ds_write_b32 v103, v125 offset:400
	ds_write_b32 v103, v126 offset:672
	ds_write_b32 v103, v127 offset:944
	ds_write_b32 v103, v112 offset:192
	ds_write_b32 v103, v113 offset:464
	ds_write_b32 v103, v114 offset:736
	ds_write_b32 v103, v115 offset:1008
	ds_write_b32 v103, v108 offset:4352
	ds_write_b32 v103, v109 offset:4624
	ds_write_b32 v103, v110 offset:4896
	ds_write_b32 v103, v111 offset:5168
	ds_write_b32 v103, v104 offset:4416
	ds_write_b32 v103, v105 offset:4688
	ds_write_b32 v103, v106 offset:4960
	ds_write_b32 v103, v107 offset:5232
	ds_write_b32 v103, v136 offset:4480
	ds_write_b32 v103, v137 offset:4752
	ds_write_b32 v103, v138 offset:5024
	ds_write_b32 v103, v139 offset:5296
	ds_write_b32 v103, v96 offset:4544
	ds_write_b32 v103, v97 offset:4816
	ds_write_b32 v103, v98 offset:5088
	ds_write_b32 v103, v99 offset:5360
	v_or_b32_e32 v98, v101, v100
	v_lshlrev_b32_e32 v156, 2, v116
	v_readlane_b32 s6, v251, 9
	v_readlane_b32 s7, v251, 10
	v_ashrrev_i32_e32 v99, 31, v98
	v_lshlrev_b64 v[98:99], 13, v[98:99]
	v_lshl_add_u64 v[96:97], s[6:7], 0, v[156:157]
	v_lshl_add_u64 v[96:97], s[2:3], 2, v[96:97]
	v_lshl_add_u64 v[98:99], v[96:97], 0, v[98:99]
	global_load_dwordx4 v[108:111], v[98:99], off
	v_mad_u32_u24 v102, v100, s8, v118
	ds_read_b128 v[104:107], v102
	v_mfma_f32_16x16x32_bf16 v[32:35], v[140:143], v[132:135], v[32:35]
	v_readlane_b32 s5, v251, 8
	s_waitcnt vmcnt(0) lgkmcnt(0)
	v_pk_add_f32 v[106:107], v[106:107], v[110:111]
	v_pk_add_f32 v[104:105], v[104:105], v[108:109]
	global_store_dwordx4 v[98:99], v[104:107], off
	v_or_b32_e32 v99, 4, v100
	v_or_b32_e32 v108, v99, v101
	v_ashrrev_i32_e32 v109, 31, v108
	v_lshlrev_b64 v[108:109], 13, v[108:109]
	v_lshl_add_u64 v[112:113], v[96:97], 0, v[108:109]
	global_load_dwordx4 v[108:111], v[112:113], off
	v_mad_u32_u24 v98, v99, s8, v118
	ds_read_b128 v[104:107], v98
	v_mfma_f32_16x16x32_bf16 v[40:43], v[140:143], v[120:123], v[40:43]
	s_waitcnt vmcnt(0) lgkmcnt(0)
	v_pk_add_f32 v[106:107], v[106:107], v[110:111]
	v_pk_add_f32 v[104:105], v[104:105], v[108:109]
	global_store_dwordx4 v[112:113], v[104:107], off
	ds_read_b128 v[106:109], v98 offset:1088
	v_mfma_f32_16x16x32_bf16 v[36:39], v[140:143], v[128:131], v[36:39]
	v_or_b32_e32 v104, 8, v100
	v_or_b32_e32 v110, v104, v101
	v_ashrrev_i32_e32 v111, 31, v110
	v_lshlrev_b64 v[110:111], 13, v[110:111]
	v_lshl_add_u64 v[114:115], v[96:97], 0, v[110:111]
	global_load_dwordx4 v[110:113], v[114:115], off
	v_or_b32_e32 v105, 12, v100
	v_mfma_f32_16x16x32_bf16 v[8:11], v[162:165], v[120:123], v[8:11]
	s_waitcnt vmcnt(0) lgkmcnt(0)
	v_pk_add_f32 v[106:107], v[106:107], v[110:111]
	v_or_b32_e32 v110, v105, v101
	v_ashrrev_i32_e32 v111, 31, v110
	v_pk_add_f32 v[108:109], v[108:109], v[112:113]
	v_lshlrev_b64 v[110:111], 13, v[110:111]
	global_store_dwordx4 v[114:115], v[106:109], off
	v_lshl_add_u64 v[114:115], v[96:97], 0, v[110:111]
	global_load_dwordx4 v[110:113], v[114:115], off
	ds_read_b128 v[106:109], v98 offset:2176
	v_mfma_f32_16x16x32_bf16 v[24:27], v[152:155], v[120:123], v[24:27]
	s_waitcnt vmcnt(0) lgkmcnt(0)
; DEV int TID() { int t = threadIdx.x; asm volatile("" : "+v"(t)); return t; }
; DEV void store_tile_f32_add(const f32x4 (&acc)[8][4], const float* xres, float* out, int m0, int n0, unsigned char* smem) {
;   const int tid = TID(), lane = tid & 63, wid = tid >> 6;
;   const int wr = wid >> 1, wc = wid & 1, fr = lane & 15, fq = lane >> 4;
;   float* st = (float*)(smem + wid * 8704);
;   const int chunk = lane & 15;
; #pragma unroll
;   for (int mq = 0; mq < 4; ++mq) {
; #pragma unroll
;     for (int mh = 0; mh < 2; ++mh)
; #pragma unroll
;       for (int ni = 0; ni < 4; ++ni)
; #pragma unroll
;         for (int j = 0; j < 4; ++j) st[(mh * 16 + fq * 4 + j) * 68 + ni * 16 + fr] = acc[mq * 2 + mh][ni][j];
; #pragma unroll
;     for (int itr = 0; itr < 8; ++itr) {
;       const int rl = (lane >> 4) + 4 * itr;
;       const f32x4 v = *(const f32x4*)(st + rl * 68 + chunk * 4);
;       const size_t idx = (size_t)(m0 + wr * 128 + mq * 32 + rl) * 2048 + n0 + wc * 64 + chunk * 4;
;       const f32x4 x = *(const f32x4*)(xres + idx);
;       *(f32x4*)(out + idx) = x + v;
;     }
;   }
; }
	v_pk_add_f32 v[108:109], v[108:109], v[112:113]
	v_pk_add_f32 v[106:107], v[106:107], v[110:111]
	global_store_dwordx4 v[114:115], v[106:109], off
	ds_read_b128 v[108:111], v98 offset:3264
	v_mfma_f32_16x16x32_bf16 v[20:23], v[152:155], v[128:131], v[20:23]
	v_or_b32_e32 v106, 16, v100
	v_or_b32_e32 v112, v106, v101
	v_ashrrev_i32_e32 v113, 31, v112
	v_lshlrev_b64 v[112:113], 13, v[112:113]
	v_lshl_add_u64 v[116:117], v[96:97], 0, v[112:113]
	global_load_dwordx4 v[112:115], v[116:117], off
	v_or_b32_e32 v107, 20, v100
	v_mfma_f32_16x16x32_bf16 v[16:19], v[152:155], v[132:135], v[16:19]
	s_waitcnt vmcnt(0) lgkmcnt(0)
	v_pk_add_f32 v[108:109], v[108:109], v[112:113]
	v_or_b32_e32 v112, v107, v101
	v_ashrrev_i32_e32 v113, 31, v112
	v_pk_add_f32 v[110:111], v[110:111], v[114:115]
	v_lshlrev_b64 v[112:113], 13, v[112:113]
	global_store_dwordx4 v[116:117], v[108:111], off
	v_lshl_add_u64 v[116:117], v[96:97], 0, v[112:113]
	global_load_dwordx4 v[112:115], v[116:117], off
	ds_read_b128 v[108:111], v98 offset:4352
	v_mfma_f32_16x16x32_bf16 v[4:7], v[162:165], v[128:131], v[4:7]
	s_waitcnt vmcnt(0) lgkmcnt(0)
	v_pk_add_f32 v[110:111], v[110:111], v[114:115]
	v_pk_add_f32 v[108:109], v[108:109], v[112:113]
	global_store_dwordx4 v[116:117], v[108:111], off
	ds_read_b128 v[110:113], v98 offset:5440
	v_mfma_f32_16x16x32_bf16 v[0:3], v[162:165], v[132:135], v[0:3]
	v_or_b32_e32 v108, 24, v100
	v_or_b32_e32 v114, v108, v101
	v_ashrrev_i32_e32 v115, 31, v114
	v_lshlrev_b64 v[114:115], 13, v[114:115]
	v_lshl_add_u64 v[118:119], v[96:97], 0, v[114:115]
	global_load_dwordx4 v[114:117], v[118:119], off
	v_or_b32_e32 v109, 28, v100
	s_waitcnt vmcnt(0) lgkmcnt(0)
	v_pk_add_f32 v[110:111], v[110:111], v[114:115]
	v_or_b32_e32 v114, v109, v101
	v_ashrrev_i32_e32 v115, 31, v114
	v_pk_add_f32 v[112:113], v[112:113], v[116:117]
	v_lshlrev_b64 v[114:115], 13, v[114:115]
	global_store_dwordx4 v[118:119], v[110:113], off
	v_lshl_add_u64 v[118:119], v[96:97], 0, v[114:115]
	global_load_dwordx4 v[114:117], v[118:119], off
	ds_read_b128 v[110:113], v98 offset:6528
	s_waitcnt vmcnt(0) lgkmcnt(0)
	v_pk_add_f32 v[112:113], v[112:113], v[116:117]
	v_pk_add_f32 v[110:111], v[110:111], v[114:115]
	global_store_dwordx4 v[118:119], v[110:113], off
	ds_write_b32 v103, v92
	ds_write_b32 v103, v93 offset:272
	ds_write_b32 v103, v94 offset:544
	ds_write_b32 v103, v95 offset:816
	ds_write_b32 v103, v88 offset:64
	ds_write_b32 v103, v89 offset:336
	ds_write_b32 v103, v90 offset:608
	ds_write_b32 v103, v91 offset:880
	ds_write_b32 v103, v84 offset:128
	ds_write_b32 v103, v85 offset:400
	ds_write_b32 v103, v86 offset:672
	ds_write_b32 v103, v87 offset:944
	ds_write_b32 v103, v80 offset:192
	ds_write_b32 v103, v81 offset:464
	ds_write_b32 v103, v82 offset:736
	ds_write_b32 v103, v83 offset:1008
	ds_write_b32 v103, v76 offset:4352
	ds_write_b32 v103, v77 offset:4624
	ds_write_b32 v103, v78 offset:4896
	ds_write_b32 v103, v79 offset:5168
	ds_write_b32 v103, v72 offset:4416
	ds_write_b32 v103, v73 offset:4688
	ds_write_b32 v103, v74 offset:4960
	ds_write_b32 v103, v75 offset:5232
	ds_write_b32 v103, v68 offset:4480
	ds_write_b32 v103, v69 offset:4752
	ds_write_b32 v103, v70 offset:5024
	ds_write_b32 v103, v71 offset:5296
	ds_write_b32 v103, v64 offset:4544
	ds_write_b32 v103, v65 offset:4816
	ds_write_b32 v103, v66 offset:5088
	ds_write_b32 v103, v67 offset:5360
	v_or_b32_e32 v64, 32, v101
	v_or_b32_e32 v70, v64, v100
	v_ashrrev_i32_e32 v71, 31, v70
	v_lshlrev_b64 v[70:71], 13, v[70:71]
	v_lshl_add_u64 v[74:75], v[96:97], 0, v[70:71]
	global_load_dwordx4 v[70:73], v[74:75], off
	ds_read_b128 v[66:69], v102
	s_waitcnt vmcnt(0) lgkmcnt(0)
	v_pk_add_f32 v[66:67], v[66:67], v[70:71]
	v_or_b32_e32 v70, v64, v99
	v_ashrrev_i32_e32 v71, 31, v70
	v_pk_add_f32 v[68:69], v[68:69], v[72:73]
	v_lshlrev_b64 v[70:71], 13, v[70:71]
	global_store_dwordx4 v[74:75], v[66:69], off
	v_lshl_add_u64 v[74:75], v[96:97], 0, v[70:71]
	global_load_dwordx4 v[70:73], v[74:75], off
	ds_read_b128 v[66:69], v98
	s_waitcnt vmcnt(0) lgkmcnt(0)
	v_pk_add_f32 v[66:67], v[66:67], v[70:71]
	v_or_b32_e32 v70, v64, v104
	v_ashrrev_i32_e32 v71, 31, v70
	v_pk_add_f32 v[68:69], v[68:69], v[72:73]
	v_lshlrev_b64 v[70:71], 13, v[70:71]
	global_store_dwordx4 v[74:75], v[66:69], off
	v_lshl_add_u64 v[74:75], v[96:97], 0, v[70:71]
	global_load_dwordx4 v[70:73], v[74:75], off
	ds_read_b128 v[66:69], v98 offset:1088
	s_waitcnt vmcnt(0) lgkmcnt(0)
	v_pk_add_f32 v[66:67], v[66:67], v[70:71]
	v_or_b32_e32 v70, v64, v105
	v_ashrrev_i32_e32 v71, 31, v70
	v_pk_add_f32 v[68:69], v[68:69], v[72:73]
	v_lshlrev_b64 v[70:71], 13, v[70:71]
	global_store_dwordx4 v[74:75], v[66:69], off
	v_lshl_add_u64 v[74:75], v[96:97], 0, v[70:71]
	global_load_dwordx4 v[70:73], v[74:75], off
	ds_read_b128 v[66:69], v98 offset:2176
	s_waitcnt vmcnt(0) lgkmcnt(0)
	v_pk_add_f32 v[66:67], v[66:67], v[70:71]
	v_or_b32_e32 v70, v64, v106
	v_ashrrev_i32_e32 v71, 31, v70
	v_pk_add_f32 v[68:69], v[68:69], v[72:73]
	v_lshlrev_b64 v[70:71], 13, v[70:71]
	global_store_dwordx4 v[74:75], v[66:69], off
	v_lshl_add_u64 v[74:75], v[96:97], 0, v[70:71]
	global_load_dwordx4 v[70:73], v[74:75], off
	ds_read_b128 v[66:69], v98 offset:3264
	s_waitcnt vmcnt(0) lgkmcnt(0)
	v_pk_add_f32 v[66:67], v[66:67], v[70:71]
	v_or_b32_e32 v70, v64, v107
	v_ashrrev_i32_e32 v71, 31, v70
	v_pk_add_f32 v[68:69], v[68:69], v[72:73]
	v_lshlrev_b64 v[70:71], 13, v[70:71]
	global_store_dwordx4 v[74:75], v[66:69], off
	v_lshl_add_u64 v[74:75], v[96:97], 0, v[70:71]
	global_load_dwordx4 v[70:73], v[74:75], off
	ds_read_b128 v[66:69], v98 offset:4352
	s_waitcnt vmcnt(0) lgkmcnt(0)
; DEV int TID() { int t = threadIdx.x; asm volatile("" : "+v"(t)); return t; }
; DEV void store_tile_f32_add(const f32x4 (&acc)[8][4], const float* xres, float* out, int m0, int n0, unsigned char* smem) {
;   const int tid = TID(), lane = tid & 63, wid = tid >> 6;
;   const int wr = wid >> 1, wc = wid & 1, fr = lane & 15, fq = lane >> 4;
;   float* st = (float*)(smem + wid * 8704);
;   const int chunk = lane & 15;
; #pragma unroll
;   for (int mq = 0; mq < 4; ++mq) {
; #pragma unroll
;     for (int mh = 0; mh < 2; ++mh)
; #pragma unroll
;       for (int ni = 0; ni < 4; ++ni)
; #pragma unroll
;         for (int j = 0; j < 4; ++j) st[(mh * 16 + fq * 4 + j) * 68 + ni * 16 + fr] = acc[mq * 2 + mh][ni][j];
; #pragma unroll
;     for (int itr = 0; itr < 8; ++itr) {
;       const int rl = (lane >> 4) + 4 * itr;
;       const f32x4 v = *(const f32x4*)(st + rl * 68 + chunk * 4);
;       const size_t idx = (size_t)(m0 + wr * 128 + mq * 32 + rl) * 2048 + n0 + wc * 64 + chunk * 4;
;       const f32x4 x = *(const f32x4*)(xres + idx);
;       *(f32x4*)(out + idx) = x + v;
;     }
;   }
; }
	v_pk_add_f32 v[66:67], v[66:67], v[70:71]
	v_or_b32_e32 v70, v64, v108
	v_ashrrev_i32_e32 v71, 31, v70
	v_pk_add_f32 v[68:69], v[68:69], v[72:73]
	v_lshlrev_b64 v[70:71], 13, v[70:71]
	global_store_dwordx4 v[74:75], v[66:69], off
	v_lshl_add_u64 v[74:75], v[96:97], 0, v[70:71]
	global_load_dwordx4 v[70:73], v[74:75], off
	ds_read_b128 v[66:69], v98 offset:5440
	v_or_b32_e32 v64, v64, v109
	v_ashrrev_i32_e32 v65, 31, v64
	v_lshlrev_b64 v[64:65], 13, v[64:65]
	v_lshl_add_u64 v[64:65], v[96:97], 0, v[64:65]
	s_waitcnt vmcnt(0) lgkmcnt(0)
	v_pk_add_f32 v[68:69], v[68:69], v[72:73]
	v_pk_add_f32 v[66:67], v[66:67], v[70:71]
	global_load_dwordx4 v[70:73], v[64:65], off
	s_nop 0
	global_store_dwordx4 v[74:75], v[66:69], off
	ds_read_b128 v[66:69], v98 offset:6528
	s_waitcnt vmcnt(1) lgkmcnt(0)
	v_pk_add_f32 v[68:69], v[68:69], v[72:73]
	v_pk_add_f32 v[66:67], v[66:67], v[70:71]
	global_store_dwordx4 v[64:65], v[66:69], off
	ds_write_b32 v103, v60
	ds_write_b32 v103, v61 offset:272
	ds_write_b32 v103, v62 offset:544
	ds_write_b32 v103, v63 offset:816
	ds_write_b32 v103, v56 offset:64
	ds_write_b32 v103, v57 offset:336
	ds_write_b32 v103, v58 offset:608
	ds_write_b32 v103, v59 offset:880
	ds_write_b32 v103, v52 offset:128
	ds_write_b32 v103, v53 offset:400
	ds_write_b32 v103, v54 offset:672
	ds_write_b32 v103, v55 offset:944
	ds_write_b32 v103, v48 offset:192
	ds_write_b32 v103, v49 offset:464
	ds_write_b32 v103, v50 offset:736
	ds_write_b32 v103, v51 offset:1008
	ds_write_b32 v103, v44 offset:4352
	ds_write_b32 v103, v45 offset:4624
	ds_write_b32 v103, v46 offset:4896
	ds_write_b32 v103, v47 offset:5168
	ds_write_b32 v103, v40 offset:4416
	ds_write_b32 v103, v41 offset:4688
	ds_write_b32 v103, v42 offset:4960
	ds_write_b32 v103, v43 offset:5232
	ds_write_b32 v103, v36 offset:4480
	ds_write_b32 v103, v37 offset:4752
	ds_write_b32 v103, v38 offset:5024
	ds_write_b32 v103, v39 offset:5296
	ds_write_b32 v103, v32 offset:4544
	ds_write_b32 v103, v33 offset:4816
	ds_write_b32 v103, v34 offset:5088
	ds_write_b32 v103, v35 offset:5360
	v_or_b32_e32 v32, 64, v101
	v_or_b32_e32 v38, v32, v100
	v_ashrrev_i32_e32 v39, 31, v38
	v_lshlrev_b64 v[38:39], 13, v[38:39]
	v_lshl_add_u64 v[42:43], v[96:97], 0, v[38:39]
	global_load_dwordx4 v[38:41], v[42:43], off
	ds_read_b128 v[34:37], v102
	s_waitcnt vmcnt(0) lgkmcnt(0)
	v_pk_add_f32 v[34:35], v[34:35], v[38:39]
	v_or_b32_e32 v38, v32, v99
	v_ashrrev_i32_e32 v39, 31, v38
	v_pk_add_f32 v[36:37], v[36:37], v[40:41]
	v_lshlrev_b64 v[38:39], 13, v[38:39]
	global_store_dwordx4 v[42:43], v[34:37], off
	v_lshl_add_u64 v[42:43], v[96:97], 0, v[38:39]
	global_load_dwordx4 v[38:41], v[42:43], off
	ds_read_b128 v[34:37], v98
	s_waitcnt vmcnt(0) lgkmcnt(0)
	v_pk_add_f32 v[34:35], v[34:35], v[38:39]
	v_or_b32_e32 v38, v32, v104
	v_ashrrev_i32_e32 v39, 31, v38
	v_pk_add_f32 v[36:37], v[36:37], v[40:41]
	v_lshlrev_b64 v[38:39], 13, v[38:39]
	global_store_dwordx4 v[42:43], v[34:37], off
	v_lshl_add_u64 v[42:43], v[96:97], 0, v[38:39]
	global_load_dwordx4 v[38:41], v[42:43], off
	ds_read_b128 v[34:37], v98 offset:1088
	s_waitcnt vmcnt(0) lgkmcnt(0)
	v_pk_add_f32 v[34:35], v[34:35], v[38:39]
	v_or_b32_e32 v38, v32, v105
	v_ashrrev_i32_e32 v39, 31, v38
	v_pk_add_f32 v[36:37], v[36:37], v[40:41]
	v_lshlrev_b64 v[38:39], 13, v[38:39]
	global_store_dwordx4 v[42:43], v[34:37], off
	v_lshl_add_u64 v[42:43], v[96:97], 0, v[38:39]
	global_load_dwordx4 v[38:41], v[42:43], off
	ds_read_b128 v[34:37], v98 offset:2176
	s_waitcnt vmcnt(0) lgkmcnt(0)
	v_pk_add_f32 v[34:35], v[34:35], v[38:39]
	v_or_b32_e32 v38, v32, v106
	v_ashrrev_i32_e32 v39, 31, v38
	v_pk_add_f32 v[36:37], v[36:37], v[40:41]
	v_lshlrev_b64 v[38:39], 13, v[38:39]
	global_store_dwordx4 v[42:43], v[34:37], off
	v_lshl_add_u64 v[42:43], v[96:97], 0, v[38:39]
	global_load_dwordx4 v[38:41], v[42:43], off
	ds_read_b128 v[34:37], v98 offset:3264
	s_waitcnt vmcnt(0) lgkmcnt(0)
	v_pk_add_f32 v[34:35], v[34:35], v[38:39]
	v_or_b32_e32 v38, v32, v107
	v_ashrrev_i32_e32 v39, 31, v38
	v_pk_add_f32 v[36:37], v[36:37], v[40:41]
	v_lshlrev_b64 v[38:39], 13, v[38:39]
	global_store_dwordx4 v[42:43], v[34:37], off
	v_lshl_add_u64 v[42:43], v[96:97], 0, v[38:39]
	global_load_dwordx4 v[38:41], v[42:43], off
	ds_read_b128 v[34:37], v98 offset:4352
	s_waitcnt vmcnt(0) lgkmcnt(0)
	v_pk_add_f32 v[34:35], v[34:35], v[38:39]
	v_or_b32_e32 v38, v32, v108
	v_ashrrev_i32_e32 v39, 31, v38
	v_pk_add_f32 v[36:37], v[36:37], v[40:41]
	v_lshlrev_b64 v[38:39], 13, v[38:39]
	global_store_dwordx4 v[42:43], v[34:37], off
	v_lshl_add_u64 v[42:43], v[96:97], 0, v[38:39]
	global_load_dwordx4 v[38:41], v[42:43], off
	ds_read_b128 v[34:37], v98 offset:5440
	v_or_b32_e32 v32, v32, v109
	v_ashrrev_i32_e32 v33, 31, v32
	v_lshlrev_b64 v[32:33], 13, v[32:33]
	v_lshl_add_u64 v[32:33], v[96:97], 0, v[32:33]
	s_waitcnt vmcnt(0) lgkmcnt(0)
; DEV int TID() { int t = threadIdx.x; asm volatile("" : "+v"(t)); return t; }
; DEV void store_tile_f32_add(const f32x4 (&acc)[8][4], const float* xres, float* out, int m0, int n0, unsigned char* smem) {
;   const int tid = TID(), lane = tid & 63, wid = tid >> 6;
;   const int wr = wid >> 1, wc = wid & 1, fr = lane & 15, fq = lane >> 4;
;   float* st = (float*)(smem + wid * 8704);
;   const int chunk = lane & 15;
; #pragma unroll
;   for (int mq = 0; mq < 4; ++mq) {
; #pragma unroll
;     for (int mh = 0; mh < 2; ++mh)
; #pragma unroll
;       for (int ni = 0; ni < 4; ++ni)
; #pragma unroll
;         for (int j = 0; j < 4; ++j) st[(mh * 16 + fq * 4 + j) * 68 + ni * 16 + fr] = acc[mq * 2 + mh][ni][j];
; #pragma unroll
;     for (int itr = 0; itr < 8; ++itr) {
;       const int rl = (lane >> 4) + 4 * itr;
;       const f32x4 v = *(const f32x4*)(st + rl * 68 + chunk * 4);
;       const size_t idx = (size_t)(m0 + wr * 128 + mq * 32 + rl) * 2048 + n0 + wc * 64 + chunk * 4;
;       const f32x4 x = *(const f32x4*)(xres + idx);
;       *(f32x4*)(out + idx) = x + v;
;     }
;   }
; }
	v_pk_add_f32 v[36:37], v[36:37], v[40:41]
	v_pk_add_f32 v[34:35], v[34:35], v[38:39]
	global_load_dwordx4 v[38:41], v[32:33], off
	s_nop 0
	global_store_dwordx4 v[42:43], v[34:37], off
	ds_read_b128 v[34:37], v98 offset:6528
	s_waitcnt vmcnt(1) lgkmcnt(0)
	v_pk_add_f32 v[36:37], v[36:37], v[40:41]
	v_pk_add_f32 v[34:35], v[34:35], v[38:39]
	global_store_dwordx4 v[32:33], v[34:37], off
	ds_write_b32 v103, v28
	ds_write_b32 v103, v29 offset:272
	ds_write_b32 v103, v30 offset:544
	ds_write_b32 v103, v31 offset:816
	ds_write_b32 v103, v24 offset:64
	ds_write_b32 v103, v25 offset:336
	ds_write_b32 v103, v26 offset:608
	ds_write_b32 v103, v27 offset:880
	ds_write_b32 v103, v20 offset:128
	ds_write_b32 v103, v21 offset:400
	ds_write_b32 v103, v22 offset:672
	ds_write_b32 v103, v23 offset:944
	ds_write_b32 v103, v16 offset:192
	ds_write_b32 v103, v17 offset:464
	ds_write_b32 v103, v18 offset:736
	ds_write_b32 v103, v19 offset:1008
	ds_write_b32 v103, v12 offset:4352
	ds_write_b32 v103, v13 offset:4624
	ds_write_b32 v103, v14 offset:4896
	ds_write_b32 v103, v15 offset:5168
	ds_write_b32 v103, v8 offset:4416
	ds_write_b32 v103, v9 offset:4688
	ds_write_b32 v103, v10 offset:4960
	ds_write_b32 v103, v11 offset:5232
	ds_write_b32 v103, v4 offset:4480
	ds_write_b32 v103, v5 offset:4752
	ds_write_b32 v103, v6 offset:5024
	ds_write_b32 v103, v7 offset:5296
	ds_write_b32 v103, v0 offset:4544
	ds_write_b32 v103, v1 offset:4816
	ds_write_b32 v103, v2 offset:5088
	ds_write_b32 v103, v3 offset:5360
	v_or_b32_e32 v10, 0x60, v101
	v_or_b32_e32 v4, v10, v100
	v_ashrrev_i32_e32 v5, 31, v4
	v_lshlrev_b64 v[4:5], 13, v[4:5]
	v_lshl_add_u64 v[8:9], v[96:97], 0, v[4:5]
	global_load_dwordx4 v[4:7], v[8:9], off
	ds_read_b128 v[0:3], v102
	s_waitcnt vmcnt(0) lgkmcnt(0)
	v_pk_add_f32 v[0:1], v[0:1], v[4:5]
	v_or_b32_e32 v4, v10, v99
	v_ashrrev_i32_e32 v5, 31, v4
	v_pk_add_f32 v[2:3], v[2:3], v[6:7]
	v_lshlrev_b64 v[4:5], 13, v[4:5]
	global_store_dwordx4 v[8:9], v[0:3], off
	v_lshl_add_u64 v[8:9], v[96:97], 0, v[4:5]
	global_load_dwordx4 v[4:7], v[8:9], off
	ds_read_b128 v[0:3], v98
	s_waitcnt vmcnt(0) lgkmcnt(0)
	v_pk_add_f32 v[0:1], v[0:1], v[4:5]
	v_or_b32_e32 v4, v10, v104
	v_ashrrev_i32_e32 v5, 31, v4
	v_pk_add_f32 v[2:3], v[2:3], v[6:7]
	v_lshlrev_b64 v[4:5], 13, v[4:5]
	global_store_dwordx4 v[8:9], v[0:3], off
	v_lshl_add_u64 v[8:9], v[96:97], 0, v[4:5]
	global_load_dwordx4 v[4:7], v[8:9], off
	ds_read_b128 v[0:3], v98 offset:1088
	s_waitcnt vmcnt(0) lgkmcnt(0)
	v_pk_add_f32 v[0:1], v[0:1], v[4:5]
	v_or_b32_e32 v4, v10, v105
	v_ashrrev_i32_e32 v5, 31, v4
	v_pk_add_f32 v[2:3], v[2:3], v[6:7]
	v_lshlrev_b64 v[4:5], 13, v[4:5]
	global_store_dwordx4 v[8:9], v[0:3], off
	v_lshl_add_u64 v[8:9], v[96:97], 0, v[4:5]
	global_load_dwordx4 v[4:7], v[8:9], off
	ds_read_b128 v[0:3], v98 offset:2176
	s_waitcnt vmcnt(0) lgkmcnt(0)
	v_pk_add_f32 v[0:1], v[0:1], v[4:5]
	v_or_b32_e32 v4, v10, v106
	v_ashrrev_i32_e32 v5, 31, v4
	v_pk_add_f32 v[2:3], v[2:3], v[6:7]
	v_lshlrev_b64 v[4:5], 13, v[4:5]
	global_store_dwordx4 v[8:9], v[0:3], off
	v_lshl_add_u64 v[8:9], v[96:97], 0, v[4:5]
	global_load_dwordx4 v[4:7], v[8:9], off
	ds_read_b128 v[0:3], v98 offset:3264
	s_waitcnt vmcnt(0) lgkmcnt(0)
	v_pk_add_f32 v[0:1], v[0:1], v[4:5]
	v_or_b32_e32 v4, v10, v107
	v_ashrrev_i32_e32 v5, 31, v4
	v_pk_add_f32 v[2:3], v[2:3], v[6:7]
	v_lshlrev_b64 v[4:5], 13, v[4:5]
	global_store_dwordx4 v[8:9], v[0:3], off
	v_lshl_add_u64 v[8:9], v[96:97], 0, v[4:5]
	global_load_dwordx4 v[4:7], v[8:9], off
	ds_read_b128 v[0:3], v98 offset:4352
	s_waitcnt vmcnt(0) lgkmcnt(0)
	v_pk_add_f32 v[0:1], v[0:1], v[4:5]
	v_or_b32_e32 v4, v10, v108
	v_ashrrev_i32_e32 v5, 31, v4
	v_pk_add_f32 v[2:3], v[2:3], v[6:7]
	v_lshlrev_b64 v[4:5], 13, v[4:5]
	global_store_dwordx4 v[8:9], v[0:3], off
	v_lshl_add_u64 v[8:9], v[96:97], 0, v[4:5]
	global_load_dwordx4 v[4:7], v[8:9], off
	ds_read_b128 v[0:3], v98 offset:5440
	s_waitcnt vmcnt(0) lgkmcnt(0)
	v_pk_add_f32 v[0:1], v[0:1], v[4:5]
	v_or_b32_e32 v4, v10, v109
	v_ashrrev_i32_e32 v5, 31, v4
	v_pk_add_f32 v[2:3], v[2:3], v[6:7]
	v_lshlrev_b64 v[4:5], 13, v[4:5]
	global_store_dwordx4 v[8:9], v[0:3], off
	v_lshl_add_u64 v[8:9], v[96:97], 0, v[4:5]
	global_load_dwordx4 v[4:7], v[8:9], off
	ds_read_b128 v[0:3], v98 offset:6528
	s_waitcnt vmcnt(0) lgkmcnt(0)
	v_pk_add_f32 v[2:3], v[2:3], v[6:7]
	v_pk_add_f32 v[0:1], v[0:1], v[4:5]
	global_store_dwordx4 v[8:9], v[0:3], off
	s_branch .LBB0_191

; DEV f32x4 mfma16(bf16x8 a, bf16x8 b, f32x4 c) { return __builtin_amdgcn_mfma_f32_16x16x32_bf16(a, b, c, 0, 0, 0); }
; DEV void gemm_tile(const u16* __restrict__ A, size_t lda, const u16* __restrict__ Bt, size_t ldb, int K,
;                    u16* sA, u16* sB, f32x4 (&acc)[8][4]) {
;     ...
;   for (int kt = 0; kt < nk; ++kt) {
;     const int st = kt & 1;
;     if (kt + 1 < nk) S_STORE(st ^ 1)
;     if (kt + 2 < nk) G_LOAD((kt + 2) << 5)
;     {
;       const u16* pa = sAr + st * 12288;
;       const u16* pb = sBr + st * 12288;
;       bf16x8 b[4];
; #pragma unroll
;       for (int ni = 0; ni < 4; ++ni) b[ni] = *(const bf16x8*)(pb + ni * 16 * 32);
; #pragma unroll
;       for (int mh = 0; mh < 2; ++mh) {
;         bf16x8 a[4];
; #pragma unroll
;         for (int mi = 0; mi < 4; ++mi) a[mi] = *(const bf16x8*)(pa + (mh * 64 + mi * 16) * 32);
; #pragma unroll
;         for (int mi = 0; mi < 4; ++mi)
; #pragma unroll
;           for (int ni = 0; ni < 4; ++ni) acc[mh * 4 + mi][ni] = mfma16(a[mi], b[ni], acc[mh * 4 + mi][ni]);
;       }
;     }
;     __syncthreads();
;   }
.LBB0_226:
	v_add_u32_e32 v229, s8, v163
	v_add_u32_e32 v228, s8, v162
	ds_read_b128 v[120:123], v229 offset:16384
	ds_read_b128 v[166:169], v228
	ds_read_b128 v[128:131], v229 offset:17408
	ds_read_b128 v[140:143], v229 offset:18432
	ds_read_b128 v[124:127], v229 offset:19456
	ds_read_b128 v[152:155], v228 offset:1024
	ds_read_b128 v[170:173], v228 offset:2048
	ds_read_b128 v[132:135], v228 offset:3072
	s_waitcnt lgkmcnt(6)
	v_mfma_f32_16x16x32_bf16 v[148:151], v[166:169], v[120:123], v[148:151]
	s_add_i32 m0, s9, 0x0
	s_waitcnt lgkmcnt(5)
	v_mfma_f32_16x16x32_bf16 v[144:147], v[166:169], v[128:131], v[144:147]
	global_load_lds_dwordx4 v[136:137], off
	v_lshl_add_u64 v[136:137], v[136:137], 0, 64
	global_load_dwordx4 v[244:247], v[136:137], off
	v_lshl_add_u64 v[136:137], v[136:137], 0, 64
	s_waitcnt lgkmcnt(4)
	v_mfma_f32_16x16x32_bf16 v[116:119], v[166:169], v[140:143], v[116:119]
	s_add_i32 m0, s9, 0x1000
	s_waitcnt lgkmcnt(3)
	v_mfma_f32_16x16x32_bf16 v[112:115], v[166:169], v[124:127], v[112:115]
	ds_read_b128 v[232:235], v228 offset:4096
	ds_read_b128 v[236:239], v228 offset:5120
	s_waitcnt lgkmcnt(4)
	v_mfma_f32_16x16x32_bf16 v[108:111], v[152:155], v[120:123], v[108:111]
	global_load_lds_dwordx4 v[138:139], off
	v_lshl_add_u64 v[138:139], v[138:139], 0, 64
	global_load_dwordx4 v[252:255], v[138:139], off
	v_lshl_add_u64 v[138:139], v[138:139], 0, 64
	v_mfma_f32_16x16x32_bf16 v[104:107], v[152:155], v[128:131], v[104:107]
	s_add_i32 m0, s9, 0x2000
	v_mfma_f32_16x16x32_bf16 v[100:103], v[152:155], v[140:143], v[100:103]
	global_load_lds_dwordx4 v[174:175], off
	v_lshl_add_u64 v[174:175], v[174:175], 0, 64
	global_load_dwordx4 v[208:211], v[174:175], off
	v_lshl_add_u64 v[174:175], v[174:175], 0, 64
	v_mfma_f32_16x16x32_bf16 v[96:99], v[152:155], v[124:127], v[96:99]
	s_add_i32 m0, s9, 0x3000
	s_waitcnt lgkmcnt(3)
	v_mfma_f32_16x16x32_bf16 v[92:95], v[170:173], v[120:123], v[92:95]
	global_load_lds_dwordx4 v[176:177], off
	v_lshl_add_u64 v[176:177], v[176:177], 0, 64
	global_load_dwordx4 v[212:215], v[176:177], off
	v_lshl_add_u64 v[176:177], v[176:177], 0, 64
	v_mfma_f32_16x16x32_bf16 v[88:91], v[170:173], v[128:131], v[88:91]
	s_add_i32 m0, s9, 0x4000
	v_mfma_f32_16x16x32_bf16 v[84:87], v[170:173], v[140:143], v[84:87]
	global_load_lds_dwordx4 v[186:187], off
	v_lshl_add_u64 v[186:187], v[186:187], 0, 64
	global_load_dwordx4 v[216:219], v[186:187], off
	v_lshl_add_u64 v[186:187], v[186:187], 0, 64
	v_mfma_f32_16x16x32_bf16 v[80:83], v[170:173], v[124:127], v[80:83]
	ds_read_b128 v[240:243], v228 offset:6144
	ds_read_b128 v[166:169], v228 offset:7168
	s_waitcnt lgkmcnt(4)
	v_mfma_f32_16x16x32_bf16 v[76:79], v[132:135], v[120:123], v[76:79]
	s_add_i32 m0, s9, 0x5000
	v_mfma_f32_16x16x32_bf16 v[72:75], v[132:135], v[128:131], v[72:75]
	global_load_lds_dwordx4 v[188:189], off
	v_lshl_add_u64 v[188:189], v[188:189], 0, 64
	global_load_dwordx4 v[220:223], v[188:189], off
	v_lshl_add_u64 v[188:189], v[188:189], 0, 64
	v_mfma_f32_16x16x32_bf16 v[68:71], v[132:135], v[140:143], v[68:71]
	s_add_i32 s9, s8, s5
	s_add_i32 s8, s8, 0x6000
	v_mfma_f32_16x16x32_bf16 v[64:67], v[132:135], v[124:127], v[64:67]
	s_cmp_eq_u32 s8, 0x12000
	s_cselect_b32 s8, 0, s8
	s_waitcnt lgkmcnt(3)
	v_mfma_f32_16x16x32_bf16 v[60:63], v[232:235], v[120:123], v[60:63]
	s_add_u32 s6, s6, 64
	s_addc_u32 s7, s7, 0
	s_cmpk_lg_i32 s6, 0xf80
	v_mfma_f32_16x16x32_bf16 v[56:59], v[232:235], v[128:131], v[56:59]
	v_mfma_f32_16x16x32_bf16 v[52:55], v[232:235], v[140:143], v[52:55]
	v_mfma_f32_16x16x32_bf16 v[48:51], v[232:235], v[124:127], v[48:51]
	s_waitcnt lgkmcnt(2)
	v_mfma_f32_16x16x32_bf16 v[44:47], v[236:239], v[120:123], v[44:47]
	v_mfma_f32_16x16x32_bf16 v[40:43], v[236:239], v[128:131], v[40:43]
	v_mfma_f32_16x16x32_bf16 v[36:39], v[236:239], v[140:143], v[36:39]
	v_mfma_f32_16x16x32_bf16 v[32:35], v[236:239], v[124:127], v[32:35]
	s_waitcnt lgkmcnt(1)
	v_mfma_f32_16x16x32_bf16 v[28:31], v[240:243], v[120:123], v[28:31]
	v_mfma_f32_16x16x32_bf16 v[24:27], v[240:243], v[128:131], v[24:27]
	v_mfma_f32_16x16x32_bf16 v[20:23], v[240:243], v[140:143], v[20:23]
	v_mfma_f32_16x16x32_bf16 v[16:19], v[240:243], v[124:127], v[16:19]
	s_waitcnt lgkmcnt(0)
	s_waitcnt vmcnt(12)
	s_barrier
	v_mfma_f32_16x16x32_bf16 v[12:15], v[166:169], v[120:123], v[12:15]
	v_mfma_f32_16x16x32_bf16 v[8:11], v[166:169], v[128:131], v[8:11]
	v_mfma_f32_16x16x32_bf16 v[4:7], v[166:169], v[140:143], v[4:7]
	v_mfma_f32_16x16x32_bf16 v[0:3], v[166:169], v[124:127], v[0:3]
	v_add_u32_e32 v229, s8, v163
	v_add_u32_e32 v228, s8, v162
	ds_read_b128 v[120:123], v229 offset:16384
	ds_read_b128 v[166:169], v228
	ds_read_b128 v[128:131], v229 offset:17408
	ds_read_b128 v[140:143], v229 offset:18432
	ds_read_b128 v[124:127], v229 offset:19456
	ds_read_b128 v[152:155], v228 offset:1024
	ds_read_b128 v[170:173], v228 offset:2048
	ds_read_b128 v[132:135], v228 offset:3072
	s_waitcnt lgkmcnt(6)
	v_mfma_f32_16x16x32_bf16 v[148:151], v[166:169], v[120:123], v[148:151]
	s_waitcnt lgkmcnt(5)
	v_mfma_f32_16x16x32_bf16 v[144:147], v[166:169], v[128:131], v[144:147]
	s_waitcnt lgkmcnt(4)
	v_mfma_f32_16x16x32_bf16 v[116:119], v[166:169], v[140:143], v[116:119]
	s_waitcnt lgkmcnt(3)
	v_mfma_f32_16x16x32_bf16 v[112:115], v[166:169], v[124:127], v[112:115]
	ds_read_b128 v[232:235], v228 offset:4096
	ds_read_b128 v[236:239], v228 offset:5120
	s_waitcnt lgkmcnt(4)
	v_mfma_f32_16x16x32_bf16 v[108:111], v[152:155], v[120:123], v[108:111]
	v_mfma_f32_16x16x32_bf16 v[104:107], v[152:155], v[128:131], v[104:107]
	v_mfma_f32_16x16x32_bf16 v[100:103], v[152:155], v[140:143], v[100:103]
	v_mfma_f32_16x16x32_bf16 v[96:99], v[152:155], v[124:127], v[96:99]
	s_waitcnt lgkmcnt(3)
; DEV f32x4 mfma16(bf16x8 a, bf16x8 b, f32x4 c) { return __builtin_amdgcn_mfma_f32_16x16x32_bf16(a, b, c, 0, 0, 0); }
; DEV void gemm_tile(const u16* __restrict__ A, size_t lda, const u16* __restrict__ Bt, size_t ldb, int K,
;                    u16* sA, u16* sB, f32x4 (&acc)[8][4]) {
;     ...
;   for (int kt = 0; kt < nk; ++kt) {
;     const int st = kt & 1;
;     if (kt + 1 < nk) S_STORE(st ^ 1)
;     if (kt + 2 < nk) G_LOAD((kt + 2) << 5)
;     {
;       const u16* pa = sAr + st * 12288;
;       const u16* pb = sBr + st * 12288;
;       bf16x8 b[4];
; #pragma unroll
;       for (int ni = 0; ni < 4; ++ni) b[ni] = *(const bf16x8*)(pb + ni * 16 * 32);
; #pragma unroll
;       for (int mh = 0; mh < 2; ++mh) {
;         bf16x8 a[4];
; #pragma unroll
;         for (int mi = 0; mi < 4; ++mi) a[mi] = *(const bf16x8*)(pa + (mh * 64 + mi * 16) * 32);
; #pragma unroll
;         for (int mi = 0; mi < 4; ++mi)
; #pragma unroll
;           for (int ni = 0; ni < 4; ++ni) acc[mh * 4 + mi][ni] = mfma16(a[mi], b[ni], acc[mh * 4 + mi][ni]);
;       }
;     }
;     __syncthreads();
;   }
	v_mfma_f32_16x16x32_bf16 v[92:95], v[170:173], v[120:123], v[92:95]
	v_mfma_f32_16x16x32_bf16 v[88:91], v[170:173], v[128:131], v[88:91]
	v_mfma_f32_16x16x32_bf16 v[84:87], v[170:173], v[140:143], v[84:87]
	v_mfma_f32_16x16x32_bf16 v[80:83], v[170:173], v[124:127], v[80:83]
	ds_read_b128 v[240:243], v228 offset:6144
	ds_read_b128 v[166:169], v228 offset:7168
	s_waitcnt lgkmcnt(4)
	v_mfma_f32_16x16x32_bf16 v[76:79], v[132:135], v[120:123], v[76:79]
	s_waitcnt vmcnt(0)
	v_add_u32_e32 v231, s9, v230
	v_mfma_f32_16x16x32_bf16 v[72:75], v[132:135], v[128:131], v[72:75]
	ds_write_b128 v231, v[244:247]
	v_mfma_f32_16x16x32_bf16 v[68:71], v[132:135], v[140:143], v[68:71]
	ds_write_b128 v231, v[252:255] offset:4096
	v_mfma_f32_16x16x32_bf16 v[64:67], v[132:135], v[124:127], v[64:67]
	ds_write_b128 v231, v[208:211] offset:8192
	s_waitcnt lgkmcnt(6)
	v_mfma_f32_16x16x32_bf16 v[60:63], v[232:235], v[120:123], v[60:63]
	ds_write_b128 v231, v[212:215] offset:12288
	v_mfma_f32_16x16x32_bf16 v[56:59], v[232:235], v[128:131], v[56:59]
	ds_write_b128 v231, v[216:219] offset:16384
	v_mfma_f32_16x16x32_bf16 v[52:55], v[232:235], v[140:143], v[52:55]
	ds_write_b128 v231, v[220:223] offset:20480
	v_mfma_f32_16x16x32_bf16 v[48:51], v[232:235], v[124:127], v[48:51]
	s_add_i32 s9, s8, s5
	s_add_i32 s8, s8, 0x6000
	s_waitcnt lgkmcnt(8)
	v_mfma_f32_16x16x32_bf16 v[44:47], v[236:239], v[120:123], v[44:47]
	s_cmp_eq_u32 s8, 0x12000
	s_cselect_b32 s8, 0, s8
	v_mfma_f32_16x16x32_bf16 v[40:43], v[236:239], v[128:131], v[40:43]
	s_add_u32 s6, s6, 64
	s_addc_u32 s7, s7, 0
	s_cmpk_lg_i32 s6, 0xf80
	v_mfma_f32_16x16x32_bf16 v[36:39], v[236:239], v[140:143], v[36:39]
	v_mfma_f32_16x16x32_bf16 v[32:35], v[236:239], v[124:127], v[32:35]
	s_waitcnt lgkmcnt(7)
	v_mfma_f32_16x16x32_bf16 v[28:31], v[240:243], v[120:123], v[28:31]
	v_mfma_f32_16x16x32_bf16 v[24:27], v[240:243], v[128:131], v[24:27]
	v_mfma_f32_16x16x32_bf16 v[20:23], v[240:243], v[140:143], v[20:23]
	v_mfma_f32_16x16x32_bf16 v[16:19], v[240:243], v[124:127], v[16:19]
	s_waitcnt lgkmcnt(6)
	s_waitcnt lgkmcnt(0)
	s_barrier
	v_mfma_f32_16x16x32_bf16 v[12:15], v[166:169], v[120:123], v[12:15]
	v_mfma_f32_16x16x32_bf16 v[8:11], v[166:169], v[128:131], v[8:11]
	v_mfma_f32_16x16x32_bf16 v[4:7], v[166:169], v[140:143], v[4:7]
	v_mfma_f32_16x16x32_bf16 v[0:3], v[166:169], v[124:127], v[0:3]
	s_cbranch_scc1 .LBB0_226
	ds_read_b128 v[120:123], v163 offset:16384
	ds_read_b128 v[124:127], v163 offset:17408
	ds_read_b128 v[128:131], v163 offset:18432
	ds_read_b128 v[132:135], v163 offset:19456
	ds_read_b128 v[136:139], v162
	ds_read_b128 v[140:143], v162 offset:1024
	ds_read_b128 v[152:155], v162 offset:2048
	ds_read_b128 v[158:161], v162 offset:3072
	s_waitcnt lgkmcnt(3)
	v_mfma_f32_16x16x32_bf16 v[148:151], v[136:139], v[120:123], v[148:151]
	v_mfma_f32_16x16x32_bf16 v[144:147], v[136:139], v[124:127], v[144:147]
	v_mfma_f32_16x16x32_bf16 v[116:119], v[136:139], v[128:131], v[116:119]
	v_mfma_f32_16x16x32_bf16 v[112:115], v[136:139], v[132:135], v[112:115]
	s_waitcnt lgkmcnt(2)
	v_mfma_f32_16x16x32_bf16 v[108:111], v[140:143], v[120:123], v[108:111]
	v_mfma_f32_16x16x32_bf16 v[104:107], v[140:143], v[124:127], v[104:107]
	v_mfma_f32_16x16x32_bf16 v[100:103], v[140:143], v[128:131], v[100:103]
	v_mfma_f32_16x16x32_bf16 v[96:99], v[140:143], v[132:135], v[96:99]
	s_waitcnt lgkmcnt(1)
	v_mfma_f32_16x16x32_bf16 v[92:95], v[152:155], v[120:123], v[92:95]
	v_mfma_f32_16x16x32_bf16 v[88:91], v[152:155], v[124:127], v[88:91]
	v_mfma_f32_16x16x32_bf16 v[84:87], v[152:155], v[128:131], v[84:87]
	v_mfma_f32_16x16x32_bf16 v[80:83], v[152:155], v[132:135], v[80:83]
	s_waitcnt lgkmcnt(0)
	v_mfma_f32_16x16x32_bf16 v[76:79], v[158:161], v[120:123], v[76:79]
	v_mfma_f32_16x16x32_bf16 v[72:75], v[158:161], v[124:127], v[72:75]
	v_mfma_f32_16x16x32_bf16 v[68:71], v[158:161], v[128:131], v[68:71]
	v_mfma_f32_16x16x32_bf16 v[64:67], v[158:161], v[132:135], v[64:67]
	ds_read_b128 v[136:139], v162 offset:4096
	ds_read_b128 v[140:143], v162 offset:5120
	ds_read_b128 v[152:155], v162 offset:6144
	ds_read_b128 v[158:161], v162 offset:7168
	s_waitcnt lgkmcnt(0)
	s_waitcnt vmcnt(0)
	s_barrier
	v_mfma_f32_16x16x32_bf16 v[60:63], v[136:139], v[120:123], v[60:63]
	v_mfma_f32_16x16x32_bf16 v[56:59], v[136:139], v[124:127], v[56:59]
	v_mfma_f32_16x16x32_bf16 v[52:55], v[136:139], v[128:131], v[52:55]
	v_mfma_f32_16x16x32_bf16 v[48:51], v[136:139], v[132:135], v[48:51]
	v_mfma_f32_16x16x32_bf16 v[44:47], v[140:143], v[120:123], v[44:47]
	v_mfma_f32_16x16x32_bf16 v[40:43], v[140:143], v[124:127], v[40:43]
	v_mfma_f32_16x16x32_bf16 v[36:39], v[140:143], v[128:131], v[36:39]
	v_mfma_f32_16x16x32_bf16 v[32:35], v[140:143], v[132:135], v[32:35]
	v_mfma_f32_16x16x32_bf16 v[28:31], v[152:155], v[120:123], v[28:31]
	v_mfma_f32_16x16x32_bf16 v[24:27], v[152:155], v[124:127], v[24:27]
	v_mfma_f32_16x16x32_bf16 v[20:23], v[152:155], v[128:131], v[20:23]
	v_mfma_f32_16x16x32_bf16 v[16:19], v[152:155], v[132:135], v[16:19]
	v_mfma_f32_16x16x32_bf16 v[12:15], v[158:161], v[120:123], v[12:15]
	v_mfma_f32_16x16x32_bf16 v[8:11], v[158:161], v[124:127], v[8:11]
	v_mfma_f32_16x16x32_bf16 v[4:7], v[158:161], v[128:131], v[4:7]
	v_mfma_f32_16x16x32_bf16 v[0:3], v[158:161], v[132:135], v[0:3]
	ds_read_b128 v[128:131], v163 offset:40960
	ds_read_b128 v[132:135], v163 offset:41984
	ds_read_b128 v[136:139], v163 offset:43008
	ds_read_b128 v[140:143], v163 offset:44032
	ds_read_b128 v[152:155], v162 offset:24576
	ds_read_b128 v[158:161], v162 offset:25600
	ds_read_b128 v[164:167], v162 offset:26624
	ds_read_b128 v[168:171], v162 offset:27648
	s_waitcnt lgkmcnt(3)
	v_mfma_f32_16x16x32_bf16 v[124:127], v[152:155], v[128:131], v[148:151]
	v_mfma_f32_16x16x32_bf16 v[120:123], v[152:155], v[132:135], v[144:147]
	v_mfma_f32_16x16x32_bf16 v[116:119], v[152:155], v[136:139], v[116:119]
	v_mfma_f32_16x16x32_bf16 v[112:115], v[152:155], v[140:143], v[112:115]
	s_waitcnt lgkmcnt(2)
	v_mfma_f32_16x16x32_bf16 v[108:111], v[158:161], v[128:131], v[108:111]
	v_mfma_f32_16x16x32_bf16 v[104:107], v[158:161], v[132:135], v[104:107]
	v_mfma_f32_16x16x32_bf16 v[100:103], v[158:161], v[136:139], v[100:103]
	v_mfma_f32_16x16x32_bf16 v[96:99], v[158:161], v[140:143], v[96:99]
	ds_read_b128 v[144:147], v162 offset:28672
	ds_read_b128 v[148:151], v162 offset:29696
	ds_read_b128 v[152:155], v162 offset:30720
	ds_read_b128 v[158:161], v162 offset:31744
	s_waitcnt lgkmcnt(0)
	s_barrier
; DEV int TID() { int t = threadIdx.x; asm volatile("" : "+v"(t)); return t; }
; DEV f32x4 mfma16(bf16x8 a, bf16x8 b, f32x4 c) { return __builtin_amdgcn_mfma_f32_16x16x32_bf16(a, b, c, 0, 0, 0); }
; DEV void gemm_tile(const u16* __restrict__ A, size_t lda, const u16* __restrict__ Bt, size_t ldb, int K,
;                    u16* sA, u16* sB, f32x4 (&acc)[8][4]) {
;     ...
;       for (int ni = 0; ni < 4; ++ni) b[ni] = *(const bf16x8*)(pb + ni * 16 * 32);
; #pragma unroll
;       for (int mh = 0; mh < 2; ++mh) {
;         bf16x8 a[4];
; #pragma unroll
;         for (int mi = 0; mi < 4; ++mi) a[mi] = *(const bf16x8*)(pa + (mh * 64 + mi * 16) * 32);
; #pragma unroll
;         for (int mi = 0; mi < 4; ++mi)
; #pragma unroll
;           for (int ni = 0; ni < 4; ++ni) acc[mh * 4 + mi][ni] = mfma16(a[mi], b[ni], acc[mh * 4 + mi][ni]);
; DEV void store_tile_bf16(const f32x4 (&acc)[8][4], u16* __restrict__ OUT, size_t ld, int m0, int n0, int ncols,
;                          unsigned char* smem) {
;   const int tid = TID(), lane = tid & 63, wid = tid >> 6;
;   const int wr = wid >> 1, wc = wid & 1, fr = lane & 15, fq = lane >> 4;
;   u16* st = (u16*)(smem + wid * 9216);
; #pragma unroll
;   for (int mh = 0; mh < 2; ++mh) {
; #pragma unroll
;     for (int mi = 0; mi < 4; ++mi)
; #pragma unroll
;       for (int ni = 0; ni < 4; ++ni)
; #pragma unroll
;         for (int j = 0; j < 4; ++j) st[(mi * 16 + fq * 4 + j) * 72 + ni * 16 + fr] = f2bf(acc[mh * 4 + mi][ni][j]);
;     const int chunk = lane & 7;
;     const int c0 = n0 + wc * 64 + chunk * 8;
; #pragma unroll
;     for (int itr = 0; itr < 8; ++itr) {
;       const int rl = (lane >> 3) + 8 * itr;
;       const u32x4 v = *(const u32x4*)(st + rl * 72 + chunk * 8);
;       if (c0 + 8 <= ncols) *(u32x4*)(OUT + (size_t)(m0 + wr * 128 + mh * 64 + rl) * ld + c0) = v;
;     }
;   }
; }
	v_mfma_f32_16x16x32_bf16 v[92:95], v[164:167], v[128:131], v[92:95]
	v_mfma_f32_16x16x32_bf16 v[76:79], v[168:171], v[128:131], v[76:79]
	v_mfma_f32_16x16x32_bf16 v[60:63], v[144:147], v[128:131], v[60:63]
	v_mfma_f32_16x16x32_bf16 v[44:47], v[148:151], v[128:131], v[44:47]
	v_mfma_f32_16x16x32_bf16 v[28:31], v[152:155], v[128:131], v[28:31]
	v_mfma_f32_16x16x32_bf16 v[12:15], v[158:161], v[128:131], v[12:15]
	v_mov_b32_e32 v129, v178
	s_nop 0
	v_lshrrev_b32_e32 v128, 6, v129
	v_mfma_f32_16x16x32_bf16 v[88:91], v[164:167], v[132:135], v[88:91]
	v_mul_lo_u32 v131, v128, s75
	v_lshrrev_b32_e32 v128, 2, v129
	v_and_b32_e32 v130, 15, v129
	v_mfma_f32_16x16x32_bf16 v[72:75], v[168:171], v[132:135], v[72:75]
	v_lshl_or_b32 v130, v130, 1, v131
	v_mfma_f32_16x16x32_bf16 v[56:59], v[144:147], v[132:135], v[56:59]
	v_mfma_f32_16x16x32_bf16 v[40:43], v[148:151], v[132:135], v[40:43]
	v_mfma_f32_16x16x32_bf16 v[24:27], v[152:155], v[132:135], v[24:27]
	v_mfma_f32_16x16x32_bf16 v[8:11], v[158:161], v[132:135], v[8:11]
	v_lshlrev_b32_e32 v133, 3, v129
	v_and_b32_e32 v132, 12, v128
	v_and_b32_e32 v128, 64, v129
	v_and_b32_e32 v133, 56, v133
	v_or3_b32 v128, v128, s18, v133
	v_lshl_or_b32 v131, v133, 1, v131
	v_bfe_u32 v133, v129, 3, 3
	v_and_b32_e32 v129, 0xffffff80, v129
	v_add_u32_e32 v134, s4, v129
	v_bfe_u32 v135, v124, 16, 1
	s_movk_i32 s4, 0x90
	v_add3_u32 v135, v124, v135, s71
	v_mad_u32_u24 v124, v132, s4, v130
	v_bfe_u32 v130, v125, 16, 1
	v_add3_u32 v125, v125, v130, s71
	ds_write_b16_d16_hi v124, v125 offset:144
	v_bfe_u32 v125, v126, 16, 1
	v_add3_u32 v125, v126, v125, s71
	ds_write_b16_d16_hi v124, v125 offset:288
	v_bfe_u32 v125, v127, 16, 1
	v_add3_u32 v125, v127, v125, s71
	ds_write_b16_d16_hi v124, v125 offset:432
	v_bfe_u32 v125, v120, 16, 1
	v_add3_u32 v120, v120, v125, s71
	ds_write_b16_d16_hi v124, v120 offset:32
	v_bfe_u32 v120, v121, 16, 1
	v_add3_u32 v120, v121, v120, s71
	ds_write_b16_d16_hi v124, v120 offset:176
	v_bfe_u32 v120, v122, 16, 1
	v_add3_u32 v120, v122, v120, s71
	ds_write_b16_d16_hi v124, v120 offset:320
	v_bfe_u32 v120, v123, 16, 1
	v_add3_u32 v120, v123, v120, s71
	ds_write_b16_d16_hi v124, v120 offset:464
	v_bfe_u32 v120, v116, 16, 1
	v_add3_u32 v116, v116, v120, s71
	ds_write_b16_d16_hi v124, v116 offset:64
	v_bfe_u32 v116, v117, 16, 1
	v_add3_u32 v116, v117, v116, s71
	ds_write_b16_d16_hi v124, v116 offset:208
	v_bfe_u32 v116, v118, 16, 1
	v_add3_u32 v116, v118, v116, s71
	ds_write_b16_d16_hi v124, v116 offset:352
	v_bfe_u32 v116, v119, 16, 1
	v_add3_u32 v116, v119, v116, s71
	ds_write_b16_d16_hi v124, v116 offset:496
	v_bfe_u32 v116, v112, 16, 1
	v_add3_u32 v112, v112, v116, s71
	ds_write_b16_d16_hi v124, v112 offset:96
	v_bfe_u32 v112, v113, 16, 1
	v_add3_u32 v112, v113, v112, s71
	ds_write_b16_d16_hi v124, v112 offset:240
	v_bfe_u32 v112, v114, 16, 1
	v_add3_u32 v112, v114, v112, s71
	ds_write_b16_d16_hi v124, v112 offset:384
	v_bfe_u32 v112, v115, 16, 1
	v_add3_u32 v112, v115, v112, s71
	ds_write_b16_d16_hi v124, v112 offset:528
	v_bfe_u32 v112, v108, 16, 1
	v_add3_u32 v108, v108, v112, s71
	ds_write_b16_d16_hi v124, v108 offset:2304
	v_bfe_u32 v108, v109, 16, 1
	v_add3_u32 v108, v109, v108, s71
	ds_write_b16_d16_hi v124, v108 offset:2448
	v_bfe_u32 v108, v110, 16, 1
	v_add3_u32 v108, v110, v108, s71
	ds_write_b16_d16_hi v124, v108 offset:2592
	v_bfe_u32 v108, v111, 16, 1
	v_add3_u32 v108, v111, v108, s71
	ds_write_b16_d16_hi v124, v108 offset:2736
	v_bfe_u32 v108, v104, 16, 1
	v_add3_u32 v104, v104, v108, s71
	ds_write_b16_d16_hi v124, v104 offset:2336
	v_bfe_u32 v104, v105, 16, 1
	v_add3_u32 v104, v105, v104, s71
	ds_write_b16_d16_hi v124, v104 offset:2480
	v_bfe_u32 v104, v106, 16, 1
	v_add3_u32 v104, v106, v104, s71
	ds_write_b16_d16_hi v124, v104 offset:2624
	v_bfe_u32 v104, v107, 16, 1
	v_add3_u32 v104, v107, v104, s71
	ds_write_b16_d16_hi v124, v104 offset:2768
	v_bfe_u32 v104, v100, 16, 1
	v_add3_u32 v100, v100, v104, s71
	ds_write_b16_d16_hi v124, v100 offset:2368
	v_bfe_u32 v100, v101, 16, 1
	v_add3_u32 v100, v101, v100, s71
	ds_write_b16_d16_hi v124, v100 offset:2512
	v_bfe_u32 v100, v102, 16, 1
	v_add3_u32 v100, v102, v100, s71
	ds_write_b16_d16_hi v124, v100 offset:2656
	v_bfe_u32 v100, v103, 16, 1
	v_add3_u32 v100, v103, v100, s71
	ds_write_b16_d16_hi v124, v100 offset:2800
	v_bfe_u32 v100, v96, 16, 1
	v_add3_u32 v96, v96, v100, s71
	ds_write_b16_d16_hi v124, v96 offset:2400
	v_bfe_u32 v96, v97, 16, 1
	v_add3_u32 v96, v97, v96, s71
	ds_write_b16_d16_hi v124, v96 offset:2544
	v_bfe_u32 v96, v98, 16, 1
	v_add3_u32 v96, v98, v96, s71
	ds_write_b16_d16_hi v124, v96 offset:2688
	v_bfe_u32 v96, v99, 16, 1
	v_add3_u32 v96, v99, v96, s71
	ds_write_b16_d16_hi v124, v96 offset:2832
	v_bfe_u32 v96, v92, 16, 1
	v_add3_u32 v92, v92, v96, s71
	ds_write_b16_d16_hi v124, v92 offset:4608
	v_bfe_u32 v92, v93, 16, 1
	v_add3_u32 v92, v93, v92, s71
	ds_write_b16_d16_hi v124, v92 offset:4752
	v_bfe_u32 v92, v94, 16, 1
	v_add3_u32 v92, v94, v92, s71
	ds_write_b16_d16_hi v124, v92 offset:4896
	v_bfe_u32 v92, v95, 16, 1
	v_add3_u32 v92, v95, v92, s71
	ds_write_b16_d16_hi v124, v92 offset:5040
	v_bfe_u32 v92, v88, 16, 1
	v_add3_u32 v88, v88, v92, s71
	ds_write_b16_d16_hi v124, v88 offset:4640
	v_bfe_u32 v88, v89, 16, 1
	v_add3_u32 v88, v89, v88, s71
	v_mfma_f32_16x16x32_bf16 v[84:87], v[164:167], v[136:139], v[84:87]
	ds_write_b16_d16_hi v124, v88 offset:4784
	v_bfe_u32 v88, v90, 16, 1
	v_add3_u32 v88, v90, v88, s71
	ds_write_b16_d16_hi v124, v88 offset:4928
	v_bfe_u32 v88, v91, 16, 1
	v_add3_u32 v88, v91, v88, s71
; DEV int TID() { int t = threadIdx.x; asm volatile("" : "+v"(t)); return t; }
; DEV f32x4 mfma16(bf16x8 a, bf16x8 b, f32x4 c) { return __builtin_amdgcn_mfma_f32_16x16x32_bf16(a, b, c, 0, 0, 0); }
; DEV void gemm_tile(const u16* __restrict__ A, size_t lda, const u16* __restrict__ Bt, size_t ldb, int K,
;                    u16* sA, u16* sB, f32x4 (&acc)[8][4]) {
;     ...
;       for (int ni = 0; ni < 4; ++ni) b[ni] = *(const bf16x8*)(pb + ni * 16 * 32);
; #pragma unroll
;       for (int mh = 0; mh < 2; ++mh) {
;         bf16x8 a[4];
; #pragma unroll
;         for (int mi = 0; mi < 4; ++mi) a[mi] = *(const bf16x8*)(pa + (mh * 64 + mi * 16) * 32);
; #pragma unroll
;         for (int mi = 0; mi < 4; ++mi)
; #pragma unroll
;           for (int ni = 0; ni < 4; ++ni) acc[mh * 4 + mi][ni] = mfma16(a[mi], b[ni], acc[mh * 4 + mi][ni]);
; DEV void store_tile_bf16(const f32x4 (&acc)[8][4], u16* __restrict__ OUT, size_t ld, int m0, int n0, int ncols,
;                          unsigned char* smem) {
;   const int tid = TID(), lane = tid & 63, wid = tid >> 6;
;   const int wr = wid >> 1, wc = wid & 1, fr = lane & 15, fq = lane >> 4;
;   u16* st = (u16*)(smem + wid * 9216);
; #pragma unroll
;   for (int mh = 0; mh < 2; ++mh) {
; #pragma unroll
;     for (int mi = 0; mi < 4; ++mi)
; #pragma unroll
;       for (int ni = 0; ni < 4; ++ni)
; #pragma unroll
;         for (int j = 0; j < 4; ++j) st[(mi * 16 + fq * 4 + j) * 72 + ni * 16 + fr] = f2bf(acc[mh * 4 + mi][ni][j]);
;     const int chunk = lane & 7;
;     const int c0 = n0 + wc * 64 + chunk * 8;
; #pragma unroll
;     for (int itr = 0; itr < 8; ++itr) {
;       const int rl = (lane >> 3) + 8 * itr;
;       const u32x4 v = *(const u32x4*)(st + rl * 72 + chunk * 8);
;       if (c0 + 8 <= ncols) *(u32x4*)(OUT + (size_t)(m0 + wr * 128 + mh * 64 + rl) * ld + c0) = v;
;     }
;   }
; }
	ds_write_b16_d16_hi v124, v88 offset:5072
	s_nop 0
	v_bfe_u32 v88, v84, 16, 1
	v_add3_u32 v84, v84, v88, s71
	ds_write_b16_d16_hi v124, v84 offset:4672
	v_bfe_u32 v84, v85, 16, 1
	v_add3_u32 v84, v85, v84, s71
	v_mfma_f32_16x16x32_bf16 v[80:83], v[164:167], v[140:143], v[80:83]
	ds_write_b16_d16_hi v124, v84 offset:4816
	v_bfe_u32 v84, v86, 16, 1
	v_add3_u32 v84, v86, v84, s71
	ds_write_b16_d16_hi v124, v84 offset:4960
	v_bfe_u32 v84, v87, 16, 1
	v_add3_u32 v84, v87, v84, s71
	ds_write_b16_d16_hi v124, v84 offset:5104
	s_nop 0
	v_bfe_u32 v84, v80, 16, 1
	v_add3_u32 v80, v80, v84, s71
	ds_write_b16_d16_hi v124, v80 offset:4704
	v_bfe_u32 v80, v81, 16, 1
	v_add3_u32 v80, v81, v80, s71
	ds_write_b16_d16_hi v124, v80 offset:4848
	v_bfe_u32 v80, v82, 16, 1
	v_add3_u32 v80, v82, v80, s71
	ds_write_b16_d16_hi v124, v80 offset:4992
	v_bfe_u32 v80, v83, 16, 1
	v_add3_u32 v80, v83, v80, s71
	ds_write_b16_d16_hi v124, v80 offset:5136
	v_bfe_u32 v80, v76, 16, 1
	v_add3_u32 v76, v76, v80, s71
	ds_write_b16_d16_hi v124, v76 offset:6912
	v_bfe_u32 v76, v77, 16, 1
	v_add3_u32 v76, v77, v76, s71
	ds_write_b16_d16_hi v124, v76 offset:7056
	v_bfe_u32 v76, v78, 16, 1
	v_add3_u32 v76, v78, v76, s71
	ds_write_b16_d16_hi v124, v76 offset:7200
	v_bfe_u32 v76, v79, 16, 1
	v_add3_u32 v76, v79, v76, s71
	ds_write_b16_d16_hi v124, v76 offset:7344
	v_bfe_u32 v76, v72, 16, 1
	v_add3_u32 v72, v72, v76, s71
	ds_write_b16_d16_hi v124, v72 offset:6944
	v_bfe_u32 v72, v73, 16, 1
	v_add3_u32 v72, v73, v72, s71
	v_mfma_f32_16x16x32_bf16 v[68:71], v[168:171], v[136:139], v[68:71]
	ds_write_b16_d16_hi v124, v72 offset:7088
	v_bfe_u32 v72, v74, 16, 1
	v_add3_u32 v72, v74, v72, s71
	ds_write_b16_d16_hi v124, v72 offset:7232
	v_bfe_u32 v72, v75, 16, 1
	v_add3_u32 v72, v75, v72, s71
	ds_write_b16_d16_hi v124, v72 offset:7376
	s_nop 0
	v_bfe_u32 v72, v68, 16, 1
	v_add3_u32 v68, v68, v72, s71
	ds_write_b16_d16_hi v124, v68 offset:6976
	v_bfe_u32 v68, v69, 16, 1
	v_add3_u32 v68, v69, v68, s71
	v_mfma_f32_16x16x32_bf16 v[64:67], v[168:171], v[140:143], v[64:67]
	ds_write_b16_d16_hi v124, v68 offset:7120
	v_bfe_u32 v68, v70, 16, 1
	v_add3_u32 v68, v70, v68, s71
	ds_write_b16_d16_hi v124, v68 offset:7264
	v_bfe_u32 v68, v71, 16, 1
	v_add3_u32 v68, v71, v68, s71
	ds_write_b16_d16_hi v124, v68 offset:7408
	s_nop 0
	v_bfe_u32 v68, v64, 16, 1
	v_add3_u32 v64, v64, v68, s71
	ds_write_b16_d16_hi v124, v64 offset:7008
	v_bfe_u32 v64, v65, 16, 1
	v_add3_u32 v64, v65, v64, s71
	ds_write_b16_d16_hi v124, v64 offset:7152
	v_bfe_u32 v64, v66, 16, 1
	v_mfma_f32_16x16x32_bf16 v[52:55], v[144:147], v[136:139], v[52:55]
	v_add3_u32 v64, v66, v64, s71
	ds_write_b16_d16_hi v124, v64 offset:7296
	v_bfe_u32 v64, v67, 16, 1
	v_mfma_f32_16x16x32_bf16 v[48:51], v[144:147], v[140:143], v[48:51]
	v_ashrrev_i32_e32 v129, 31, v128
	v_add3_u32 v64, v67, v64, s71
	v_cmp_gt_i32_e32 vcc, s33, v128
	v_mfma_f32_16x16x32_bf16 v[36:39], v[148:151], v[136:139], v[36:39]
	v_lshl_add_u64 v[128:129], v[128:129], 1, s[68:69]
	ds_write_b16_d16_hi v124, v64 offset:7440
	v_mad_u32_u24 v66, v133, s4, v131
	v_mfma_f32_16x16x32_bf16 v[32:35], v[148:151], v[140:143], v[32:35]
	v_or_b32_e32 v64, v134, v133
	ds_write_b16_d16_hi v124, v135
	v_mfma_f32_16x16x32_bf16 v[20:23], v[152:155], v[136:139], v[20:23]
	v_mfma_f32_16x16x32_bf16 v[16:19], v[152:155], v[140:143], v[16:19]
	v_mfma_f32_16x16x32_bf16 v[4:7], v[158:161], v[136:139], v[4:7]
	v_mfma_f32_16x16x32_bf16 v[0:3], v[158:161], v[140:143], v[0:3]
	s_and_saveexec_b64 s[4:5], vcc
	s_cbranch_execz .LBB0_229
	ds_read_b128 v[68:71], v66
	v_ashrrev_i32_e32 v65, 31, v64
	v_lshlrev_b64 v[72:73], 13, v[64:65]
	v_lshl_add_u64 v[72:73], v[128:129], 0, v[72:73]
	s_waitcnt lgkmcnt(0)
	global_store_dwordx4 v[72:73], v[68:71], off
	ds_read_b128 v[68:71], v66 offset:1152
	v_or_b32_e32 v72, 8, v64
	v_ashrrev_i32_e32 v73, 31, v72
	v_lshlrev_b64 v[72:73], 13, v[72:73]
	v_lshl_add_u64 v[72:73], v[128:129], 0, v[72:73]
	s_waitcnt lgkmcnt(0)
	global_store_dwordx4 v[72:73], v[68:71], off
	ds_read_b128 v[68:71], v66 offset:2304
	v_or_b32_e32 v72, 16, v64
	v_ashrrev_i32_e32 v73, 31, v72
	v_lshlrev_b64 v[72:73], 13, v[72:73]
	v_lshl_add_u64 v[72:73], v[128:129], 0, v[72:73]
	s_waitcnt lgkmcnt(0)
	global_store_dwordx4 v[72:73], v[68:71], off
	ds_read_b128 v[68:71], v66 offset:3456
	v_or_b32_e32 v72, 24, v64
	v_ashrrev_i32_e32 v73, 31, v72
	v_lshlrev_b64 v[72:73], 13, v[72:73]
	v_lshl_add_u64 v[72:73], v[128:129], 0, v[72:73]
	s_waitcnt lgkmcnt(0)
	global_store_dwordx4 v[72:73], v[68:71], off
	ds_read_b128 v[68:71], v66 offset:4608
	v_or_b32_e32 v72, 32, v64
	v_ashrrev_i32_e32 v73, 31, v72
	v_lshlrev_b64 v[72:73], 13, v[72:73]
	v_lshl_add_u64 v[72:73], v[128:129], 0, v[72:73]
	s_waitcnt lgkmcnt(0)
	global_store_dwordx4 v[72:73], v[68:71], off
	ds_read_b128 v[68:71], v66 offset:5760
	v_or_b32_e32 v72, 40, v64
	v_ashrrev_i32_e32 v73, 31, v72
	v_lshlrev_b64 v[72:73], 13, v[72:73]
	v_lshl_add_u64 v[72:73], v[128:129], 0, v[72:73]
	s_waitcnt lgkmcnt(0)
	global_store_dwordx4 v[72:73], v[68:71], off
	ds_read_b128 v[68:71], v66 offset:6912
	v_or_b32_e32 v72, 48, v64
	v_ashrrev_i32_e32 v73, 31, v72
	v_lshlrev_b64 v[72:73], 13, v[72:73]
	v_lshl_add_u64 v[72:73], v[128:129], 0, v[72:73]
	s_waitcnt lgkmcnt(0)
	global_store_dwordx4 v[72:73], v[68:71], off
	ds_read_b128 v[68:71], v66 offset:8064
	v_or_b32_e32 v72, 56, v64
	v_ashrrev_i32_e32 v73, 31, v72
	v_lshlrev_b64 v[72:73], 13, v[72:73]
	v_lshl_add_u64 v[72:73], v[128:129], 0, v[72:73]
	s_waitcnt lgkmcnt(0)
	global_store_dwordx4 v[72:73], v[68:71], off

; DEV f32x4 mfma16(bf16x8 a, bf16x8 b, f32x4 c) { return __builtin_amdgcn_mfma_f32_16x16x32_bf16(a, b, c, 0, 0, 0); }
; DEV void gemm_tile(const u16* __restrict__ A, size_t lda, const u16* __restrict__ Bt, size_t ldb, int K,
;                    u16* sA, u16* sB, f32x4 (&acc)[8][4]) {
;     ...
;   for (int kt = 0; kt < nk; ++kt) {
;     const int st = kt & 1;
;     if (kt + 1 < nk) S_STORE(st ^ 1)
;     if (kt + 2 < nk) G_LOAD((kt + 2) << 5)
;     {
;       const u16* pa = sAr + st * 12288;
;       const u16* pb = sBr + st * 12288;
;       bf16x8 b[4];
; #pragma unroll
;       for (int ni = 0; ni < 4; ++ni) b[ni] = *(const bf16x8*)(pb + ni * 16 * 32);
; #pragma unroll
;       for (int mh = 0; mh < 2; ++mh) {
;         bf16x8 a[4];
; #pragma unroll
;         for (int mi = 0; mi < 4; ++mi) a[mi] = *(const bf16x8*)(pa + (mh * 64 + mi * 16) * 32);
; #pragma unroll
;         for (int mi = 0; mi < 4; ++mi)
; #pragma unroll
;           for (int ni = 0; ni < 4; ++ni) acc[mh * 4 + mi][ni] = mfma16(a[mi], b[ni], acc[mh * 4 + mi][ni]);
;       }
;     }
;     __syncthreads();
;   }
.LBB0_251:
	v_add_u32_e32 v229, s8, v163
	v_add_u32_e32 v228, s8, v162
	ds_read_b128 v[124:127], v229 offset:16384
	ds_read_b128 v[166:169], v228
	ds_read_b128 v[132:135], v229 offset:17408
	ds_read_b128 v[144:147], v229 offset:18432
	ds_read_b128 v[128:131], v229 offset:19456
	ds_read_b128 v[152:155], v228 offset:1024
	ds_read_b128 v[170:173], v228 offset:2048
	ds_read_b128 v[136:139], v228 offset:3072
	s_waitcnt lgkmcnt(6)
	v_mfma_f32_16x16x32_bf16 v[148:151], v[166:169], v[124:127], v[148:151]
	s_add_i32 m0, s9, 0x0
	s_waitcnt lgkmcnt(5)
	v_mfma_f32_16x16x32_bf16 v[120:123], v[166:169], v[132:135], v[120:123]
	global_load_lds_dwordx4 v[140:141], off
	v_lshl_add_u64 v[140:141], v[140:141], 0, 64
	global_load_dwordx4 v[244:247], v[140:141], off
	v_lshl_add_u64 v[140:141], v[140:141], 0, 64
	s_waitcnt lgkmcnt(4)
	v_mfma_f32_16x16x32_bf16 v[116:119], v[166:169], v[144:147], v[116:119]
	s_add_i32 m0, s9, 0x1000
	s_waitcnt lgkmcnt(3)
	v_mfma_f32_16x16x32_bf16 v[112:115], v[166:169], v[128:131], v[112:115]
	ds_read_b128 v[232:235], v228 offset:4096
	ds_read_b128 v[236:239], v228 offset:5120
	s_waitcnt lgkmcnt(4)
	v_mfma_f32_16x16x32_bf16 v[108:111], v[152:155], v[124:127], v[108:111]
	global_load_lds_dwordx4 v[142:143], off
	v_lshl_add_u64 v[142:143], v[142:143], 0, 64
	global_load_dwordx4 v[252:255], v[142:143], off
	v_lshl_add_u64 v[142:143], v[142:143], 0, 64
	v_mfma_f32_16x16x32_bf16 v[104:107], v[152:155], v[132:135], v[104:107]
	s_add_i32 m0, s9, 0x2000
	v_mfma_f32_16x16x32_bf16 v[100:103], v[152:155], v[144:147], v[100:103]
	global_load_lds_dwordx4 v[174:175], off
	v_lshl_add_u64 v[174:175], v[174:175], 0, 64
	global_load_dwordx4 v[208:211], v[174:175], off
	v_lshl_add_u64 v[174:175], v[174:175], 0, 64
	v_mfma_f32_16x16x32_bf16 v[96:99], v[152:155], v[128:131], v[96:99]
	s_add_i32 m0, s9, 0x3000
	s_waitcnt lgkmcnt(3)
	v_mfma_f32_16x16x32_bf16 v[92:95], v[170:173], v[124:127], v[92:95]
	global_load_lds_dwordx4 v[176:177], off
	v_lshl_add_u64 v[176:177], v[176:177], 0, 64
	global_load_dwordx4 v[212:215], v[176:177], off
	v_lshl_add_u64 v[176:177], v[176:177], 0, 64
	v_mfma_f32_16x16x32_bf16 v[88:91], v[170:173], v[132:135], v[88:91]
	s_add_i32 m0, s9, 0x4000
	v_mfma_f32_16x16x32_bf16 v[84:87], v[170:173], v[144:147], v[84:87]
	global_load_lds_dwordx4 v[186:187], off
	v_lshl_add_u64 v[186:187], v[186:187], 0, 64
	global_load_dwordx4 v[216:219], v[186:187], off
	v_lshl_add_u64 v[186:187], v[186:187], 0, 64
	v_mfma_f32_16x16x32_bf16 v[80:83], v[170:173], v[128:131], v[80:83]
	ds_read_b128 v[240:243], v228 offset:6144
	ds_read_b128 v[166:169], v228 offset:7168
	s_waitcnt lgkmcnt(4)
	v_mfma_f32_16x16x32_bf16 v[76:79], v[136:139], v[124:127], v[76:79]
	s_add_i32 m0, s9, 0x5000
	v_mfma_f32_16x16x32_bf16 v[72:75], v[136:139], v[132:135], v[72:75]
	global_load_lds_dwordx4 v[188:189], off
	v_lshl_add_u64 v[188:189], v[188:189], 0, 64
	global_load_dwordx4 v[220:223], v[188:189], off
	v_lshl_add_u64 v[188:189], v[188:189], 0, 64
	v_mfma_f32_16x16x32_bf16 v[68:71], v[136:139], v[144:147], v[68:71]
	s_add_i32 s9, s8, s5
	s_add_i32 s8, s8, 0x6000
	v_mfma_f32_16x16x32_bf16 v[64:67], v[136:139], v[128:131], v[64:67]
	s_cmp_eq_u32 s8, 0x12000
	s_cselect_b32 s8, 0, s8
	s_waitcnt lgkmcnt(3)
	v_mfma_f32_16x16x32_bf16 v[60:63], v[232:235], v[124:127], v[60:63]
	s_add_u32 s6, s6, 64
	s_addc_u32 s7, s7, 0
	s_cmpk_lg_i32 s6, 0xf80
	v_mfma_f32_16x16x32_bf16 v[56:59], v[232:235], v[132:135], v[56:59]
	v_mfma_f32_16x16x32_bf16 v[52:55], v[232:235], v[144:147], v[52:55]
	v_mfma_f32_16x16x32_bf16 v[48:51], v[232:235], v[128:131], v[48:51]
	s_waitcnt lgkmcnt(2)
	v_mfma_f32_16x16x32_bf16 v[44:47], v[236:239], v[124:127], v[44:47]
	v_mfma_f32_16x16x32_bf16 v[40:43], v[236:239], v[132:135], v[40:43]
	v_mfma_f32_16x16x32_bf16 v[36:39], v[236:239], v[144:147], v[36:39]
	v_mfma_f32_16x16x32_bf16 v[32:35], v[236:239], v[128:131], v[32:35]
	s_waitcnt lgkmcnt(1)
	v_mfma_f32_16x16x32_bf16 v[28:31], v[240:243], v[124:127], v[28:31]
	v_mfma_f32_16x16x32_bf16 v[24:27], v[240:243], v[132:135], v[24:27]
	v_mfma_f32_16x16x32_bf16 v[20:23], v[240:243], v[144:147], v[20:23]
	v_mfma_f32_16x16x32_bf16 v[16:19], v[240:243], v[128:131], v[16:19]
	s_waitcnt lgkmcnt(0)
	s_waitcnt vmcnt(12)
	s_barrier
	v_mfma_f32_16x16x32_bf16 v[12:15], v[166:169], v[124:127], v[12:15]
	v_mfma_f32_16x16x32_bf16 v[8:11], v[166:169], v[132:135], v[8:11]
	v_mfma_f32_16x16x32_bf16 v[4:7], v[166:169], v[144:147], v[4:7]
	v_mfma_f32_16x16x32_bf16 v[0:3], v[166:169], v[128:131], v[0:3]
	v_add_u32_e32 v229, s8, v163
	v_add_u32_e32 v228, s8, v162
	ds_read_b128 v[124:127], v229 offset:16384
	ds_read_b128 v[166:169], v228
	ds_read_b128 v[132:135], v229 offset:17408
	ds_read_b128 v[144:147], v229 offset:18432
	ds_read_b128 v[128:131], v229 offset:19456
	ds_read_b128 v[152:155], v228 offset:1024
	ds_read_b128 v[170:173], v228 offset:2048
	ds_read_b128 v[136:139], v228 offset:3072
	s_waitcnt lgkmcnt(6)
	v_mfma_f32_16x16x32_bf16 v[148:151], v[166:169], v[124:127], v[148:151]
	s_waitcnt lgkmcnt(5)
	v_mfma_f32_16x16x32_bf16 v[120:123], v[166:169], v[132:135], v[120:123]
	s_waitcnt lgkmcnt(4)
	v_mfma_f32_16x16x32_bf16 v[116:119], v[166:169], v[144:147], v[116:119]
	s_waitcnt lgkmcnt(3)
	v_mfma_f32_16x16x32_bf16 v[112:115], v[166:169], v[128:131], v[112:115]
	ds_read_b128 v[232:235], v228 offset:4096
	ds_read_b128 v[236:239], v228 offset:5120
	s_waitcnt lgkmcnt(4)
	v_mfma_f32_16x16x32_bf16 v[108:111], v[152:155], v[124:127], v[108:111]
	v_mfma_f32_16x16x32_bf16 v[104:107], v[152:155], v[132:135], v[104:107]
	v_mfma_f32_16x16x32_bf16 v[100:103], v[152:155], v[144:147], v[100:103]
	v_mfma_f32_16x16x32_bf16 v[96:99], v[152:155], v[128:131], v[96:99]
	s_waitcnt lgkmcnt(3)
; DEV f32x4 mfma16(bf16x8 a, bf16x8 b, f32x4 c) { return __builtin_amdgcn_mfma_f32_16x16x32_bf16(a, b, c, 0, 0, 0); }
; DEV void gemm_tile(const u16* __restrict__ A, size_t lda, const u16* __restrict__ Bt, size_t ldb, int K,
;                    u16* sA, u16* sB, f32x4 (&acc)[8][4]) {
;     ...
;   for (int kt = 0; kt < nk; ++kt) {
;     const int st = kt & 1;
;     if (kt + 1 < nk) S_STORE(st ^ 1)
;     if (kt + 2 < nk) G_LOAD((kt + 2) << 5)
;     {
;       const u16* pa = sAr + st * 12288;
;       const u16* pb = sBr + st * 12288;
;       bf16x8 b[4];
; #pragma unroll
;       for (int ni = 0; ni < 4; ++ni) b[ni] = *(const bf16x8*)(pb + ni * 16 * 32);
; #pragma unroll
;       for (int mh = 0; mh < 2; ++mh) {
;         bf16x8 a[4];
; #pragma unroll
;         for (int mi = 0; mi < 4; ++mi) a[mi] = *(const bf16x8*)(pa + (mh * 64 + mi * 16) * 32);
; #pragma unroll
;         for (int mi = 0; mi < 4; ++mi)
; #pragma unroll
;           for (int ni = 0; ni < 4; ++ni) acc[mh * 4 + mi][ni] = mfma16(a[mi], b[ni], acc[mh * 4 + mi][ni]);
;       }
;     }
;     __syncthreads();
;   }
	v_mfma_f32_16x16x32_bf16 v[92:95], v[170:173], v[124:127], v[92:95]
	v_mfma_f32_16x16x32_bf16 v[88:91], v[170:173], v[132:135], v[88:91]
	v_mfma_f32_16x16x32_bf16 v[84:87], v[170:173], v[144:147], v[84:87]
	v_mfma_f32_16x16x32_bf16 v[80:83], v[170:173], v[128:131], v[80:83]
	ds_read_b128 v[240:243], v228 offset:6144
	ds_read_b128 v[166:169], v228 offset:7168
	s_waitcnt lgkmcnt(4)
	v_mfma_f32_16x16x32_bf16 v[76:79], v[136:139], v[124:127], v[76:79]
	s_waitcnt vmcnt(0)
	v_add_u32_e32 v231, s9, v230
	v_mfma_f32_16x16x32_bf16 v[72:75], v[136:139], v[132:135], v[72:75]
	ds_write_b128 v231, v[244:247]
	v_mfma_f32_16x16x32_bf16 v[68:71], v[136:139], v[144:147], v[68:71]
	ds_write_b128 v231, v[252:255] offset:4096
	v_mfma_f32_16x16x32_bf16 v[64:67], v[136:139], v[128:131], v[64:67]
	ds_write_b128 v231, v[208:211] offset:8192
	s_waitcnt lgkmcnt(6)
	v_mfma_f32_16x16x32_bf16 v[60:63], v[232:235], v[124:127], v[60:63]
	ds_write_b128 v231, v[212:215] offset:12288
	v_mfma_f32_16x16x32_bf16 v[56:59], v[232:235], v[132:135], v[56:59]
	ds_write_b128 v231, v[216:219] offset:16384
	v_mfma_f32_16x16x32_bf16 v[52:55], v[232:235], v[144:147], v[52:55]
	ds_write_b128 v231, v[220:223] offset:20480
	v_mfma_f32_16x16x32_bf16 v[48:51], v[232:235], v[128:131], v[48:51]
	s_add_i32 s9, s8, s5
	s_add_i32 s8, s8, 0x6000
	s_waitcnt lgkmcnt(8)
	v_mfma_f32_16x16x32_bf16 v[44:47], v[236:239], v[124:127], v[44:47]
	s_cmp_eq_u32 s8, 0x12000
	s_cselect_b32 s8, 0, s8
	v_mfma_f32_16x16x32_bf16 v[40:43], v[236:239], v[132:135], v[40:43]
	s_add_u32 s6, s6, 64
	s_addc_u32 s7, s7, 0
	s_cmpk_lg_i32 s6, 0xf80
	v_mfma_f32_16x16x32_bf16 v[36:39], v[236:239], v[144:147], v[36:39]
	v_mfma_f32_16x16x32_bf16 v[32:35], v[236:239], v[128:131], v[32:35]
	s_waitcnt lgkmcnt(7)
	v_mfma_f32_16x16x32_bf16 v[28:31], v[240:243], v[124:127], v[28:31]
	v_mfma_f32_16x16x32_bf16 v[24:27], v[240:243], v[132:135], v[24:27]
	v_mfma_f32_16x16x32_bf16 v[20:23], v[240:243], v[144:147], v[20:23]
	v_mfma_f32_16x16x32_bf16 v[16:19], v[240:243], v[128:131], v[16:19]
	s_waitcnt lgkmcnt(6)
	s_waitcnt lgkmcnt(0)
	s_barrier
	v_mfma_f32_16x16x32_bf16 v[12:15], v[166:169], v[124:127], v[12:15]
	v_mfma_f32_16x16x32_bf16 v[8:11], v[166:169], v[132:135], v[8:11]
	v_mfma_f32_16x16x32_bf16 v[4:7], v[166:169], v[144:147], v[4:7]
	v_mfma_f32_16x16x32_bf16 v[0:3], v[166:169], v[128:131], v[0:3]
	s_cbranch_scc1 .LBB0_251
	ds_read_b128 v[124:127], v163 offset:16384
	ds_read_b128 v[128:131], v163 offset:17408
	ds_read_b128 v[132:135], v163 offset:18432
	ds_read_b128 v[136:139], v163 offset:19456
	ds_read_b128 v[140:143], v162
	ds_read_b128 v[144:147], v162 offset:1024
	ds_read_b128 v[152:155], v162 offset:2048
	ds_read_b128 v[158:161], v162 offset:3072
	s_movk_i32 s5, 0x2200
	s_waitcnt lgkmcnt(3)
	v_mfma_f32_16x16x32_bf16 v[148:151], v[140:143], v[124:127], v[148:151]
	v_mfma_f32_16x16x32_bf16 v[120:123], v[140:143], v[128:131], v[120:123]
	v_mfma_f32_16x16x32_bf16 v[116:119], v[140:143], v[132:135], v[116:119]
	v_mfma_f32_16x16x32_bf16 v[112:115], v[140:143], v[136:139], v[112:115]
	s_waitcnt lgkmcnt(2)
	v_mfma_f32_16x16x32_bf16 v[108:111], v[144:147], v[124:127], v[108:111]
	v_mfma_f32_16x16x32_bf16 v[104:107], v[144:147], v[128:131], v[104:107]
	v_mfma_f32_16x16x32_bf16 v[100:103], v[144:147], v[132:135], v[100:103]
	v_mfma_f32_16x16x32_bf16 v[96:99], v[144:147], v[136:139], v[96:99]
	s_waitcnt lgkmcnt(1)
	v_mfma_f32_16x16x32_bf16 v[92:95], v[152:155], v[124:127], v[92:95]
	v_mfma_f32_16x16x32_bf16 v[88:91], v[152:155], v[128:131], v[88:91]
	v_mfma_f32_16x16x32_bf16 v[84:87], v[152:155], v[132:135], v[84:87]
	v_mfma_f32_16x16x32_bf16 v[80:83], v[152:155], v[136:139], v[80:83]
	s_waitcnt lgkmcnt(0)
	v_mfma_f32_16x16x32_bf16 v[76:79], v[158:161], v[124:127], v[76:79]
	v_mfma_f32_16x16x32_bf16 v[72:75], v[158:161], v[128:131], v[72:75]
	v_mfma_f32_16x16x32_bf16 v[68:71], v[158:161], v[132:135], v[68:71]
	v_mfma_f32_16x16x32_bf16 v[64:67], v[158:161], v[136:139], v[64:67]
	ds_read_b128 v[140:143], v162 offset:4096
	ds_read_b128 v[144:147], v162 offset:5120
	ds_read_b128 v[152:155], v162 offset:6144
	ds_read_b128 v[158:161], v162 offset:7168
	s_waitcnt lgkmcnt(0)
	s_waitcnt vmcnt(0)
	s_barrier
	v_mfma_f32_16x16x32_bf16 v[60:63], v[140:143], v[124:127], v[60:63]
	v_mfma_f32_16x16x32_bf16 v[56:59], v[140:143], v[128:131], v[56:59]
	v_mfma_f32_16x16x32_bf16 v[52:55], v[140:143], v[132:135], v[52:55]
	v_mfma_f32_16x16x32_bf16 v[48:51], v[140:143], v[136:139], v[48:51]
	v_mfma_f32_16x16x32_bf16 v[44:47], v[144:147], v[124:127], v[44:47]
	v_mfma_f32_16x16x32_bf16 v[40:43], v[144:147], v[128:131], v[40:43]
	v_mfma_f32_16x16x32_bf16 v[36:39], v[144:147], v[132:135], v[36:39]
	v_mfma_f32_16x16x32_bf16 v[32:35], v[144:147], v[136:139], v[32:35]
	v_mfma_f32_16x16x32_bf16 v[28:31], v[152:155], v[124:127], v[28:31]
	v_mfma_f32_16x16x32_bf16 v[24:27], v[152:155], v[128:131], v[24:27]
	v_mfma_f32_16x16x32_bf16 v[20:23], v[152:155], v[132:135], v[20:23]
	v_mfma_f32_16x16x32_bf16 v[16:19], v[152:155], v[136:139], v[16:19]
	v_mfma_f32_16x16x32_bf16 v[12:15], v[158:161], v[124:127], v[12:15]
	v_mfma_f32_16x16x32_bf16 v[8:11], v[158:161], v[128:131], v[8:11]
	v_mfma_f32_16x16x32_bf16 v[4:7], v[158:161], v[132:135], v[4:7]
	v_mfma_f32_16x16x32_bf16 v[0:3], v[158:161], v[136:139], v[0:3]
	ds_read_b128 v[124:127], v163 offset:40960
	ds_read_b128 v[128:131], v163 offset:41984
	ds_read_b128 v[132:135], v163 offset:43008
	ds_read_b128 v[136:139], v163 offset:44032
	ds_read_b128 v[140:143], v162 offset:24576
	ds_read_b128 v[144:147], v162 offset:25600
	ds_read_b128 v[152:155], v162 offset:26624
	ds_read_b128 v[158:161], v162 offset:27648
	s_waitcnt lgkmcnt(3)
	v_mfma_f32_16x16x32_bf16 v[148:151], v[140:143], v[124:127], v[148:151]
	v_mfma_f32_16x16x32_bf16 v[120:123], v[140:143], v[128:131], v[120:123]
	v_mfma_f32_16x16x32_bf16 v[116:119], v[140:143], v[132:135], v[116:119]
	v_mfma_f32_16x16x32_bf16 v[112:115], v[140:143], v[136:139], v[112:115]
	s_waitcnt lgkmcnt(2)
	v_mfma_f32_16x16x32_bf16 v[108:111], v[144:147], v[124:127], v[108:111]
	v_mfma_f32_16x16x32_bf16 v[140:143], v[144:147], v[128:131], v[104:107]
	v_mfma_f32_16x16x32_bf16 v[164:167], v[144:147], v[132:135], v[100:103]
	v_mfma_f32_16x16x32_bf16 v[96:99], v[144:147], v[136:139], v[96:99]
	s_waitcnt lgkmcnt(1)
	v_mfma_f32_16x16x32_bf16 v[92:95], v[152:155], v[124:127], v[92:95]
	v_mfma_f32_16x16x32_bf16 v[88:91], v[152:155], v[128:131], v[88:91]
	v_mfma_f32_16x16x32_bf16 v[84:87], v[152:155], v[132:135], v[84:87]
	v_mfma_f32_16x16x32_bf16 v[80:83], v[152:155], v[136:139], v[80:83]
	ds_read_b128 v[100:103], v162 offset:28672
	ds_read_b128 v[104:107], v162 offset:29696
	ds_read_b128 v[144:147], v162 offset:30720
	ds_read_b128 v[152:155], v162 offset:31744
	s_waitcnt lgkmcnt(0)
	s_barrier
; DEV int TID() { int t = threadIdx.x; asm volatile("" : "+v"(t)); return t; }
; DEV void store_tile_f32_add(const f32x4 (&acc)[8][4], const float* xres, float* out, int m0, int n0, unsigned char* smem) {
;   const int tid = TID(), lane = tid & 63, wid = tid >> 6;
;   const int wr = wid >> 1, wc = wid & 1, fr = lane & 15, fq = lane >> 4;
;   float* st = (float*)(smem + wid * 8704);
;   const int chunk = lane & 15;
; #pragma unroll
;   for (int mq = 0; mq < 4; ++mq) {
; #pragma unroll
;     for (int mh = 0; mh < 2; ++mh)
; #pragma unroll
;       for (int ni = 0; ni < 4; ++ni)
; #pragma unroll
;         for (int j = 0; j < 4; ++j) st[(mh * 16 + fq * 4 + j) * 68 + ni * 16 + fr] = acc[mq * 2 + mh][ni][j];
; #pragma unroll
;     for (int itr = 0; itr < 8; ++itr) {
;       const int rl = (lane >> 4) + 4 * itr;
;       const f32x4 v = *(const f32x4*)(st + rl * 68 + chunk * 4);
;       const size_t idx = (size_t)(m0 + wr * 128 + mq * 32 + rl) * 2048 + n0 + wc * 64 + chunk * 4;
;       const f32x4 x = *(const f32x4*)(xres + idx);
;       *(f32x4*)(out + idx) = x + v;
;     }
;   }
; }
	v_mfma_f32_16x16x32_bf16 v[60:63], v[100:103], v[124:127], v[60:63]
	v_mfma_f32_16x16x32_bf16 v[56:59], v[100:103], v[128:131], v[56:59]
	v_mfma_f32_16x16x32_bf16 v[52:55], v[100:103], v[132:135], v[52:55]
	v_mfma_f32_16x16x32_bf16 v[48:51], v[100:103], v[136:139], v[48:51]
	v_mov_b32_e32 v100, v178
	s_nop 0
	v_lshrrev_b32_e32 v101, 6, v100
	v_and_b32_e32 v103, 15, v100
	v_mfma_f32_16x16x32_bf16 v[44:47], v[104:107], v[124:127], v[44:47]
	v_mul_lo_u32 v101, v101, s5
	v_bfe_u32 v102, v100, 4, 2
	v_mfma_f32_16x16x32_bf16 v[40:43], v[104:107], v[128:131], v[40:43]
	v_mfma_f32_16x16x32_bf16 v[36:39], v[104:107], v[132:135], v[36:39]
	v_mfma_f32_16x16x32_bf16 v[32:35], v[104:107], v[136:139], v[32:35]
	v_lshlrev_b32_e32 v104, 2, v103
	v_or_b32_e32 v105, v101, v104
	v_and_b32_e32 v101, 0xffffff80, v100
	v_mad_u32_u24 v107, v103, 12, v105
	v_add_u32_e32 v103, s4, v101
	v_mov_b32_e32 v101, s3
	s_movk_i32 s3, 0x440
	v_mad_u32_u24 v106, v102, s3, v105
	ds_write_b32 v106, v148
	ds_write_b32 v106, v149 offset:272
	ds_write_b32 v106, v150 offset:544
	ds_write_b32 v106, v151 offset:816
	ds_write_b32 v106, v120 offset:64
	ds_write_b32 v106, v121 offset:336
	ds_write_b32 v106, v122 offset:608
	ds_write_b32 v106, v123 offset:880
	ds_write_b32 v106, v116 offset:128
	ds_write_b32 v106, v117 offset:400
	ds_write_b32 v106, v118 offset:672
	ds_write_b32 v106, v119 offset:944
	ds_write_b32 v106, v112 offset:192
	ds_write_b32 v106, v113 offset:464
	ds_write_b32 v106, v114 offset:736
	ds_write_b32 v106, v115 offset:1008
	ds_write_b32 v106, v108 offset:4352
	ds_write_b32 v106, v109 offset:4624
	ds_write_b32 v106, v110 offset:4896
	ds_write_b32 v106, v111 offset:5168
	ds_write_b32 v106, v140 offset:4416
	ds_write_b32 v106, v141 offset:4688
	ds_write_b32 v106, v142 offset:4960
	ds_write_b32 v106, v143 offset:5232
	ds_write_b32 v106, v164 offset:4480
	ds_write_b32 v106, v165 offset:4752
	ds_write_b32 v106, v166 offset:5024
	ds_write_b32 v106, v167 offset:5296
	ds_write_b32 v106, v96 offset:4544
	ds_write_b32 v106, v97 offset:4816
	ds_write_b32 v106, v98 offset:5088
	ds_write_b32 v106, v99 offset:5360
	v_or_b32_e32 v108, v103, v102
	v_and_b32_e32 v100, 64, v100
	v_ashrrev_i32_e32 v109, 31, v108
	v_or3_b32 v100, v104, v100, s2
	v_lshlrev_b64 v[108:109], 11, v[108:109]
	v_lshl_add_u64 v[108:109], v[100:101], 0, v[108:109]
	v_lshlrev_b64 v[112:113], 2, v[108:109]
	v_lshl_add_u64 v[108:109], s[20:21], 0, v[112:113]
	global_load_dwordx4 v[108:111], v[108:109], off
	s_movk_i32 s2, 0x110
	v_mad_u32_u24 v104, v102, s2, v107
	ds_read_b128 v[96:99], v104
	v_readlane_b32 s4, v251, 7
	v_readlane_b32 s6, v251, 9
	v_readlane_b32 s7, v251, 10
	v_or_b32_e32 v105, 20, v102
	v_mfma_f32_16x16x32_bf16 v[64:67], v[158:161], v[136:139], v[64:67]
	v_readlane_b32 s5, v251, 8
	s_waitcnt vmcnt(0) lgkmcnt(0)
	v_pk_add_f32 v[98:99], v[98:99], v[110:111]
	v_pk_add_f32 v[96:97], v[96:97], v[108:109]
	v_lshl_add_u64 v[108:109], s[6:7], 0, v[112:113]
	global_store_dwordx4 v[108:109], v[96:99], off
	v_or_b32_e32 v109, 4, v102
	v_or_b32_e32 v108, 28, v102
	v_or_b32_e32 v98, v109, v103
	v_ashrrev_i32_e32 v99, 31, v98
	v_lshlrev_b64 v[98:99], 11, v[98:99]
	v_lshl_add_u64 v[98:99], v[98:99], 0, v[100:101]
	v_lshlrev_b64 v[98:99], 2, v[98:99]
	v_lshl_add_u64 v[114:115], s[20:21], 0, v[98:99]
	global_load_dwordx4 v[114:117], v[114:115], off
	v_mad_u32_u24 v96, v109, s2, v107
	ds_read_b128 v[110:113], v96
	v_lshl_add_u64 v[98:99], s[6:7], 0, v[98:99]
	v_or_b32_e32 v97, 8, v102
	v_or_b32_e32 v107, 24, v102
	v_mfma_f32_16x16x32_bf16 v[76:79], v[158:161], v[124:127], v[76:79]
	s_waitcnt vmcnt(0) lgkmcnt(0)
	v_pk_add_f32 v[112:113], v[112:113], v[116:117]
	v_pk_add_f32 v[110:111], v[110:111], v[114:115]
	global_store_dwordx4 v[98:99], v[110:113], off
	v_or_b32_e32 v98, v97, v103
	v_ashrrev_i32_e32 v99, 31, v98
	v_lshlrev_b64 v[98:99], 11, v[98:99]
	v_lshl_add_u64 v[98:99], v[98:99], 0, v[100:101]
	v_lshlrev_b64 v[98:99], 2, v[98:99]
	v_lshl_add_u64 v[114:115], s[20:21], 0, v[98:99]
	global_load_dwordx4 v[114:117], v[114:115], off
	ds_read_b128 v[110:113], v96 offset:1088
	v_lshl_add_u64 v[98:99], s[6:7], 0, v[98:99]
	v_mfma_f32_16x16x32_bf16 v[72:75], v[158:161], v[128:131], v[72:75]
	s_waitcnt vmcnt(0) lgkmcnt(0)
	v_pk_add_f32 v[112:113], v[112:113], v[116:117]
	v_pk_add_f32 v[110:111], v[110:111], v[114:115]
	global_store_dwordx4 v[98:99], v[110:113], off
	v_or_b32_e32 v98, 12, v102
	v_or_b32_e32 v114, v98, v103
	v_ashrrev_i32_e32 v115, 31, v114
	v_lshlrev_b64 v[114:115], 11, v[114:115]
	v_lshl_add_u64 v[114:115], v[114:115], 0, v[100:101]
	v_lshlrev_b64 v[118:119], 2, v[114:115]
	v_lshl_add_u64 v[114:115], s[20:21], 0, v[118:119]
	global_load_dwordx4 v[114:117], v[114:115], off
	ds_read_b128 v[110:113], v96 offset:2176
	v_or_b32_e32 v99, 16, v102
	v_mfma_f32_16x16x32_bf16 v[68:71], v[158:161], v[132:135], v[68:71]
	s_waitcnt vmcnt(0) lgkmcnt(0)
	v_pk_add_f32 v[112:113], v[112:113], v[116:117]
	v_pk_add_f32 v[110:111], v[110:111], v[114:115]
	v_lshl_add_u64 v[114:115], s[6:7], 0, v[118:119]
	global_store_dwordx4 v[114:115], v[110:113], off
	v_or_b32_e32 v114, v99, v103
	v_ashrrev_i32_e32 v115, 31, v114
	v_lshlrev_b64 v[114:115], 11, v[114:115]
	v_lshl_add_u64 v[114:115], v[114:115], 0, v[100:101]
	v_lshlrev_b64 v[118:119], 2, v[114:115]
	v_lshl_add_u64 v[114:115], s[20:21], 0, v[118:119]
	global_load_dwordx4 v[114:117], v[114:115], off
	ds_read_b128 v[110:113], v96 offset:3264
	v_mfma_f32_16x16x32_bf16 v[28:31], v[144:147], v[124:127], v[28:31]
	s_waitcnt vmcnt(0) lgkmcnt(0)
; DEV int TID() { int t = threadIdx.x; asm volatile("" : "+v"(t)); return t; }
; DEV void store_tile_f32_add(const f32x4 (&acc)[8][4], const float* xres, float* out, int m0, int n0, unsigned char* smem) {
;   const int tid = TID(), lane = tid & 63, wid = tid >> 6;
;   const int wr = wid >> 1, wc = wid & 1, fr = lane & 15, fq = lane >> 4;
;   float* st = (float*)(smem + wid * 8704);
;   const int chunk = lane & 15;
; #pragma unroll
;   for (int mq = 0; mq < 4; ++mq) {
; #pragma unroll
;     for (int mh = 0; mh < 2; ++mh)
; #pragma unroll
;       for (int ni = 0; ni < 4; ++ni)
; #pragma unroll
;         for (int j = 0; j < 4; ++j) st[(mh * 16 + fq * 4 + j) * 68 + ni * 16 + fr] = acc[mq * 2 + mh][ni][j];
; #pragma unroll
;     for (int itr = 0; itr < 8; ++itr) {
;       const int rl = (lane >> 4) + 4 * itr;
;       const f32x4 v = *(const f32x4*)(st + rl * 68 + chunk * 4);
;       const size_t idx = (size_t)(m0 + wr * 128 + mq * 32 + rl) * 2048 + n0 + wc * 64 + chunk * 4;
;       const f32x4 x = *(const f32x4*)(xres + idx);
;       *(f32x4*)(out + idx) = x + v;
;     }
;   }
; }
	v_pk_add_f32 v[112:113], v[112:113], v[116:117]
	v_pk_add_f32 v[110:111], v[110:111], v[114:115]
	v_lshl_add_u64 v[114:115], s[6:7], 0, v[118:119]
	global_store_dwordx4 v[114:115], v[110:113], off
	v_or_b32_e32 v114, v105, v103
	v_ashrrev_i32_e32 v115, 31, v114
	v_lshlrev_b64 v[114:115], 11, v[114:115]
	v_lshl_add_u64 v[114:115], v[114:115], 0, v[100:101]
	v_lshlrev_b64 v[118:119], 2, v[114:115]
	v_lshl_add_u64 v[114:115], s[20:21], 0, v[118:119]
	global_load_dwordx4 v[114:117], v[114:115], off
	ds_read_b128 v[110:113], v96 offset:4352
	v_mfma_f32_16x16x32_bf16 v[0:3], v[152:155], v[136:139], v[0:3]
	s_waitcnt vmcnt(0) lgkmcnt(0)
	v_pk_add_f32 v[112:113], v[112:113], v[116:117]
	v_pk_add_f32 v[110:111], v[110:111], v[114:115]
	v_lshl_add_u64 v[114:115], s[6:7], 0, v[118:119]
	global_store_dwordx4 v[114:115], v[110:113], off
	v_or_b32_e32 v114, v107, v103
	v_ashrrev_i32_e32 v115, 31, v114
	v_lshlrev_b64 v[114:115], 11, v[114:115]
	v_lshl_add_u64 v[114:115], v[114:115], 0, v[100:101]
	v_lshlrev_b64 v[118:119], 2, v[114:115]
	v_lshl_add_u64 v[114:115], s[20:21], 0, v[118:119]
	global_load_dwordx4 v[114:117], v[114:115], off
	ds_read_b128 v[110:113], v96 offset:5440
	v_mfma_f32_16x16x32_bf16 v[24:27], v[144:147], v[128:131], v[24:27]
	s_waitcnt vmcnt(0) lgkmcnt(0)
	v_pk_add_f32 v[112:113], v[112:113], v[116:117]
	v_pk_add_f32 v[110:111], v[110:111], v[114:115]
	v_lshl_add_u64 v[114:115], s[6:7], 0, v[118:119]
	global_store_dwordx4 v[114:115], v[110:113], off
	v_or_b32_e32 v114, v108, v103
	v_ashrrev_i32_e32 v115, 31, v114
	v_lshlrev_b64 v[114:115], 11, v[114:115]
	v_lshl_add_u64 v[114:115], v[114:115], 0, v[100:101]
	v_lshlrev_b64 v[118:119], 2, v[114:115]
	v_lshl_add_u64 v[114:115], s[20:21], 0, v[118:119]
	global_load_dwordx4 v[114:117], v[114:115], off
	ds_read_b128 v[110:113], v96 offset:6528
	v_mfma_f32_16x16x32_bf16 v[20:23], v[144:147], v[132:135], v[20:23]
	s_waitcnt vmcnt(0) lgkmcnt(0)
	v_pk_add_f32 v[112:113], v[112:113], v[116:117]
	v_pk_add_f32 v[110:111], v[110:111], v[114:115]
	v_lshl_add_u64 v[114:115], s[6:7], 0, v[118:119]
	global_store_dwordx4 v[114:115], v[110:113], off
	ds_write_b32 v106, v92
	ds_write_b32 v106, v93 offset:272
	ds_write_b32 v106, v94 offset:544
	ds_write_b32 v106, v95 offset:816
	ds_write_b32 v106, v88 offset:64
	ds_write_b32 v106, v89 offset:336
	ds_write_b32 v106, v90 offset:608
	ds_write_b32 v106, v91 offset:880
	ds_write_b32 v106, v84 offset:128
	ds_write_b32 v106, v85 offset:400
	ds_write_b32 v106, v86 offset:672
	ds_write_b32 v106, v87 offset:944
	ds_write_b32 v106, v80 offset:192
	ds_write_b32 v106, v81 offset:464
	ds_write_b32 v106, v82 offset:736
	ds_write_b32 v106, v83 offset:1008
	ds_write_b32 v106, v76 offset:4352
	ds_write_b32 v106, v77 offset:4624
	ds_write_b32 v106, v78 offset:4896
	ds_write_b32 v106, v79 offset:5168
	ds_write_b32 v106, v72 offset:4416
	ds_write_b32 v106, v73 offset:4688
	ds_write_b32 v106, v74 offset:4960
	ds_write_b32 v106, v75 offset:5232
	ds_write_b32 v106, v68 offset:4480
	ds_write_b32 v106, v69 offset:4752
	ds_write_b32 v106, v70 offset:5024
	ds_write_b32 v106, v71 offset:5296
	ds_write_b32 v106, v64 offset:4544
	ds_write_b32 v106, v65 offset:4816
	ds_write_b32 v106, v66 offset:5088
	ds_write_b32 v106, v67 offset:5360
	v_or_b32_e32 v64, 32, v103
	v_or_b32_e32 v70, v64, v102
	v_ashrrev_i32_e32 v71, 31, v70
	v_lshlrev_b64 v[70:71], 11, v[70:71]
	v_lshl_add_u64 v[70:71], v[70:71], 0, v[100:101]
	v_lshlrev_b64 v[74:75], 2, v[70:71]
	v_lshl_add_u64 v[70:71], s[20:21], 0, v[74:75]
	global_load_dwordx4 v[70:73], v[70:71], off
	ds_read_b128 v[66:69], v104
	v_mfma_f32_16x16x32_bf16 v[16:19], v[144:147], v[136:139], v[16:19]
	s_waitcnt vmcnt(0) lgkmcnt(0)
	v_pk_add_f32 v[68:69], v[68:69], v[72:73]
	v_pk_add_f32 v[66:67], v[66:67], v[70:71]
	v_lshl_add_u64 v[70:71], s[6:7], 0, v[74:75]
	global_store_dwordx4 v[70:71], v[66:69], off
	v_or_b32_e32 v70, v64, v109
	v_ashrrev_i32_e32 v71, 31, v70
	v_lshlrev_b64 v[70:71], 11, v[70:71]
	v_lshl_add_u64 v[70:71], v[70:71], 0, v[100:101]
	v_lshlrev_b64 v[74:75], 2, v[70:71]
	v_lshl_add_u64 v[70:71], s[20:21], 0, v[74:75]
	global_load_dwordx4 v[70:73], v[70:71], off
	ds_read_b128 v[66:69], v96
	v_mfma_f32_16x16x32_bf16 v[12:15], v[152:155], v[124:127], v[12:15]
	s_waitcnt vmcnt(0) lgkmcnt(0)
	v_pk_add_f32 v[68:69], v[68:69], v[72:73]
	v_pk_add_f32 v[66:67], v[66:67], v[70:71]
	v_lshl_add_u64 v[70:71], s[6:7], 0, v[74:75]
	global_store_dwordx4 v[70:71], v[66:69], off
	v_or_b32_e32 v70, v64, v97
	v_ashrrev_i32_e32 v71, 31, v70
	v_lshlrev_b64 v[70:71], 11, v[70:71]
	v_lshl_add_u64 v[70:71], v[70:71], 0, v[100:101]
	v_lshlrev_b64 v[74:75], 2, v[70:71]
	v_lshl_add_u64 v[70:71], s[20:21], 0, v[74:75]
	global_load_dwordx4 v[70:73], v[70:71], off
	ds_read_b128 v[66:69], v96 offset:1088
	v_mfma_f32_16x16x32_bf16 v[8:11], v[152:155], v[128:131], v[8:11]
	s_waitcnt vmcnt(0) lgkmcnt(0)
	v_pk_add_f32 v[68:69], v[68:69], v[72:73]
	v_pk_add_f32 v[66:67], v[66:67], v[70:71]
	v_lshl_add_u64 v[70:71], s[6:7], 0, v[74:75]
	global_store_dwordx4 v[70:71], v[66:69], off
	v_or_b32_e32 v70, v64, v98
	v_ashrrev_i32_e32 v71, 31, v70
	v_lshlrev_b64 v[70:71], 11, v[70:71]
	v_lshl_add_u64 v[70:71], v[70:71], 0, v[100:101]
	v_lshlrev_b64 v[74:75], 2, v[70:71]
	v_lshl_add_u64 v[70:71], s[20:21], 0, v[74:75]
	global_load_dwordx4 v[70:73], v[70:71], off
	ds_read_b128 v[66:69], v96 offset:2176
	v_mfma_f32_16x16x32_bf16 v[4:7], v[152:155], v[132:135], v[4:7]
	s_waitcnt vmcnt(0) lgkmcnt(0)
; DEV int TID() { int t = threadIdx.x; asm volatile("" : "+v"(t)); return t; }
; DEV void store_tile_f32_add(const f32x4 (&acc)[8][4], const float* xres, float* out, int m0, int n0, unsigned char* smem) {
;   const int tid = TID(), lane = tid & 63, wid = tid >> 6;
;   const int wr = wid >> 1, wc = wid & 1, fr = lane & 15, fq = lane >> 4;
;   float* st = (float*)(smem + wid * 8704);
;   const int chunk = lane & 15;
; #pragma unroll
;   for (int mq = 0; mq < 4; ++mq) {
; #pragma unroll
;     for (int mh = 0; mh < 2; ++mh)
; #pragma unroll
;       for (int ni = 0; ni < 4; ++ni)
; #pragma unroll
;         for (int j = 0; j < 4; ++j) st[(mh * 16 + fq * 4 + j) * 68 + ni * 16 + fr] = acc[mq * 2 + mh][ni][j];
; #pragma unroll
;     for (int itr = 0; itr < 8; ++itr) {
;       const int rl = (lane >> 4) + 4 * itr;
;       const f32x4 v = *(const f32x4*)(st + rl * 68 + chunk * 4);
;       const size_t idx = (size_t)(m0 + wr * 128 + mq * 32 + rl) * 2048 + n0 + wc * 64 + chunk * 4;
;       const f32x4 x = *(const f32x4*)(xres + idx);
;       *(f32x4*)(out + idx) = x + v;
;     }
;   }
; }
	v_pk_add_f32 v[68:69], v[68:69], v[72:73]
	v_pk_add_f32 v[66:67], v[66:67], v[70:71]
	v_lshl_add_u64 v[70:71], s[6:7], 0, v[74:75]
	global_store_dwordx4 v[70:71], v[66:69], off
	v_or_b32_e32 v70, v64, v99
	v_ashrrev_i32_e32 v71, 31, v70
	v_lshlrev_b64 v[70:71], 11, v[70:71]
	v_lshl_add_u64 v[70:71], v[70:71], 0, v[100:101]
	v_lshlrev_b64 v[74:75], 2, v[70:71]
	v_lshl_add_u64 v[70:71], s[20:21], 0, v[74:75]
	global_load_dwordx4 v[70:73], v[70:71], off
	ds_read_b128 v[66:69], v96 offset:3264
	s_waitcnt vmcnt(0) lgkmcnt(0)
	v_pk_add_f32 v[68:69], v[68:69], v[72:73]
	v_pk_add_f32 v[66:67], v[66:67], v[70:71]
	v_lshl_add_u64 v[70:71], s[6:7], 0, v[74:75]
	global_store_dwordx4 v[70:71], v[66:69], off
	v_or_b32_e32 v70, v64, v105
	v_ashrrev_i32_e32 v71, 31, v70
	v_lshlrev_b64 v[70:71], 11, v[70:71]
	v_lshl_add_u64 v[70:71], v[70:71], 0, v[100:101]
	v_lshlrev_b64 v[74:75], 2, v[70:71]
	v_lshl_add_u64 v[70:71], s[20:21], 0, v[74:75]
	global_load_dwordx4 v[70:73], v[70:71], off
	ds_read_b128 v[66:69], v96 offset:4352
	s_waitcnt vmcnt(0) lgkmcnt(0)
	v_pk_add_f32 v[68:69], v[68:69], v[72:73]
	v_pk_add_f32 v[66:67], v[66:67], v[70:71]
	v_lshl_add_u64 v[70:71], s[6:7], 0, v[74:75]
	global_store_dwordx4 v[70:71], v[66:69], off
	v_or_b32_e32 v70, v64, v107
	v_ashrrev_i32_e32 v71, 31, v70
	v_lshlrev_b64 v[70:71], 11, v[70:71]
	v_lshl_add_u64 v[70:71], v[70:71], 0, v[100:101]
	v_lshlrev_b64 v[74:75], 2, v[70:71]
	v_lshl_add_u64 v[70:71], s[20:21], 0, v[74:75]
	global_load_dwordx4 v[70:73], v[70:71], off
	ds_read_b128 v[66:69], v96 offset:5440
	v_or_b32_e32 v64, v64, v108
	v_ashrrev_i32_e32 v65, 31, v64
	v_lshlrev_b64 v[64:65], 11, v[64:65]
	v_lshl_add_u64 v[64:65], v[64:65], 0, v[100:101]
	v_lshlrev_b64 v[64:65], 2, v[64:65]
	s_waitcnt vmcnt(0) lgkmcnt(0)
	v_pk_add_f32 v[68:69], v[68:69], v[72:73]
	v_pk_add_f32 v[66:67], v[66:67], v[70:71]
	v_lshl_add_u64 v[70:71], s[6:7], 0, v[74:75]
	global_store_dwordx4 v[70:71], v[66:69], off
	v_lshl_add_u64 v[70:71], s[20:21], 0, v[64:65]
	global_load_dwordx4 v[70:73], v[70:71], off
	ds_read_b128 v[66:69], v96 offset:6528
	v_lshl_add_u64 v[64:65], s[6:7], 0, v[64:65]
	s_waitcnt vmcnt(0) lgkmcnt(0)
	v_pk_add_f32 v[68:69], v[68:69], v[72:73]
	v_pk_add_f32 v[66:67], v[66:67], v[70:71]
	global_store_dwordx4 v[64:65], v[66:69], off
	ds_write_b32 v106, v60
	ds_write_b32 v106, v61 offset:272
	ds_write_b32 v106, v62 offset:544
	ds_write_b32 v106, v63 offset:816
	ds_write_b32 v106, v56 offset:64
	ds_write_b32 v106, v57 offset:336
	ds_write_b32 v106, v58 offset:608
	ds_write_b32 v106, v59 offset:880
	ds_write_b32 v106, v52 offset:128
	ds_write_b32 v106, v53 offset:400
	ds_write_b32 v106, v54 offset:672
	ds_write_b32 v106, v55 offset:944
	ds_write_b32 v106, v48 offset:192
	ds_write_b32 v106, v49 offset:464
	ds_write_b32 v106, v50 offset:736
	ds_write_b32 v106, v51 offset:1008
	ds_write_b32 v106, v44 offset:4352
	ds_write_b32 v106, v45 offset:4624
	ds_write_b32 v106, v46 offset:4896
	ds_write_b32 v106, v47 offset:5168
	ds_write_b32 v106, v40 offset:4416
	ds_write_b32 v106, v41 offset:4688
	ds_write_b32 v106, v42 offset:4960
	ds_write_b32 v106, v43 offset:5232
	ds_write_b32 v106, v36 offset:4480
	ds_write_b32 v106, v37 offset:4752
	ds_write_b32 v106, v38 offset:5024
	ds_write_b32 v106, v39 offset:5296
	ds_write_b32 v106, v32 offset:4544
	ds_write_b32 v106, v33 offset:4816
	ds_write_b32 v106, v34 offset:5088
	ds_write_b32 v106, v35 offset:5360
	v_or_b32_e32 v32, 64, v103
	v_or_b32_e32 v38, v32, v102
	v_ashrrev_i32_e32 v39, 31, v38
	v_lshlrev_b64 v[38:39], 11, v[38:39]
	v_lshl_add_u64 v[38:39], v[38:39], 0, v[100:101]
	v_lshlrev_b64 v[42:43], 2, v[38:39]
	v_lshl_add_u64 v[38:39], s[20:21], 0, v[42:43]
	global_load_dwordx4 v[38:41], v[38:39], off
	ds_read_b128 v[34:37], v104
	s_waitcnt vmcnt(0) lgkmcnt(0)
	v_pk_add_f32 v[36:37], v[36:37], v[40:41]
	v_pk_add_f32 v[34:35], v[34:35], v[38:39]
	v_lshl_add_u64 v[38:39], s[6:7], 0, v[42:43]
	global_store_dwordx4 v[38:39], v[34:37], off
	v_or_b32_e32 v38, v32, v109
	v_ashrrev_i32_e32 v39, 31, v38
	v_lshlrev_b64 v[38:39], 11, v[38:39]
	v_lshl_add_u64 v[38:39], v[38:39], 0, v[100:101]
	v_lshlrev_b64 v[42:43], 2, v[38:39]
	v_lshl_add_u64 v[38:39], s[20:21], 0, v[42:43]
	global_load_dwordx4 v[38:41], v[38:39], off
	ds_read_b128 v[34:37], v96
	s_waitcnt vmcnt(0) lgkmcnt(0)
	v_pk_add_f32 v[36:37], v[36:37], v[40:41]
	v_pk_add_f32 v[34:35], v[34:35], v[38:39]
	v_lshl_add_u64 v[38:39], s[6:7], 0, v[42:43]
	global_store_dwordx4 v[38:39], v[34:37], off
	v_or_b32_e32 v38, v32, v97
	v_ashrrev_i32_e32 v39, 31, v38
	v_lshlrev_b64 v[38:39], 11, v[38:39]
	v_lshl_add_u64 v[38:39], v[38:39], 0, v[100:101]
	v_lshlrev_b64 v[42:43], 2, v[38:39]
	v_lshl_add_u64 v[38:39], s[20:21], 0, v[42:43]
	global_load_dwordx4 v[38:41], v[38:39], off
	ds_read_b128 v[34:37], v96 offset:1088
	s_waitcnt vmcnt(0) lgkmcnt(0)
	v_pk_add_f32 v[36:37], v[36:37], v[40:41]
	v_pk_add_f32 v[34:35], v[34:35], v[38:39]
	v_lshl_add_u64 v[38:39], s[6:7], 0, v[42:43]
	global_store_dwordx4 v[38:39], v[34:37], off
	v_or_b32_e32 v38, v32, v98
	v_ashrrev_i32_e32 v39, 31, v38
	v_lshlrev_b64 v[38:39], 11, v[38:39]
	v_lshl_add_u64 v[38:39], v[38:39], 0, v[100:101]
	v_lshlrev_b64 v[42:43], 2, v[38:39]
	v_lshl_add_u64 v[38:39], s[20:21], 0, v[42:43]
	global_load_dwordx4 v[38:41], v[38:39], off
	ds_read_b128 v[34:37], v96 offset:2176
	s_waitcnt vmcnt(0) lgkmcnt(0)
	v_pk_add_f32 v[36:37], v[36:37], v[40:41]
	v_pk_add_f32 v[34:35], v[34:35], v[38:39]
	v_lshl_add_u64 v[38:39], s[6:7], 0, v[42:43]
	global_store_dwordx4 v[38:39], v[34:37], off
	v_or_b32_e32 v38, v32, v99
	v_ashrrev_i32_e32 v39, 31, v38
	v_lshlrev_b64 v[38:39], 11, v[38:39]
	v_lshl_add_u64 v[38:39], v[38:39], 0, v[100:101]
	v_lshlrev_b64 v[42:43], 2, v[38:39]
	v_lshl_add_u64 v[38:39], s[20:21], 0, v[42:43]
	global_load_dwordx4 v[38:41], v[38:39], off
	ds_read_b128 v[34:37], v96 offset:3264
	s_waitcnt vmcnt(0) lgkmcnt(0)
; DEV int TID() { int t = threadIdx.x; asm volatile("" : "+v"(t)); return t; }
; DEV void store_tile_f32_add(const f32x4 (&acc)[8][4], const float* xres, float* out, int m0, int n0, unsigned char* smem) {
;   const int tid = TID(), lane = tid & 63, wid = tid >> 6;
;   const int wr = wid >> 1, wc = wid & 1, fr = lane & 15, fq = lane >> 4;
;   float* st = (float*)(smem + wid * 8704);
;   const int chunk = lane & 15;
; #pragma unroll
;   for (int mq = 0; mq < 4; ++mq) {
; #pragma unroll
;     for (int mh = 0; mh < 2; ++mh)
; #pragma unroll
;       for (int ni = 0; ni < 4; ++ni)
; #pragma unroll
;         for (int j = 0; j < 4; ++j) st[(mh * 16 + fq * 4 + j) * 68 + ni * 16 + fr] = acc[mq * 2 + mh][ni][j];
; #pragma unroll
;     for (int itr = 0; itr < 8; ++itr) {
;       const int rl = (lane >> 4) + 4 * itr;
;       const f32x4 v = *(const f32x4*)(st + rl * 68 + chunk * 4);
;       const size_t idx = (size_t)(m0 + wr * 128 + mq * 32 + rl) * 2048 + n0 + wc * 64 + chunk * 4;
;       const f32x4 x = *(const f32x4*)(xres + idx);
;       *(f32x4*)(out + idx) = x + v;
;     }
;   }
; }
	v_pk_add_f32 v[36:37], v[36:37], v[40:41]
	v_pk_add_f32 v[34:35], v[34:35], v[38:39]
	v_lshl_add_u64 v[38:39], s[6:7], 0, v[42:43]
	global_store_dwordx4 v[38:39], v[34:37], off
	v_or_b32_e32 v38, v32, v105
	v_ashrrev_i32_e32 v39, 31, v38
	v_lshlrev_b64 v[38:39], 11, v[38:39]
	v_lshl_add_u64 v[38:39], v[38:39], 0, v[100:101]
	v_lshlrev_b64 v[42:43], 2, v[38:39]
	v_lshl_add_u64 v[38:39], s[20:21], 0, v[42:43]
	global_load_dwordx4 v[38:41], v[38:39], off
	ds_read_b128 v[34:37], v96 offset:4352
	s_waitcnt vmcnt(0) lgkmcnt(0)
	v_pk_add_f32 v[36:37], v[36:37], v[40:41]
	v_pk_add_f32 v[34:35], v[34:35], v[38:39]
	v_lshl_add_u64 v[38:39], s[6:7], 0, v[42:43]
	global_store_dwordx4 v[38:39], v[34:37], off
	v_or_b32_e32 v38, v32, v107
	v_ashrrev_i32_e32 v39, 31, v38
	v_lshlrev_b64 v[38:39], 11, v[38:39]
	v_lshl_add_u64 v[38:39], v[38:39], 0, v[100:101]
	v_lshlrev_b64 v[42:43], 2, v[38:39]
	v_lshl_add_u64 v[38:39], s[20:21], 0, v[42:43]
	global_load_dwordx4 v[38:41], v[38:39], off
	ds_read_b128 v[34:37], v96 offset:5440
	v_or_b32_e32 v32, v32, v108
	v_ashrrev_i32_e32 v33, 31, v32
	v_lshlrev_b64 v[32:33], 11, v[32:33]
	v_lshl_add_u64 v[32:33], v[32:33], 0, v[100:101]
	v_lshlrev_b64 v[32:33], 2, v[32:33]
	s_waitcnt vmcnt(0) lgkmcnt(0)
	v_pk_add_f32 v[36:37], v[36:37], v[40:41]
	v_pk_add_f32 v[34:35], v[34:35], v[38:39]
	v_lshl_add_u64 v[38:39], s[6:7], 0, v[42:43]
	global_store_dwordx4 v[38:39], v[34:37], off
	v_lshl_add_u64 v[38:39], s[20:21], 0, v[32:33]
	global_load_dwordx4 v[38:41], v[38:39], off
	ds_read_b128 v[34:37], v96 offset:6528
	v_lshl_add_u64 v[32:33], s[6:7], 0, v[32:33]
	s_waitcnt vmcnt(0) lgkmcnt(0)
	v_pk_add_f32 v[36:37], v[36:37], v[40:41]
	v_pk_add_f32 v[34:35], v[34:35], v[38:39]
	global_store_dwordx4 v[32:33], v[34:37], off
	ds_write_b32 v106, v28
	ds_write_b32 v106, v29 offset:272
	ds_write_b32 v106, v30 offset:544
	ds_write_b32 v106, v31 offset:816
	ds_write_b32 v106, v24 offset:64
	ds_write_b32 v106, v25 offset:336
	ds_write_b32 v106, v26 offset:608
	ds_write_b32 v106, v27 offset:880
	ds_write_b32 v106, v20 offset:128
	ds_write_b32 v106, v21 offset:400
	ds_write_b32 v106, v22 offset:672
	ds_write_b32 v106, v23 offset:944
	ds_write_b32 v106, v16 offset:192
	ds_write_b32 v106, v17 offset:464
	ds_write_b32 v106, v18 offset:736
	ds_write_b32 v106, v19 offset:1008
	ds_write_b32 v106, v12 offset:4352
	ds_write_b32 v106, v13 offset:4624
	ds_write_b32 v106, v14 offset:4896
	ds_write_b32 v106, v15 offset:5168
	ds_write_b32 v106, v8 offset:4416
	ds_write_b32 v106, v9 offset:4688
	ds_write_b32 v106, v10 offset:4960
	ds_write_b32 v106, v11 offset:5232
	ds_write_b32 v106, v4 offset:4480
	ds_write_b32 v106, v5 offset:4752
	ds_write_b32 v106, v6 offset:5024
	ds_write_b32 v106, v7 offset:5296
	ds_write_b32 v106, v0 offset:4544
	ds_write_b32 v106, v1 offset:4816
	ds_write_b32 v106, v2 offset:5088
	ds_write_b32 v106, v3 offset:5360
	v_or_b32_e32 v0, 0x60, v103
	v_or_b32_e32 v6, v0, v102
	v_ashrrev_i32_e32 v7, 31, v6
	v_lshlrev_b64 v[6:7], 11, v[6:7]
	v_lshl_add_u64 v[6:7], v[6:7], 0, v[100:101]
	v_lshlrev_b64 v[10:11], 2, v[6:7]
	v_lshl_add_u64 v[6:7], s[20:21], 0, v[10:11]
	global_load_dwordx4 v[6:9], v[6:7], off
	ds_read_b128 v[2:5], v104
	s_waitcnt vmcnt(0) lgkmcnt(0)
	v_pk_add_f32 v[4:5], v[4:5], v[8:9]
	v_pk_add_f32 v[2:3], v[2:3], v[6:7]
	v_lshl_add_u64 v[6:7], s[6:7], 0, v[10:11]
	global_store_dwordx4 v[6:7], v[2:5], off
	v_or_b32_e32 v6, v0, v109
	v_ashrrev_i32_e32 v7, 31, v6
	v_lshlrev_b64 v[6:7], 11, v[6:7]
	v_lshl_add_u64 v[6:7], v[6:7], 0, v[100:101]
	v_lshlrev_b64 v[10:11], 2, v[6:7]
	v_lshl_add_u64 v[6:7], s[20:21], 0, v[10:11]
	global_load_dwordx4 v[6:9], v[6:7], off
	ds_read_b128 v[2:5], v96
	s_waitcnt vmcnt(0) lgkmcnt(0)
	v_pk_add_f32 v[4:5], v[4:5], v[8:9]
	v_pk_add_f32 v[2:3], v[2:3], v[6:7]
	v_lshl_add_u64 v[6:7], s[6:7], 0, v[10:11]
	global_store_dwordx4 v[6:7], v[2:5], off
	v_or_b32_e32 v6, v0, v97
	v_ashrrev_i32_e32 v7, 31, v6
	v_lshlrev_b64 v[6:7], 11, v[6:7]
	v_lshl_add_u64 v[6:7], v[6:7], 0, v[100:101]
	v_lshlrev_b64 v[10:11], 2, v[6:7]
	v_lshl_add_u64 v[6:7], s[20:21], 0, v[10:11]
	global_load_dwordx4 v[6:9], v[6:7], off
	ds_read_b128 v[2:5], v96 offset:1088
	s_waitcnt vmcnt(0) lgkmcnt(0)
	v_pk_add_f32 v[4:5], v[4:5], v[8:9]
	v_pk_add_f32 v[2:3], v[2:3], v[6:7]
	v_lshl_add_u64 v[6:7], s[6:7], 0, v[10:11]
	global_store_dwordx4 v[6:7], v[2:5], off
	v_or_b32_e32 v6, v0, v98
	v_ashrrev_i32_e32 v7, 31, v6
	v_lshlrev_b64 v[6:7], 11, v[6:7]
	v_lshl_add_u64 v[6:7], v[6:7], 0, v[100:101]
	v_lshlrev_b64 v[10:11], 2, v[6:7]
	v_lshl_add_u64 v[6:7], s[20:21], 0, v[10:11]
	global_load_dwordx4 v[6:9], v[6:7], off
	ds_read_b128 v[2:5], v96 offset:2176
	s_waitcnt vmcnt(0) lgkmcnt(0)
	v_pk_add_f32 v[4:5], v[4:5], v[8:9]
	v_pk_add_f32 v[2:3], v[2:3], v[6:7]
	v_lshl_add_u64 v[6:7], s[6:7], 0, v[10:11]
	global_store_dwordx4 v[6:7], v[2:5], off
	v_or_b32_e32 v6, v0, v99
	v_ashrrev_i32_e32 v7, 31, v6
	v_lshlrev_b64 v[6:7], 11, v[6:7]
	v_lshl_add_u64 v[6:7], v[6:7], 0, v[100:101]
	v_lshlrev_b64 v[10:11], 2, v[6:7]
	v_lshl_add_u64 v[6:7], s[20:21], 0, v[10:11]
	global_load_dwordx4 v[6:9], v[6:7], off
	ds_read_b128 v[2:5], v96 offset:3264
	s_waitcnt vmcnt(0) lgkmcnt(0)
	v_pk_add_f32 v[4:5], v[4:5], v[8:9]
	v_pk_add_f32 v[2:3], v[2:3], v[6:7]
	v_lshl_add_u64 v[6:7], s[6:7], 0, v[10:11]
	global_store_dwordx4 v[6:7], v[2:5], off
	v_or_b32_e32 v6, v0, v105
	v_ashrrev_i32_e32 v7, 31, v6
	v_lshlrev_b64 v[6:7], 11, v[6:7]
	v_lshl_add_u64 v[6:7], v[6:7], 0, v[100:101]
	v_lshlrev_b64 v[10:11], 2, v[6:7]
	v_lshl_add_u64 v[6:7], s[20:21], 0, v[10:11]
	global_load_dwordx4 v[6:9], v[6:7], off
	ds_read_b128 v[2:5], v96 offset:4352
	s_waitcnt vmcnt(0) lgkmcnt(0)
	v_pk_add_f32 v[4:5], v[4:5], v[8:9]
	v_pk_add_f32 v[2:3], v[2:3], v[6:7]
	v_lshl_add_u64 v[6:7], s[6:7], 0, v[10:11]
	global_store_dwordx4 v[6:7], v[2:5], off
	v_or_b32_e32 v6, v0, v107
	v_ashrrev_i32_e32 v7, 31, v6
	v_lshlrev_b64 v[6:7], 11, v[6:7]
	v_lshl_add_u64 v[6:7], v[6:7], 0, v[100:101]
	v_lshlrev_b64 v[10:11], 2, v[6:7]
	v_lshl_add_u64 v[6:7], s[20:21], 0, v[10:11]
	global_load_dwordx4 v[6:9], v[6:7], off
	ds_read_b128 v[2:5], v96 offset:5440
	v_or_b32_e32 v0, v0, v108
	v_ashrrev_i32_e32 v1, 31, v0
	v_lshlrev_b64 v[0:1], 11, v[0:1]
	v_lshl_add_u64 v[0:1], v[0:1], 0, v[100:101]
	v_lshlrev_b64 v[0:1], 2, v[0:1]
	s_waitcnt vmcnt(0) lgkmcnt(0)
	v_pk_add_f32 v[4:5], v[4:5], v[8:9]
	v_pk_add_f32 v[2:3], v[2:3], v[6:7]
	v_lshl_add_u64 v[6:7], s[6:7], 0, v[10:11]
	global_store_dwordx4 v[6:7], v[2:5], off
	v_lshl_add_u64 v[6:7], s[20:21], 0, v[0:1]
	global_load_dwordx4 v[6:9], v[6:7], off
	ds_read_b128 v[2:5], v96 offset:6528
	v_lshl_add_u64 v[0:1], s[6:7], 0, v[0:1]
	s_waitcnt vmcnt(0) lgkmcnt(0)
	v_pk_add_f32 v[4:5], v[4:5], v[8:9]
	v_pk_add_f32 v[2:3], v[2:3], v[6:7]
	global_store_dwordx4 v[0:1], v[2:5], off
	s_branch .LBB0_244

; DEV f32x4 mfma16(bf16x8 a, bf16x8 b, f32x4 c) { return __builtin_amdgcn_mfma_f32_16x16x32_bf16(a, b, c, 0, 0, 0); }
; DEV void gemm_tile(const u16* __restrict__ A, size_t lda, const u16* __restrict__ Bt, size_t ldb, int K,
;                    u16* sA, u16* sB, f32x4 (&acc)[8][4]) {
;     ...
;   for (int kt = 0; kt < nk; ++kt) {
;     const int st = kt & 1;
;     if (kt + 1 < nk) S_STORE(st ^ 1)
;     if (kt + 2 < nk) G_LOAD((kt + 2) << 5)
;     {
;       const u16* pa = sAr + st * 12288;
;       const u16* pb = sBr + st * 12288;
;       bf16x8 b[4];
; #pragma unroll
;       for (int ni = 0; ni < 4; ++ni) b[ni] = *(const bf16x8*)(pb + ni * 16 * 32);
; #pragma unroll
;       for (int mh = 0; mh < 2; ++mh) {
;         bf16x8 a[4];
; #pragma unroll
;         for (int mi = 0; mi < 4; ++mi) a[mi] = *(const bf16x8*)(pa + (mh * 64 + mi * 16) * 32);
; #pragma unroll
;         for (int mi = 0; mi < 4; ++mi)
; #pragma unroll
;           for (int ni = 0; ni < 4; ++ni) acc[mh * 4 + mi][ni] = mfma16(a[mi], b[ni], acc[mh * 4 + mi][ni]);
;       }
;     }
;     __syncthreads();
.LBB0_414:
	v_add_u32_e32 v229, s8, v163
	v_add_u32_e32 v228, s8, v162
	ds_read_b128 v[116:119], v229 offset:16384
	ds_read_b128 v[166:169], v228
	ds_read_b128 v[128:131], v229 offset:17408
	ds_read_b128 v[140:143], v229 offset:18432
	ds_read_b128 v[120:123], v229 offset:19456
	ds_read_b128 v[152:155], v228 offset:1024
	ds_read_b128 v[170:173], v228 offset:2048
	ds_read_b128 v[132:135], v228 offset:3072
	s_waitcnt lgkmcnt(6)
	v_mfma_f32_16x16x32_bf16 v[148:151], v[166:169], v[116:119], v[148:151]
	s_add_i32 m0, s9, 0x0
	s_waitcnt lgkmcnt(5)
	v_mfma_f32_16x16x32_bf16 v[144:147], v[166:169], v[128:131], v[144:147]
	global_load_lds_dwordx4 v[136:137], off
	v_lshl_add_u64 v[136:137], v[136:137], 0, 64
	global_load_dwordx4 v[244:247], v[136:137], off
	v_lshl_add_u64 v[136:137], v[136:137], 0, 64
	s_waitcnt lgkmcnt(4)
	v_mfma_f32_16x16x32_bf16 v[124:127], v[166:169], v[140:143], v[124:127]
	s_add_i32 m0, s9, 0x1000
	s_waitcnt lgkmcnt(3)
	v_mfma_f32_16x16x32_bf16 v[112:115], v[166:169], v[120:123], v[112:115]
	ds_read_b128 v[232:235], v228 offset:4096
	ds_read_b128 v[236:239], v228 offset:5120
	s_waitcnt lgkmcnt(4)
	v_mfma_f32_16x16x32_bf16 v[108:111], v[152:155], v[116:119], v[108:111]
	global_load_lds_dwordx4 v[138:139], off
	v_lshl_add_u64 v[138:139], v[138:139], 0, 64
	global_load_dwordx4 v[252:255], v[138:139], off
	v_lshl_add_u64 v[138:139], v[138:139], 0, 64
	v_mfma_f32_16x16x32_bf16 v[104:107], v[152:155], v[128:131], v[104:107]
	s_add_i32 m0, s9, 0x2000
	v_mfma_f32_16x16x32_bf16 v[100:103], v[152:155], v[140:143], v[100:103]
	global_load_lds_dwordx4 v[174:175], off
	v_lshl_add_u64 v[174:175], v[174:175], 0, 64
	global_load_dwordx4 v[208:211], v[174:175], off
	v_lshl_add_u64 v[174:175], v[174:175], 0, 64
	v_mfma_f32_16x16x32_bf16 v[96:99], v[152:155], v[120:123], v[96:99]
	s_add_i32 m0, s9, 0x3000
	s_waitcnt lgkmcnt(3)
	v_mfma_f32_16x16x32_bf16 v[92:95], v[170:173], v[116:119], v[92:95]
	global_load_lds_dwordx4 v[176:177], off
	v_lshl_add_u64 v[176:177], v[176:177], 0, 64
	global_load_dwordx4 v[212:215], v[176:177], off
	v_lshl_add_u64 v[176:177], v[176:177], 0, 64
	v_mfma_f32_16x16x32_bf16 v[88:91], v[170:173], v[128:131], v[88:91]
	s_add_i32 m0, s9, 0x4000
	v_mfma_f32_16x16x32_bf16 v[84:87], v[170:173], v[140:143], v[84:87]
	global_load_lds_dwordx4 v[186:187], off
	v_lshl_add_u64 v[186:187], v[186:187], 0, 64
	global_load_dwordx4 v[216:219], v[186:187], off
	v_lshl_add_u64 v[186:187], v[186:187], 0, 64
	v_mfma_f32_16x16x32_bf16 v[80:83], v[170:173], v[120:123], v[80:83]
	ds_read_b128 v[240:243], v228 offset:6144
	ds_read_b128 v[166:169], v228 offset:7168
	s_waitcnt lgkmcnt(4)
	v_mfma_f32_16x16x32_bf16 v[76:79], v[132:135], v[116:119], v[76:79]
	s_add_i32 m0, s9, 0x5000
	v_mfma_f32_16x16x32_bf16 v[72:75], v[132:135], v[128:131], v[72:75]
	global_load_lds_dwordx4 v[188:189], off
	v_lshl_add_u64 v[188:189], v[188:189], 0, 64
	global_load_dwordx4 v[220:223], v[188:189], off
	v_lshl_add_u64 v[188:189], v[188:189], 0, 64
	v_mfma_f32_16x16x32_bf16 v[68:71], v[132:135], v[140:143], v[68:71]
	s_add_i32 s9, s8, s5
	s_add_i32 s8, s8, 0x6000
	v_mfma_f32_16x16x32_bf16 v[64:67], v[132:135], v[120:123], v[64:67]
	s_cmp_eq_u32 s8, 0x12000
	s_cselect_b32 s8, 0, s8
	s_waitcnt lgkmcnt(3)
	v_mfma_f32_16x16x32_bf16 v[60:63], v[232:235], v[116:119], v[60:63]
	s_add_u32 s6, s6, 64
	s_addc_u32 s7, s7, 0
	s_cmpk_lg_i32 s6, 0xf80
	v_mfma_f32_16x16x32_bf16 v[56:59], v[232:235], v[128:131], v[56:59]
	v_mfma_f32_16x16x32_bf16 v[52:55], v[232:235], v[140:143], v[52:55]
	v_mfma_f32_16x16x32_bf16 v[48:51], v[232:235], v[120:123], v[48:51]
	s_waitcnt lgkmcnt(2)
	v_mfma_f32_16x16x32_bf16 v[44:47], v[236:239], v[116:119], v[44:47]
	v_mfma_f32_16x16x32_bf16 v[40:43], v[236:239], v[128:131], v[40:43]
	v_mfma_f32_16x16x32_bf16 v[36:39], v[236:239], v[140:143], v[36:39]
	v_mfma_f32_16x16x32_bf16 v[32:35], v[236:239], v[120:123], v[32:35]
	s_waitcnt lgkmcnt(1)
	v_mfma_f32_16x16x32_bf16 v[28:31], v[240:243], v[116:119], v[28:31]
	v_mfma_f32_16x16x32_bf16 v[24:27], v[240:243], v[128:131], v[24:27]
	v_mfma_f32_16x16x32_bf16 v[20:23], v[240:243], v[140:143], v[20:23]
	v_mfma_f32_16x16x32_bf16 v[16:19], v[240:243], v[120:123], v[16:19]
	s_waitcnt lgkmcnt(0)
	s_waitcnt vmcnt(12)
	s_barrier
	v_mfma_f32_16x16x32_bf16 v[12:15], v[166:169], v[116:119], v[12:15]
	v_mfma_f32_16x16x32_bf16 v[8:11], v[166:169], v[128:131], v[8:11]
	v_mfma_f32_16x16x32_bf16 v[4:7], v[166:169], v[140:143], v[4:7]
	v_mfma_f32_16x16x32_bf16 v[0:3], v[166:169], v[120:123], v[0:3]
	v_add_u32_e32 v229, s8, v163
	v_add_u32_e32 v228, s8, v162
	ds_read_b128 v[116:119], v229 offset:16384
	ds_read_b128 v[166:169], v228
	ds_read_b128 v[128:131], v229 offset:17408
	ds_read_b128 v[140:143], v229 offset:18432
	ds_read_b128 v[120:123], v229 offset:19456
	ds_read_b128 v[152:155], v228 offset:1024
	ds_read_b128 v[170:173], v228 offset:2048
	ds_read_b128 v[132:135], v228 offset:3072
	s_waitcnt lgkmcnt(6)
	v_mfma_f32_16x16x32_bf16 v[148:151], v[166:169], v[116:119], v[148:151]
	s_waitcnt lgkmcnt(5)
	v_mfma_f32_16x16x32_bf16 v[144:147], v[166:169], v[128:131], v[144:147]
	s_waitcnt lgkmcnt(4)
	v_mfma_f32_16x16x32_bf16 v[124:127], v[166:169], v[140:143], v[124:127]
	s_waitcnt lgkmcnt(3)
	v_mfma_f32_16x16x32_bf16 v[112:115], v[166:169], v[120:123], v[112:115]
	ds_read_b128 v[232:235], v228 offset:4096
	ds_read_b128 v[236:239], v228 offset:5120
	s_waitcnt lgkmcnt(4)
	v_mfma_f32_16x16x32_bf16 v[108:111], v[152:155], v[116:119], v[108:111]
	v_mfma_f32_16x16x32_bf16 v[104:107], v[152:155], v[128:131], v[104:107]
	v_mfma_f32_16x16x32_bf16 v[100:103], v[152:155], v[140:143], v[100:103]
	v_mfma_f32_16x16x32_bf16 v[96:99], v[152:155], v[120:123], v[96:99]
	s_waitcnt lgkmcnt(3)
; DEV f32x4 mfma16(bf16x8 a, bf16x8 b, f32x4 c) { return __builtin_amdgcn_mfma_f32_16x16x32_bf16(a, b, c, 0, 0, 0); }
; DEV void gemm_tile(const u16* __restrict__ A, size_t lda, const u16* __restrict__ Bt, size_t ldb, int K,
;                    u16* sA, u16* sB, f32x4 (&acc)[8][4]) {
;     ...
;   for (int kt = 0; kt < nk; ++kt) {
;     const int st = kt & 1;
;     if (kt + 1 < nk) S_STORE(st ^ 1)
;     if (kt + 2 < nk) G_LOAD((kt + 2) << 5)
;     {
;       const u16* pa = sAr + st * 12288;
;       const u16* pb = sBr + st * 12288;
;       bf16x8 b[4];
; #pragma unroll
;       for (int ni = 0; ni < 4; ++ni) b[ni] = *(const bf16x8*)(pb + ni * 16 * 32);
; #pragma unroll
;       for (int mh = 0; mh < 2; ++mh) {
;         bf16x8 a[4];
; #pragma unroll
;         for (int mi = 0; mi < 4; ++mi) a[mi] = *(const bf16x8*)(pa + (mh * 64 + mi * 16) * 32);
; #pragma unroll
;         for (int mi = 0; mi < 4; ++mi)
; #pragma unroll
;           for (int ni = 0; ni < 4; ++ni) acc[mh * 4 + mi][ni] = mfma16(a[mi], b[ni], acc[mh * 4 + mi][ni]);
;       }
;     }
;     __syncthreads();
	v_mfma_f32_16x16x32_bf16 v[92:95], v[170:173], v[116:119], v[92:95]
	v_mfma_f32_16x16x32_bf16 v[88:91], v[170:173], v[128:131], v[88:91]
	v_mfma_f32_16x16x32_bf16 v[84:87], v[170:173], v[140:143], v[84:87]
	v_mfma_f32_16x16x32_bf16 v[80:83], v[170:173], v[120:123], v[80:83]
	ds_read_b128 v[240:243], v228 offset:6144
	ds_read_b128 v[166:169], v228 offset:7168
	s_waitcnt lgkmcnt(4)
	v_mfma_f32_16x16x32_bf16 v[76:79], v[132:135], v[116:119], v[76:79]
	s_waitcnt vmcnt(0)
	v_add_u32_e32 v231, s9, v230
	v_mfma_f32_16x16x32_bf16 v[72:75], v[132:135], v[128:131], v[72:75]
	ds_write_b128 v231, v[244:247]
	v_mfma_f32_16x16x32_bf16 v[68:71], v[132:135], v[140:143], v[68:71]
	ds_write_b128 v231, v[252:255] offset:4096
	v_mfma_f32_16x16x32_bf16 v[64:67], v[132:135], v[120:123], v[64:67]
	ds_write_b128 v231, v[208:211] offset:8192
	s_waitcnt lgkmcnt(6)
	v_mfma_f32_16x16x32_bf16 v[60:63], v[232:235], v[116:119], v[60:63]
	ds_write_b128 v231, v[212:215] offset:12288
	v_mfma_f32_16x16x32_bf16 v[56:59], v[232:235], v[128:131], v[56:59]
	ds_write_b128 v231, v[216:219] offset:16384
	v_mfma_f32_16x16x32_bf16 v[52:55], v[232:235], v[140:143], v[52:55]
	ds_write_b128 v231, v[220:223] offset:20480
	v_mfma_f32_16x16x32_bf16 v[48:51], v[232:235], v[120:123], v[48:51]
	s_add_i32 s9, s8, s5
	s_add_i32 s8, s8, 0x6000
	s_waitcnt lgkmcnt(8)
	v_mfma_f32_16x16x32_bf16 v[44:47], v[236:239], v[116:119], v[44:47]
	s_cmp_eq_u32 s8, 0x12000
	s_cselect_b32 s8, 0, s8
	v_mfma_f32_16x16x32_bf16 v[40:43], v[236:239], v[128:131], v[40:43]
	s_add_u32 s6, s6, 64
	s_addc_u32 s7, s7, 0
	s_cmpk_lg_i32 s6, 0xf80
	v_mfma_f32_16x16x32_bf16 v[36:39], v[236:239], v[140:143], v[36:39]
	v_mfma_f32_16x16x32_bf16 v[32:35], v[236:239], v[120:123], v[32:35]
	s_waitcnt lgkmcnt(7)
	v_mfma_f32_16x16x32_bf16 v[28:31], v[240:243], v[116:119], v[28:31]
	v_mfma_f32_16x16x32_bf16 v[24:27], v[240:243], v[128:131], v[24:27]
	v_mfma_f32_16x16x32_bf16 v[20:23], v[240:243], v[140:143], v[20:23]
	v_mfma_f32_16x16x32_bf16 v[16:19], v[240:243], v[120:123], v[16:19]
	s_waitcnt lgkmcnt(6)
	s_waitcnt lgkmcnt(0)
	s_barrier
	v_mfma_f32_16x16x32_bf16 v[12:15], v[166:169], v[116:119], v[12:15]
	v_mfma_f32_16x16x32_bf16 v[8:11], v[166:169], v[128:131], v[8:11]
	v_mfma_f32_16x16x32_bf16 v[4:7], v[166:169], v[140:143], v[4:7]
	v_mfma_f32_16x16x32_bf16 v[0:3], v[166:169], v[120:123], v[0:3]
	s_cbranch_scc1 .LBB0_414
	ds_read_b128 v[116:119], v163 offset:16384
	ds_read_b128 v[120:123], v163 offset:17408
	ds_read_b128 v[128:131], v163 offset:18432
	ds_read_b128 v[132:135], v163 offset:19456
	ds_read_b128 v[136:139], v162
	ds_read_b128 v[140:143], v162 offset:1024
	ds_read_b128 v[152:155], v162 offset:2048
	ds_read_b128 v[158:161], v162 offset:3072
	s_movk_i32 s5, 0xff9
	s_waitcnt lgkmcnt(3)
	v_mfma_f32_16x16x32_bf16 v[148:151], v[136:139], v[116:119], v[148:151]
	v_mfma_f32_16x16x32_bf16 v[144:147], v[136:139], v[120:123], v[144:147]
	v_mfma_f32_16x16x32_bf16 v[164:167], v[136:139], v[128:131], v[124:127]
	v_mfma_f32_16x16x32_bf16 v[112:115], v[136:139], v[132:135], v[112:115]
	s_waitcnt lgkmcnt(2)
	v_mfma_f32_16x16x32_bf16 v[108:111], v[140:143], v[116:119], v[108:111]
	v_mfma_f32_16x16x32_bf16 v[104:107], v[140:143], v[120:123], v[104:107]
	v_mfma_f32_16x16x32_bf16 v[100:103], v[140:143], v[128:131], v[100:103]
	v_mfma_f32_16x16x32_bf16 v[96:99], v[140:143], v[132:135], v[96:99]
	s_waitcnt lgkmcnt(1)
	v_mfma_f32_16x16x32_bf16 v[92:95], v[152:155], v[116:119], v[92:95]
	v_mfma_f32_16x16x32_bf16 v[88:91], v[152:155], v[120:123], v[88:91]
	v_mfma_f32_16x16x32_bf16 v[84:87], v[152:155], v[128:131], v[84:87]
	v_mfma_f32_16x16x32_bf16 v[80:83], v[152:155], v[132:135], v[80:83]
	ds_read_b128 v[124:127], v162 offset:4096
	ds_read_b128 v[136:139], v162 offset:5120
	ds_read_b128 v[140:143], v162 offset:6144
	ds_read_b128 v[152:155], v162 offset:7168
	s_waitcnt lgkmcnt(0)
	s_waitcnt vmcnt(0)
	s_barrier
	v_mfma_f32_16x16x32_bf16 v[76:79], v[158:161], v[116:119], v[76:79]
	v_mfma_f32_16x16x32_bf16 v[72:75], v[158:161], v[120:123], v[72:75]
	v_mfma_f32_16x16x32_bf16 v[68:71], v[158:161], v[128:131], v[68:71]
	v_mfma_f32_16x16x32_bf16 v[64:67], v[158:161], v[132:135], v[64:67]
	v_mfma_f32_16x16x32_bf16 v[52:55], v[124:127], v[128:131], v[52:55]
	v_mfma_f32_16x16x32_bf16 v[48:51], v[124:127], v[132:135], v[48:51]
	v_mfma_f32_16x16x32_bf16 v[44:47], v[136:139], v[116:119], v[44:47]
	v_mfma_f32_16x16x32_bf16 v[40:43], v[136:139], v[120:123], v[40:43]
	v_mfma_f32_16x16x32_bf16 v[36:39], v[136:139], v[128:131], v[36:39]
	v_mfma_f32_16x16x32_bf16 v[32:35], v[136:139], v[132:135], v[32:35]
	v_mfma_f32_16x16x32_bf16 v[28:31], v[140:143], v[116:119], v[28:31]
	v_mfma_f32_16x16x32_bf16 v[24:27], v[140:143], v[120:123], v[24:27]
	v_mfma_f32_16x16x32_bf16 v[20:23], v[140:143], v[128:131], v[20:23]
	v_mfma_f32_16x16x32_bf16 v[16:19], v[140:143], v[132:135], v[16:19]
	v_mfma_f32_16x16x32_bf16 v[12:15], v[152:155], v[116:119], v[12:15]
	v_mfma_f32_16x16x32_bf16 v[8:11], v[152:155], v[120:123], v[8:11]
	v_mfma_f32_16x16x32_bf16 v[4:7], v[152:155], v[128:131], v[4:7]
	v_mfma_f32_16x16x32_bf16 v[0:3], v[152:155], v[132:135], v[0:3]
	ds_read_b128 v[128:131], v163 offset:40960
	ds_read_b128 v[132:135], v163 offset:41984
	ds_read_b128 v[136:139], v163 offset:43008
	ds_read_b128 v[140:143], v163 offset:44032
	ds_read_b128 v[152:155], v162 offset:24576
	ds_read_b128 v[158:161], v162 offset:25600
	ds_read_b128 v[168:171], v162 offset:26624
	ds_read_b128 v[172:175], v162 offset:27648
	v_mfma_f32_16x16x32_bf16 v[60:63], v[124:127], v[116:119], v[60:63]
	v_mfma_f32_16x16x32_bf16 v[56:59], v[124:127], v[120:123], v[56:59]
	s_waitcnt lgkmcnt(3)
	v_mfma_f32_16x16x32_bf16 v[124:127], v[152:155], v[128:131], v[148:151]
	v_mfma_f32_16x16x32_bf16 v[120:123], v[152:155], v[132:135], v[144:147]
	v_mfma_f32_16x16x32_bf16 v[116:119], v[152:155], v[136:139], v[164:167]
	v_mfma_f32_16x16x32_bf16 v[112:115], v[152:155], v[140:143], v[112:115]
	s_waitcnt lgkmcnt(2)
	v_mfma_f32_16x16x32_bf16 v[108:111], v[158:161], v[128:131], v[108:111]
	v_mfma_f32_16x16x32_bf16 v[104:107], v[158:161], v[132:135], v[104:107]
	v_mfma_f32_16x16x32_bf16 v[100:103], v[158:161], v[136:139], v[100:103]
	v_mfma_f32_16x16x32_bf16 v[96:99], v[158:161], v[140:143], v[96:99]
	ds_read_b128 v[144:147], v162 offset:28672
	ds_read_b128 v[148:151], v162 offset:29696
	ds_read_b128 v[152:155], v162 offset:30720
	ds_read_b128 v[158:161], v162 offset:31744
	s_waitcnt lgkmcnt(0)
	s_barrier
; DEV int TID() { int t = threadIdx.x; asm volatile("" : "+v"(t)); return t; }
; DEV f32x4 mfma16(bf16x8 a, bf16x8 b, f32x4 c) { return __builtin_amdgcn_mfma_f32_16x16x32_bf16(a, b, c, 0, 0, 0); }
; DEV void gemm_tile(const u16* __restrict__ A, size_t lda, const u16* __restrict__ Bt, size_t ldb, int K,
;                    u16* sA, u16* sB, f32x4 (&acc)[8][4]) {
;     ...
;         for (int mi = 0; mi < 4; ++mi) a[mi] = *(const bf16x8*)(pa + (mh * 64 + mi * 16) * 32);
; #pragma unroll
;         for (int mi = 0; mi < 4; ++mi)
; #pragma unroll
;           for (int ni = 0; ni < 4; ++ni) acc[mh * 4 + mi][ni] = mfma16(a[mi], b[ni], acc[mh * 4 + mi][ni]);
; DEV void store_tile_bf16(const f32x4 (&acc)[8][4], u16* __restrict__ OUT, size_t ld, int m0, int n0, int ncols,
;                          unsigned char* smem) {
;   const int tid = TID(), lane = tid & 63, wid = tid >> 6;
;   const int wr = wid >> 1, wc = wid & 1, fr = lane & 15, fq = lane >> 4;
;   u16* st = (u16*)(smem + wid * 9216);
; #pragma unroll
;   for (int mh = 0; mh < 2; ++mh) {
; #pragma unroll
;     for (int mi = 0; mi < 4; ++mi)
; #pragma unroll
;       for (int ni = 0; ni < 4; ++ni)
; #pragma unroll
;         for (int j = 0; j < 4; ++j) st[(mi * 16 + fq * 4 + j) * 72 + ni * 16 + fr] = f2bf(acc[mh * 4 + mi][ni][j]);
;     const int chunk = lane & 7;
;     const int c0 = n0 + wc * 64 + chunk * 8;
; #pragma unroll
;     for (int itr = 0; itr < 8; ++itr) {
;       const int rl = (lane >> 3) + 8 * itr;
;       const u32x4 v = *(const u32x4*)(st + rl * 72 + chunk * 8);
;       if (c0 + 8 <= ncols) *(u32x4*)(OUT + (size_t)(m0 + wr * 128 + mh * 64 + rl) * ld + c0) = v;
;     }
;   }
; }
	v_mfma_f32_16x16x32_bf16 v[92:95], v[168:171], v[128:131], v[92:95]
	v_mfma_f32_16x16x32_bf16 v[76:79], v[172:175], v[128:131], v[76:79]
	v_mfma_f32_16x16x32_bf16 v[60:63], v[144:147], v[128:131], v[60:63]
	v_mfma_f32_16x16x32_bf16 v[44:47], v[148:151], v[128:131], v[44:47]
	v_mfma_f32_16x16x32_bf16 v[28:31], v[152:155], v[128:131], v[28:31]
	v_mfma_f32_16x16x32_bf16 v[12:15], v[158:161], v[128:131], v[12:15]
	v_mov_b32_e32 v129, v178
	s_nop 0
	v_lshrrev_b32_e32 v128, 6, v129
	v_mfma_f32_16x16x32_bf16 v[88:91], v[168:171], v[132:135], v[88:91]
	v_mul_lo_u32 v131, v128, s75
	v_lshrrev_b32_e32 v128, 2, v129
	v_and_b32_e32 v130, 15, v129
	v_mfma_f32_16x16x32_bf16 v[72:75], v[172:175], v[132:135], v[72:75]
	v_lshl_or_b32 v130, v130, 1, v131
	v_mfma_f32_16x16x32_bf16 v[56:59], v[144:147], v[132:135], v[56:59]
	v_mfma_f32_16x16x32_bf16 v[40:43], v[148:151], v[132:135], v[40:43]
	v_mfma_f32_16x16x32_bf16 v[24:27], v[152:155], v[132:135], v[24:27]
	v_mfma_f32_16x16x32_bf16 v[8:11], v[158:161], v[132:135], v[8:11]
	v_lshlrev_b32_e32 v133, 3, v129
	v_and_b32_e32 v132, 12, v128
	v_and_b32_e32 v128, 64, v129
	v_and_b32_e32 v133, 56, v133
	v_or3_b32 v128, v128, s14, v133
	v_lshl_or_b32 v131, v133, 1, v131
	v_bfe_u32 v133, v129, 3, 3
	v_and_b32_e32 v129, 0xffffff80, v129
	v_add_u32_e32 v134, s4, v129
	v_bfe_u32 v135, v124, 16, 1
	s_movk_i32 s4, 0x90
	v_add3_u32 v135, v124, v135, s71
	v_mad_u32_u24 v124, v132, s4, v130
	v_bfe_u32 v130, v125, 16, 1
	v_add3_u32 v125, v125, v130, s71
	ds_write_b16_d16_hi v124, v125 offset:144
	v_bfe_u32 v125, v126, 16, 1
	v_add3_u32 v125, v126, v125, s71
	ds_write_b16_d16_hi v124, v125 offset:288
	v_bfe_u32 v125, v127, 16, 1
	v_add3_u32 v125, v127, v125, s71
	ds_write_b16_d16_hi v124, v125 offset:432
	v_bfe_u32 v125, v120, 16, 1
	v_add3_u32 v120, v120, v125, s71
	ds_write_b16_d16_hi v124, v120 offset:32
	v_bfe_u32 v120, v121, 16, 1
	v_add3_u32 v120, v121, v120, s71
	ds_write_b16_d16_hi v124, v120 offset:176
	v_bfe_u32 v120, v122, 16, 1
	v_add3_u32 v120, v122, v120, s71
	ds_write_b16_d16_hi v124, v120 offset:320
	v_bfe_u32 v120, v123, 16, 1
	v_add3_u32 v120, v123, v120, s71
	ds_write_b16_d16_hi v124, v120 offset:464
	v_bfe_u32 v120, v116, 16, 1
	v_add3_u32 v116, v116, v120, s71
	ds_write_b16_d16_hi v124, v116 offset:64
	v_bfe_u32 v116, v117, 16, 1
	v_add3_u32 v116, v117, v116, s71
	ds_write_b16_d16_hi v124, v116 offset:208
	v_bfe_u32 v116, v118, 16, 1
	v_add3_u32 v116, v118, v116, s71
	ds_write_b16_d16_hi v124, v116 offset:352
	v_bfe_u32 v116, v119, 16, 1
	v_add3_u32 v116, v119, v116, s71
	ds_write_b16_d16_hi v124, v116 offset:496
	v_bfe_u32 v116, v112, 16, 1
	v_add3_u32 v112, v112, v116, s71
	ds_write_b16_d16_hi v124, v112 offset:96
	v_bfe_u32 v112, v113, 16, 1
	v_add3_u32 v112, v113, v112, s71
	ds_write_b16_d16_hi v124, v112 offset:240
	v_bfe_u32 v112, v114, 16, 1
	v_add3_u32 v112, v114, v112, s71
	ds_write_b16_d16_hi v124, v112 offset:384
	v_bfe_u32 v112, v115, 16, 1
	v_add3_u32 v112, v115, v112, s71
	ds_write_b16_d16_hi v124, v112 offset:528
	v_bfe_u32 v112, v108, 16, 1
	v_add3_u32 v108, v108, v112, s71
	ds_write_b16_d16_hi v124, v108 offset:2304
	v_bfe_u32 v108, v109, 16, 1
	v_add3_u32 v108, v109, v108, s71
	ds_write_b16_d16_hi v124, v108 offset:2448
	v_bfe_u32 v108, v110, 16, 1
	v_add3_u32 v108, v110, v108, s71
	ds_write_b16_d16_hi v124, v108 offset:2592
	v_bfe_u32 v108, v111, 16, 1
	v_add3_u32 v108, v111, v108, s71
	ds_write_b16_d16_hi v124, v108 offset:2736
	v_bfe_u32 v108, v104, 16, 1
	v_add3_u32 v104, v104, v108, s71
	ds_write_b16_d16_hi v124, v104 offset:2336
	v_bfe_u32 v104, v105, 16, 1
	v_add3_u32 v104, v105, v104, s71
	ds_write_b16_d16_hi v124, v104 offset:2480
	v_bfe_u32 v104, v106, 16, 1
	v_add3_u32 v104, v106, v104, s71
	ds_write_b16_d16_hi v124, v104 offset:2624
	v_bfe_u32 v104, v107, 16, 1
	v_add3_u32 v104, v107, v104, s71
	ds_write_b16_d16_hi v124, v104 offset:2768
	v_bfe_u32 v104, v100, 16, 1
	v_add3_u32 v100, v100, v104, s71
	ds_write_b16_d16_hi v124, v100 offset:2368
	v_bfe_u32 v100, v101, 16, 1
	v_add3_u32 v100, v101, v100, s71
	ds_write_b16_d16_hi v124, v100 offset:2512
	v_bfe_u32 v100, v102, 16, 1
	v_add3_u32 v100, v102, v100, s71
	ds_write_b16_d16_hi v124, v100 offset:2656
	v_bfe_u32 v100, v103, 16, 1
	v_add3_u32 v100, v103, v100, s71
	ds_write_b16_d16_hi v124, v100 offset:2800
	v_bfe_u32 v100, v96, 16, 1
	v_add3_u32 v96, v96, v100, s71
	ds_write_b16_d16_hi v124, v96 offset:2400
	v_bfe_u32 v96, v97, 16, 1
	v_add3_u32 v96, v97, v96, s71
	ds_write_b16_d16_hi v124, v96 offset:2544
	v_bfe_u32 v96, v98, 16, 1
	v_add3_u32 v96, v98, v96, s71
	ds_write_b16_d16_hi v124, v96 offset:2688
	v_bfe_u32 v96, v99, 16, 1
	v_add3_u32 v96, v99, v96, s71
	ds_write_b16_d16_hi v124, v96 offset:2832
	v_bfe_u32 v96, v92, 16, 1
	v_add3_u32 v92, v92, v96, s71
	ds_write_b16_d16_hi v124, v92 offset:4608
	v_bfe_u32 v92, v93, 16, 1
	v_add3_u32 v92, v93, v92, s71
	ds_write_b16_d16_hi v124, v92 offset:4752
	v_bfe_u32 v92, v94, 16, 1
	v_add3_u32 v92, v94, v92, s71
	ds_write_b16_d16_hi v124, v92 offset:4896
	v_bfe_u32 v92, v95, 16, 1
	v_add3_u32 v92, v95, v92, s71
	ds_write_b16_d16_hi v124, v92 offset:5040
	v_bfe_u32 v92, v88, 16, 1
	v_add3_u32 v88, v88, v92, s71
	ds_write_b16_d16_hi v124, v88 offset:4640
	v_bfe_u32 v88, v89, 16, 1
	v_add3_u32 v88, v89, v88, s71
	v_mfma_f32_16x16x32_bf16 v[84:87], v[168:171], v[136:139], v[84:87]
	ds_write_b16_d16_hi v124, v88 offset:4784
	v_bfe_u32 v88, v90, 16, 1
	v_add3_u32 v88, v90, v88, s71
	ds_write_b16_d16_hi v124, v88 offset:4928
	v_bfe_u32 v88, v91, 16, 1
	v_add3_u32 v88, v91, v88, s71
; DEV int TID() { int t = threadIdx.x; asm volatile("" : "+v"(t)); return t; }
; DEV void store_tile_bf16(const f32x4 (&acc)[8][4], u16* __restrict__ OUT, size_t ld, int m0, int n0, int ncols,
;                          unsigned char* smem) {
;   const int tid = TID(), lane = tid & 63, wid = tid >> 6;
;   const int wr = wid >> 1, wc = wid & 1, fr = lane & 15, fq = lane >> 4;
;   u16* st = (u16*)(smem + wid * 9216);
; #pragma unroll
;   for (int mh = 0; mh < 2; ++mh) {
; #pragma unroll
;     for (int mi = 0; mi < 4; ++mi)
; #pragma unroll
;       for (int ni = 0; ni < 4; ++ni)
; #pragma unroll
;         for (int j = 0; j < 4; ++j) st[(mi * 16 + fq * 4 + j) * 72 + ni * 16 + fr] = f2bf(acc[mh * 4 + mi][ni][j]);
;     const int chunk = lane & 7;
;     const int c0 = n0 + wc * 64 + chunk * 8;
; #pragma unroll
;     for (int itr = 0; itr < 8; ++itr) {
;       const int rl = (lane >> 3) + 8 * itr;
;       const u32x4 v = *(const u32x4*)(st + rl * 72 + chunk * 8);
;       if (c0 + 8 <= ncols) *(u32x4*)(OUT + (size_t)(m0 + wr * 128 + mh * 64 + rl) * ld + c0) = v;
;     }
;   }
; }
	ds_write_b16_d16_hi v124, v88 offset:5072
	s_nop 0
	v_bfe_u32 v88, v84, 16, 1
	v_add3_u32 v84, v84, v88, s71
	ds_write_b16_d16_hi v124, v84 offset:4672
	v_bfe_u32 v84, v85, 16, 1
	v_add3_u32 v84, v85, v84, s71
	v_mfma_f32_16x16x32_bf16 v[80:83], v[168:171], v[140:143], v[80:83]
	ds_write_b16_d16_hi v124, v84 offset:4816
	v_bfe_u32 v84, v86, 16, 1
	v_add3_u32 v84, v86, v84, s71
	ds_write_b16_d16_hi v124, v84 offset:4960
	v_bfe_u32 v84, v87, 16, 1
	v_add3_u32 v84, v87, v84, s71
	ds_write_b16_d16_hi v124, v84 offset:5104
	s_nop 0
	v_bfe_u32 v84, v80, 16, 1
	v_add3_u32 v80, v80, v84, s71
	ds_write_b16_d16_hi v124, v80 offset:4704
	v_bfe_u32 v80, v81, 16, 1
	v_add3_u32 v80, v81, v80, s71
	ds_write_b16_d16_hi v124, v80 offset:4848
	v_bfe_u32 v80, v82, 16, 1
	v_add3_u32 v80, v82, v80, s71
	ds_write_b16_d16_hi v124, v80 offset:4992
	v_bfe_u32 v80, v83, 16, 1
	v_add3_u32 v80, v83, v80, s71
	ds_write_b16_d16_hi v124, v80 offset:5136
	v_bfe_u32 v80, v76, 16, 1
	v_add3_u32 v76, v76, v80, s71
	ds_write_b16_d16_hi v124, v76 offset:6912
	v_bfe_u32 v76, v77, 16, 1
	v_add3_u32 v76, v77, v76, s71
	ds_write_b16_d16_hi v124, v76 offset:7056
	v_bfe_u32 v76, v78, 16, 1
	v_add3_u32 v76, v78, v76, s71
	ds_write_b16_d16_hi v124, v76 offset:7200
	v_bfe_u32 v76, v79, 16, 1
	v_add3_u32 v76, v79, v76, s71
	ds_write_b16_d16_hi v124, v76 offset:7344
	v_bfe_u32 v76, v72, 16, 1
	v_add3_u32 v72, v72, v76, s71
	ds_write_b16_d16_hi v124, v72 offset:6944
	v_bfe_u32 v72, v73, 16, 1
	v_add3_u32 v72, v73, v72, s71
	v_mfma_f32_16x16x32_bf16 v[68:71], v[172:175], v[136:139], v[68:71]
	ds_write_b16_d16_hi v124, v72 offset:7088
	v_bfe_u32 v72, v74, 16, 1
	v_add3_u32 v72, v74, v72, s71
	ds_write_b16_d16_hi v124, v72 offset:7232
	v_bfe_u32 v72, v75, 16, 1
	v_add3_u32 v72, v75, v72, s71
	ds_write_b16_d16_hi v124, v72 offset:7376
	s_nop 0
	v_bfe_u32 v72, v68, 16, 1
	v_add3_u32 v68, v68, v72, s71
	ds_write_b16_d16_hi v124, v68 offset:6976
	v_bfe_u32 v68, v69, 16, 1
	v_add3_u32 v68, v69, v68, s71
	v_mfma_f32_16x16x32_bf16 v[64:67], v[172:175], v[140:143], v[64:67]
	ds_write_b16_d16_hi v124, v68 offset:7120
	v_bfe_u32 v68, v70, 16, 1
	v_add3_u32 v68, v70, v68, s71
	ds_write_b16_d16_hi v124, v68 offset:7264
	v_bfe_u32 v68, v71, 16, 1
	v_add3_u32 v68, v71, v68, s71
	ds_write_b16_d16_hi v124, v68 offset:7408
	s_nop 0
	v_bfe_u32 v68, v64, 16, 1
	v_add3_u32 v64, v64, v68, s71
	ds_write_b16_d16_hi v124, v64 offset:7008
	v_bfe_u32 v64, v65, 16, 1
	v_add3_u32 v64, v65, v64, s71
	ds_write_b16_d16_hi v124, v64 offset:7152
	v_bfe_u32 v64, v66, 16, 1
	v_mfma_f32_16x16x32_bf16 v[52:55], v[144:147], v[136:139], v[52:55]
	v_add3_u32 v64, v66, v64, s71
	ds_write_b16_d16_hi v124, v64 offset:7296
	v_bfe_u32 v64, v67, 16, 1
	v_mfma_f32_16x16x32_bf16 v[48:51], v[144:147], v[140:143], v[48:51]
	v_ashrrev_i32_e32 v129, 31, v128
	v_add3_u32 v64, v67, v64, s71
	v_cmp_gt_i32_e32 vcc, s5, v128
	v_mfma_f32_16x16x32_bf16 v[36:39], v[148:151], v[136:139], v[36:39]
	v_lshl_add_u64 v[128:129], v[128:129], 1, s[68:69]
	ds_write_b16_d16_hi v124, v64 offset:7440
	v_mad_u32_u24 v66, v133, s4, v131
	v_mfma_f32_16x16x32_bf16 v[32:35], v[148:151], v[140:143], v[32:35]
	v_or_b32_e32 v64, v134, v133
	ds_write_b16_d16_hi v124, v135
	v_mfma_f32_16x16x32_bf16 v[20:23], v[152:155], v[136:139], v[20:23]
	v_mfma_f32_16x16x32_bf16 v[16:19], v[152:155], v[140:143], v[16:19]
	v_mfma_f32_16x16x32_bf16 v[4:7], v[158:161], v[136:139], v[4:7]
	v_mfma_f32_16x16x32_bf16 v[0:3], v[158:161], v[140:143], v[0:3]
	s_and_saveexec_b64 s[4:5], vcc
	s_cbranch_execz .LBB0_417
	ds_read_b128 v[68:71], v66
	v_ashrrev_i32_e32 v65, 31, v64
	v_lshlrev_b64 v[72:73], 13, v[64:65]
	v_lshl_add_u64 v[72:73], v[128:129], 0, v[72:73]
	s_waitcnt lgkmcnt(0)
	global_store_dwordx4 v[72:73], v[68:71], off
	ds_read_b128 v[68:71], v66 offset:1152
	v_or_b32_e32 v72, 8, v64
	v_ashrrev_i32_e32 v73, 31, v72
	v_lshlrev_b64 v[72:73], 13, v[72:73]
	v_lshl_add_u64 v[72:73], v[128:129], 0, v[72:73]
	s_waitcnt lgkmcnt(0)
	global_store_dwordx4 v[72:73], v[68:71], off
	ds_read_b128 v[68:71], v66 offset:2304
	v_or_b32_e32 v72, 16, v64
	v_ashrrev_i32_e32 v73, 31, v72
	v_lshlrev_b64 v[72:73], 13, v[72:73]
	v_lshl_add_u64 v[72:73], v[128:129], 0, v[72:73]
	s_waitcnt lgkmcnt(0)
	global_store_dwordx4 v[72:73], v[68:71], off
	ds_read_b128 v[68:71], v66 offset:3456
	v_or_b32_e32 v72, 24, v64
	v_ashrrev_i32_e32 v73, 31, v72
	v_lshlrev_b64 v[72:73], 13, v[72:73]
	v_lshl_add_u64 v[72:73], v[128:129], 0, v[72:73]
	s_waitcnt lgkmcnt(0)
	global_store_dwordx4 v[72:73], v[68:71], off
	ds_read_b128 v[68:71], v66 offset:4608
	v_or_b32_e32 v72, 32, v64
	v_ashrrev_i32_e32 v73, 31, v72
	v_lshlrev_b64 v[72:73], 13, v[72:73]
	v_lshl_add_u64 v[72:73], v[128:129], 0, v[72:73]
	s_waitcnt lgkmcnt(0)
	global_store_dwordx4 v[72:73], v[68:71], off
	ds_read_b128 v[68:71], v66 offset:5760
	v_or_b32_e32 v72, 40, v64
	v_ashrrev_i32_e32 v73, 31, v72
	v_lshlrev_b64 v[72:73], 13, v[72:73]
	v_lshl_add_u64 v[72:73], v[128:129], 0, v[72:73]
	s_waitcnt lgkmcnt(0)
	global_store_dwordx4 v[72:73], v[68:71], off
	ds_read_b128 v[68:71], v66 offset:6912
	v_or_b32_e32 v72, 48, v64
	v_ashrrev_i32_e32 v73, 31, v72
	v_lshlrev_b64 v[72:73], 13, v[72:73]
	v_lshl_add_u64 v[72:73], v[128:129], 0, v[72:73]
	s_waitcnt lgkmcnt(0)
	global_store_dwordx4 v[72:73], v[68:71], off
	ds_read_b128 v[68:71], v66 offset:8064
	v_or_b32_e32 v72, 56, v64
	v_ashrrev_i32_e32 v73, 31, v72
	v_lshlrev_b64 v[72:73], 13, v[72:73]
	v_lshl_add_u64 v[72:73], v[128:129], 0, v[72:73]
	s_waitcnt lgkmcnt(0)
	global_store_dwordx4 v[72:73], v[68:71], off
